# rebuilt pipeline: chunk-MLP unit loads all rows/u/gate/weights at unit start (B2), no chain post-X read hoist, stage-H hoist distance 90
# speedup vs baseline: 1.0050x; 1.0046x over previous
.LBB0_327:
	s_or_b64 exec, exec, s[0:1]
	s_nop 5
	v_cvt_f16_f32_e32 v2, v52
	v_cvt_f16_f32_e32 v52, v53
	v_cvt_f16_f32_e32 v53, v54
	v_cvt_f16_f32_e32 v54, v55
	v_cndmask_b32_e64 v2, v2, 0, s[18:19]
	v_cndmask_b32_e64 v52, 0, v52, s[20:21]
	v_cndmask_b32_e64 v53, v53, 0, s[22:23]
	v_cndmask_b32_e64 v54, v54, 0, s[24:25]
	v_pack_b32_f16 v53, v53, v54
	v_pack_b32_f16 v52, v2, v52
	ds_write_b64 v123, v[52:53]
	s_waitcnt lgkmcnt(0)
	s_barrier
	ds_read_b128 v[126:129], v124 offset:55360
	ds_read_b128 v[52:55], v125
	ds_read_b128 v[178:181], v125 offset:64
	ds_read_b128 v[182:185], v125 offset:2304
	ds_read_b128 v[186:189], v125 offset:2368
	ds_read_b128 v[190:193], v125 offset:4608
	ds_read_b128 v[194:197], v125 offset:4672
	ds_read_b128 v[68:71], v124 offset:55296
	s_nop 0
	s_nop 0
	ds_read_b128 v[198:201], v125 offset:6912
	s_nop 0
	s_waitcnt lgkmcnt(1)
	v_mfma_f32_16x16x32_f16 v[48:51], v[68:71], v[52:55], v[48:51]
	s_nop 0
	v_add_u32_e32 v2, 0x1e500, v96
	ds_read_b128 v[202:205], v125 offset:6976
	s_add_i32 s28, s28, 1
	s_nop 0
	v_mfma_f32_16x16x32_f16 v[52:55], v[126:129], v[178:181], v[48:51]
	ds_read_b128 v[178:181], v2
	s_nop 2
	s_nop 0
	s_nop 0
	v_mfma_f32_16x16x32_f16 v[48:51], v[68:71], v[182:185], v[56:59]
	s_nop 2
	s_nop 0
	ds_read_b128 v[182:185], v248 offset:46080
	v_cvt_pk_f16_f32 v55, v54, v55
	v_cvt_pk_f16_f32 v54, v52, v53
	s_nop 0
	v_mfma_f32_16x16x32_f16 v[56:59], v[126:129], v[186:189], v[48:51]
	ds_read_b128 v[186:189], v248 offset:46144
	s_nop 2
	s_nop 0
	s_nop 0
	ds_read_b128 v[206:209], v2 offset:64
	v_mfma_f32_16x16x32_f16 v[48:51], v[68:71], v[190:193], v[60:63]
	s_nop 2
	s_nop 0
	s_nop 0
	ds_read_b128 v[190:193], v249 offset:48384
	v_mfma_f32_16x16x32_f16 v[60:63], v[126:129], v[194:197], v[48:51]
	s_nop 2
	s_nop 0
	ds_read_b128 v[194:197], v249 offset:48448
	s_nop 0
	s_waitcnt lgkmcnt(7)
	v_mfma_f32_16x16x32_f16 v[48:51], v[68:71], v[198:201], v[64:67]
	s_nop 2
	ds_read_b128 v[198:201], v2 offset:128
	s_nop 0
	s_nop 0
	s_waitcnt lgkmcnt(7)
	v_mfma_f32_16x16x32_f16 v[48:51], v[126:129], v[202:205], v[48:51]
	s_nop 0
	ds_read_b128 v[202:205], v248 offset:50688
	s_nop 0
	s_waitcnt lgkmcnt(7)
	v_pk_mul_f32 v[44:45], v[44:45], v[178:179]
	v_pk_mul_f32 v[46:47], v[46:47], v[180:181]
	ds_read_b128 v[178:181], v248 offset:50752
	s_nop 0
	s_nop 2
	v_cvt_pk_f16_f32 v51, v50, v51
	s_nop 0
	s_waitcnt lgkmcnt(7)
	v_mfma_f32_16x16x32_f16 v[44:47], v[182:185], v[68:71], v[44:47]
	ds_read_b128 v[182:185], v2 offset:192
	s_nop 0
	v_cvt_pk_f16_f32 v50, v48, v49
	s_nop 0
	s_waitcnt lgkmcnt(7)
	v_mfma_f32_16x16x32_f16 v[44:47], v[186:189], v[126:129], v[44:47]
	ds_read_b128 v[186:189], v249 offset:52992
	s_waitcnt lgkmcnt(7)
	v_pk_mul_f32 v[32:33], v[32:33], v[206:207]
	v_pk_mul_f32 v[34:35], v[34:35], v[208:209]
	s_nop 0
	s_nop 0
	s_waitcnt lgkmcnt(6)
	v_mfma_f32_16x16x32_f16 v[32:35], v[190:193], v[68:71], v[32:35]
	s_nop 0
	s_nop 0
	s_waitcnt lgkmcnt(5)
	v_mfma_f32_16x16x32_f16 v[32:35], v[194:197], v[126:129], v[32:35]
	s_waitcnt lgkmcnt(4)
	v_pk_mul_f32 v[40:41], v[40:41], v[198:199]
	v_pk_mul_f32 v[42:43], v[42:43], v[200:201]
	s_nop 0
	s_nop 0
	s_waitcnt lgkmcnt(3)
	v_mfma_f32_16x16x32_f16 v[40:43], v[202:205], v[68:71], v[40:43]
	s_nop 0
	s_nop 0
	s_waitcnt lgkmcnt(2)
	v_mfma_f32_16x16x32_f16 v[40:43], v[178:181], v[126:129], v[40:43]
	v_add_u32_e32 v2, s26, v91
	s_add_i32 s26, s26, 64
	s_waitcnt lgkmcnt(1)
	v_pk_mul_f32 v[36:37], v[36:37], v[182:183]
	v_pk_mul_f32 v[38:39], v[38:39], v[184:185]
	s_nop 0
	s_nop 0
	s_waitcnt lgkmcnt(0)
	v_mfma_f32_16x16x32_f16 v[36:39], v[186:189], v[68:71], v[36:39]
	ds_read_b128 v[64:67], v249 offset:53056
	s_nop 0
	s_waitcnt lgkmcnt(0)
	v_mfma_f32_16x16x32_f16 v[36:39], v[64:67], v[126:129], v[36:39]
	v_add_u32_e32 v64, s27, v112
	v_add_u32_e32 v65, 0xff, v64
	v_cndmask_b32_e64 v65, v65, v2, s[2:3]
	v_add_u32_e32 v52, v65, v89
	v_mad_i64_i32 v[52:53], s[0:1], v52, s91, v[82:83]
	global_store_dwordx2 v[52:53], v[54:55], off
	v_add_u32_e32 v52, 16, v2
	v_add_u32_e32 v53, 0xef, v64
	v_cndmask_b32_e64 v54, v53, v52, s[2:3]
	v_add_u32_e32 v54, v54, v89
	v_cvt_pk_f16_f32 v53, v58, v59
	v_cvt_pk_f16_f32 v52, v56, v57
	v_mad_i64_i32 v[54:55], s[0:1], v54, s91, v[82:83]
	global_store_dwordx2 v[54:55], v[52:53], off
	v_add_u32_e32 v52, 32, v2
	v_add_u32_e32 v53, 0xdf, v64
	v_cndmask_b32_e64 v54, v53, v52, s[2:3]
	v_add_u32_e32 v54, v54, v89
	v_cvt_pk_f16_f32 v53, v62, v63
	v_cvt_pk_f16_f32 v52, v60, v61
	v_mad_i64_i32 v[54:55], s[0:1], v54, s91, v[82:83]
	global_store_dwordx2 v[54:55], v[52:53], off
	v_add_u32_e32 v2, 48, v2
	v_add_u32_e32 v52, 0xcf, v64
	v_cndmask_b32_e64 v2, v52, v2, s[2:3]
	v_add_u32_e32 v2, v2, v89
	s_sub_i32 s27, s27, 64
	v_mad_i64_i32 v[48:49], s[0:1], v2, s91, v[82:83]
	s_cmpk_lg_i32 s27, 0xff00
	global_store_dwordx2 v[48:49], v[50:51], off
	s_cbranch_scc0 .LBB0_485

.LBB0_340:
	s_or_b64 exec, exec, s[0:1]
	s_waitcnt lgkmcnt(0)
	s_barrier
	ds_read_b128 v[52:55], v92 offset:9216
	ds_read_b128 v[60:63], v94
	ds_read_b128 v[48:51], v92
	s_nop 0
	s_nop 0
	ds_read_b128 v[68:71], v101
	ds_read_b128 v[56:59], v250 offset:16
	s_nop 0
	v_add_u32_e32 v81, v95, v103
	s_nop 0
	s_waitcnt lgkmcnt(4)
	v_cvt_f32_f16_sdwa v67, v52 dst_sel:DWORD dst_unused:UNUSED_PAD src0_sel:WORD_1
	s_nop 0
	s_waitcnt lgkmcnt(3)
	v_mul_f32_e32 v2, 0x3fb8aa3b, v60
	v_exp_f32_e32 v60, v2
	v_mul_f32_e32 v2, 0x3fb8aa3b, v61
	v_exp_f32_e32 v61, v2
	v_cvt_f32_f16_e32 v66, v52
	v_rcp_f32_e32 v64, v60
	v_add3_u32 v52, v78, v97, v247
	v_rcp_f32_e32 v65, v61
	v_cvt_f32_f16_sdwa v127, v54 dst_sel:DWORD dst_unused:UNUSED_PAD src0_sel:WORD_1
	v_cvt_f32_f16_e32 v126, v54
	v_pk_mul_f32 v[66:67], v[64:65], v[66:67]
	s_waitcnt lgkmcnt(2)
	v_cvt_f32_f16_sdwa v65, v48 dst_sel:DWORD dst_unused:UNUSED_PAD src0_sel:WORD_1
	v_cvt_f32_f16_e32 v64, v48
	s_nop 0
	s_waitcnt lgkmcnt(1)
	v_fma_mixlo_f16 v2, v68, v66, 0
	ds_write_b16 v52, v2 offset:46080
	v_fma_mixlo_f16 v2, v69, v67, 0
	v_pk_mul_f32 v[64:65], v[64:65], s[68:69] op_sel_hi:[1,0]
	ds_write_b16 v121, v2 offset:46080
	v_mul_f32_e32 v2, 0x3fb8aa3b, v62
	v_pk_mul_f32 v[64:65], v[64:65], v[60:61]
	v_exp_f32_e32 v60, v2
	v_mul_f32_e32 v2, 0x3fb8aa3b, v63
	v_exp_f32_e32 v61, v2
	v_cvt_f32_f16_sdwa v69, v53 dst_sel:DWORD dst_unused:UNUSED_PAD src0_sel:WORD_1
	v_rcp_f32_e32 v62, v60
	v_cvt_f32_f16_e32 v68, v53
	v_rcp_f32_e32 v63, v61
	v_cvt_f32_f16_sdwa v53, v49 dst_sel:DWORD dst_unused:UNUSED_PAD src0_sel:WORD_1
	v_cvt_f32_f16_e32 v52, v49
	v_cvt_pk_f16_f32 v48, v64, v65
	v_pk_mul_f32 v[68:69], v[62:63], v[68:69]
	v_pk_mul_f32 v[52:53], v[52:53], s[68:69] op_sel_hi:[1,0]
	v_fma_mixlo_f16 v2, v70, v68, 0
	ds_write_b16 v121, v2 offset:46224
	v_fma_mixlo_f16 v2, v71, v69, 0
	ds_write_b16 v121, v2 offset:46368
	s_waitcnt lgkmcnt(4)
	v_mul_f32_e32 v2, 0x3fb8aa3b, v56
	v_exp_f32_e32 v56, v2
	v_mul_f32_e32 v2, 0x3fb8aa3b, v57
	v_exp_f32_e32 v57, v2
	v_pk_mul_f32 v[52:53], v[52:53], v[60:61]
	ds_read_b128 v[60:63], v102
	v_rcp_f32_e32 v70, v56
	s_nop 0
	v_rcp_f32_e32 v71, v57
	v_cvt_pk_f16_f32 v49, v52, v53
	v_pk_mul_f32 v[70:71], v[70:71], v[126:127]
	s_nop 0
	s_waitcnt lgkmcnt(0)
	v_fma_mixlo_f16 v2, v60, v70, 0
	ds_write_b16 v121, v2 offset:46512
	v_fma_mixlo_f16 v2, v61, v71, 0
	ds_write_b16 v121, v2 offset:46656
	v_mul_f32_e32 v2, 0x3fb8aa3b, v58
	v_cvt_f32_f16_sdwa v127, v50 dst_sel:DWORD dst_unused:UNUSED_PAD src0_sel:WORD_1
	v_cvt_f32_f16_e32 v126, v50
	v_exp_f32_e32 v58, v2
	v_mul_f32_e32 v2, 0x3fb8aa3b, v59
	v_exp_f32_e32 v59, v2
	v_pk_mul_f32 v[126:127], v[126:127], s[68:69] op_sel_hi:[1,0]
	v_cvt_f32_f16_sdwa v61, v55 dst_sel:DWORD dst_unused:UNUSED_PAD src0_sel:WORD_1
	v_pk_mul_f32 v[126:127], v[126:127], v[56:57]
	v_rcp_f32_e32 v56, v58
	v_rcp_f32_e32 v57, v59
	v_cvt_f32_f16_e32 v60, v55
	v_bfe_u32 v55, v71, 16, 1
	v_add3_u32 v55, v71, v55, s34
	v_cvt_pk_f16_f32 v50, v126, v127
	v_pk_mul_f32 v[128:129], v[56:57], v[60:61]
	v_bfe_u32 v56, v70, 16, 1
	v_fma_mixlo_f16 v2, v62, v128, 0
	ds_write_b16 v121, v2 offset:46800
	v_bfe_u32 v2, v129, 16, 1
	v_bfe_u32 v54, v128, 16, 1
	v_bfe_u32 v57, v69, 16, 1
	v_bfe_u32 v60, v68, 16, 1
	v_bfe_u32 v61, v67, 16, 1
	v_bfe_u32 v62, v66, 16, 1
	v_add3_u32 v62, v66, v62, s34
	v_add3_u32 v61, v67, v61, s34
	v_add3_u32 v60, v68, v60, s34
	v_add3_u32 v66, v69, v57, s34
	v_add3_u32 v56, v70, v56, s34
	v_add3_u32 v54, v128, v54, s34
	v_add3_u32 v2, v129, v2, s34
	v_perm_b32 v57, v2, v54, s82
	v_perm_b32 v56, v55, v56, s82
	v_perm_b32 v55, v66, v60, s82
	v_perm_b32 v54, v61, v62, s82
	v_cvt_f32_f16_sdwa v61, v51 dst_sel:DWORD dst_unused:UNUSED_PAD src0_sel:WORD_1
	v_cvt_f32_f16_e32 v60, v51
	v_bfe_u32 v62, v126, 16, 1
	v_bfe_u32 v66, v53, 16, 1
	v_bfe_u32 v67, v52, 16, 1
	v_pk_mul_f32 v[60:61], v[60:61], s[68:69] op_sel_hi:[1,0]
	v_bfe_u32 v68, v65, 16, 1
	v_pk_mul_f32 v[58:59], v[60:61], v[58:59]
	v_bfe_u32 v61, v127, 16, 1
	v_bfe_u32 v2, v59, 16, 1
	v_bfe_u32 v60, v58, 16, 1
	v_cvt_pk_f16_f32 v51, v58, v59
	v_bfe_u32 v69, v64, 16, 1
	v_add3_u32 v58, v58, v60, s34
	v_add3_u32 v2, v59, v2, s34
	v_add3_u32 v64, v64, v69, s34
	v_add3_u32 v65, v65, v68, s34
	v_add3_u32 v52, v52, v67, s34
	v_add3_u32 v53, v53, v66, s34
	v_add3_u32 v62, v126, v62, s34
	v_add3_u32 v66, v127, v61, s34
	v_perm_b32 v61, v2, v58, s82
	v_fma_mixlo_f16 v2, v63, v129, 0
	v_perm_b32 v60, v66, v62, s82
	v_perm_b32 v59, v53, v52, s82
	v_perm_b32 v58, v65, v64, s82
	ds_write_b16 v121, v2 offset:46944
	ds_write_b128 v92, v[58:61] offset:18432
	ds_write_b128 v92, v[54:57] offset:27648
	ds_write_b128 v92, v[48:51] offset:36864
	v_add_u32_e32 v2, v79, v72
	s_nop 0
	s_barrier
	ds_read_b128 v[52:55], v81 offset:36864
	ds_read_b128 v[56:59], v81 offset:39168
	ds_read_b128 v[60:63], v81 offset:41472
	ds_read_b128 v[64:67], v81 offset:43776
	ds_read_b128 v[68:71], v2 offset:64
	ds_read_b128 v[178:181], v81 offset:36928
	ds_read_b128 v[182:185], v81 offset:39232
	ds_read_b128 v[186:189], v81 offset:41536
	ds_read_b128 v[48:51], v2
	s_nop 0
	s_nop 0
	s_nop 0
	s_nop 0
	s_nop 0
	s_waitcnt lgkmcnt(0)
	v_mfma_f32_16x16x32_f16 v[52:55], v[48:51], v[52:55], 0
	s_nop 0
	v_mfma_f32_16x16x32_f16 v[56:59], v[48:51], v[56:59], 0
	s_nop 0
	v_mfma_f32_16x16x32_f16 v[60:63], v[48:51], v[60:63], 0
	s_nop 0
	v_mfma_f32_16x16x32_f16 v[64:67], v[48:51], v[64:67], 0
	s_nop 0
	s_nop 0
	v_add_u32_e32 v2, v100, v72
	s_nop 0
	v_mfma_f32_16x16x32_f16 v[48:51], v[68:71], v[178:181], v[52:55]
	s_nop 2
	s_nop 0
	s_nop 0
	v_mfma_f32_16x16x32_f16 v[56:59], v[68:71], v[182:185], v[56:59]
	s_nop 0
	s_nop 0
	v_mfma_f32_16x16x32_f16 v[60:63], v[68:71], v[186:189], v[60:63]
	ds_read_b128 v[52:55], v81 offset:43840
	s_nop 0
	s_waitcnt lgkmcnt(0)
	v_mfma_f32_16x16x32_f16 v[64:67], v[68:71], v[52:55], v[64:67]
	v_mov_b32_e32 v52, 0
	v_mov_b32_e32 v68, 0
	v_mov_b32_e32 v69, 0
	v_mov_b32_e32 v70, 0
	v_mov_b32_e32 v71, 0
	s_and_saveexec_b64 s[0:1], s[6:7]
	s_cbranch_execz .LBB0_342
	v_add_u32_e32 v253, v95, v106
	ds_read_b128 v[68:71], v2 offset:18432
	ds_read_b128 v[126:129], v253 offset:27648
	v_add_u32_e32 v53, v95, v106
	s_nop 0
	s_nop 0
	s_nop 0
	s_waitcnt lgkmcnt(0)
	v_mfma_f32_16x16x32_bf16 v[68:71], v[126:129], v[68:71], 0
	ds_read_b128 v[130:133], v53 offset:27712
	ds_read_b128 v[126:129], v2 offset:18496
	s_nop 0
	s_nop 0
	s_waitcnt lgkmcnt(0)
	v_mfma_f32_16x16x32_bf16 v[68:71], v[130:133], v[126:129], v[68:71]

.LBB0_356:
	s_and_b32 s27, s26, 1
	v_lshl_add_u32 v0, s27, 13, v232
	ds_read2_b64 v[36:39], v0 offset1:32
	v_mad_u32_u24 v2, s27, v165, v233
	s_waitcnt lgkmcnt(0)
	v_pk_mul_f32 v[66:67], v[36:37], v[38:39]
	v_xor_b32_e32 v90, 16, v0
	ds_read2_b64 v[38:41], v90 offset0:64 offset1:96
	s_waitcnt lgkmcnt(0)
	v_pk_mul_f32 v[64:65], v[66:67], v[38:39]
	s_nop 0
	v_pk_mul_f32 v[60:61], v[64:65], v[40:41]
	v_xor_b32_e32 v91, 32, v0
	ds_read2_b64 v[38:41], v91 offset0:128 offset1:160
	s_waitcnt lgkmcnt(0)
	v_pk_mul_f32 v[54:55], v[60:61], v[38:39]
	s_nop 0
	v_pk_mul_f32 v[48:49], v[54:55], v[40:41]
	v_xor_b32_e32 v92, 48, v0
	ds_read2_b64 v[38:41], v92 offset0:192 offset1:224
	v_add_u32_e32 v0, 0x800, v0
	v_xor_b32_e32 v91, 32, v0
	ds_read2_b64 v[68:71], v91 offset0:128 offset1:160
	s_waitcnt lgkmcnt(1)
	v_pk_mul_f32 v[44:45], v[48:49], v[38:39]
	s_nop 0
	v_pk_mul_f32 v[38:39], v[44:45], v[40:41]
	ds_read2_b64 v[40:43], v0 offset1:32
	s_waitcnt lgkmcnt(0)
	v_pk_mul_f32 v[58:59], v[38:39], v[40:41]
	s_nop 0
	v_pk_mul_f32 v[50:51], v[58:59], v[42:43]
	v_xor_b32_e32 v90, 16, v0
	ds_read2_b64 v[40:43], v90 offset0:64 offset1:96
	s_waitcnt lgkmcnt(0)
	v_pk_mul_f32 v[46:47], v[50:51], v[40:41]
	s_nop 0
	v_pk_mul_f32 v[42:43], v[46:47], v[42:43]
	v_rcp_f32_e32 v40, v38
	v_pk_mul_f32 v[62:63], v[42:43], v[68:69]
	v_rcp_f32_e32 v41, v39
	v_pk_mul_f32 v[56:57], v[62:63], v[70:71]
	v_xor_b32_e32 v92, 48, v0
	ds_read2_b64 v[68:71], v92 offset0:192 offset1:224
	s_waitcnt lgkmcnt(0)
	v_pk_mul_f32 v[52:53], v[56:57], v[68:69]
	s_nop 0
	v_pk_mul_f32 v[0:1], v[52:53], v[70:71]
	s_and_saveexec_b64 s[28:29], s[4:5]
	s_cbranch_execz .LBB0_358
	v_lshl_add_u32 v253, v177, 1, v2
	v_lshl_add_u32 v252, v184, 1, v2
	ds_read2st64_b32 v[72:73], v253 offset0:96 offset1:112
	ds_read2st64_b32 v[68:69], v253 offset0:64 offset1:80
	ds_read_b32 v84, v253 offset:32768
	ds_read2st64_b32 v[240:241], v252 offset0:64 offset1:80
	ds_read2st64_b32 v[242:243], v252 offset0:96 offset1:112
	v_lshl_add_u32 v74, v177, 1, v2
	s_nop 0
	s_nop 0
	v_rcp_f32_e32 v70, v36
	v_rcp_f32_e32 v71, v37
	s_waitcnt lgkmcnt(4)
	v_cvt_f32_f16_e32 v78, v73
	v_cvt_f32_f16_sdwa v79, v73 dst_sel:DWORD dst_unused:UNUSED_PAD src0_sel:WORD_1
	s_waitcnt lgkmcnt(3)
	v_cvt_f32_f16_e32 v74, v68
	v_cvt_f32_f16_sdwa v75, v68 dst_sel:DWORD dst_unused:UNUSED_PAD src0_sel:WORD_1
	v_cvt_f32_f16_e32 v76, v72
	v_cvt_f32_f16_sdwa v77, v72 dst_sel:DWORD dst_unused:UNUSED_PAD src0_sel:WORD_1
	v_cvt_f32_f16_e32 v72, v69
	v_cvt_f32_f16_sdwa v73, v69 dst_sel:DWORD dst_unused:UNUSED_PAD src0_sel:WORD_1
	v_pk_mul_f32 v[78:79], v[36:37], v[78:79]
	v_pk_mul_f32 v[76:77], v[70:71], v[76:77]
	v_pk_mul_f32 v[70:71], v[70:71], v[74:75]
	v_pk_mul_f32 v[72:73], v[40:41], v[72:73]
	v_pk_mul_f32 v[74:75], v[40:41], v[78:79]
	v_cvt_pk_f16_f32 v68, v78, v79
	v_pk_mul_f32 v[80:81], v[38:39], v[76:77]
	v_pk_mul_f32 v[82:83], v[38:39], v[70:71]
	ds_write2st64_b32 v183, v69, v68 offset1:18
	v_cvt_pk_f16_f32 v68, v72, v73
	v_cvt_pk_f16_f32 v69, v74, v75
	v_pk_mul_f32 v[76:77], v[0:1], v[76:77]
	ds_write2st64_b32 v183, v68, v69 offset0:36 offset1:54
	v_cvt_pk_f16_f32 v68, v80, v81
	v_cvt_pk_f16_f32 v69, v82, v83
	v_lshl_add_u32 v253, v186, 1, v2
	ds_read_b32 v82, v252 offset:32768
	ds_write2st64_b32 v183, v68, v69 offset0:72 offset1:90
	v_cvt_f16_f32_e32 v68, v76
	v_pk_mul_f32 v[70:71], v[0:1], v[70:71]
	v_cvt_f16_f32_e32 v69, v77
	v_cvt_f16_f32_e32 v70, v70
	v_cvt_f16_f32_e32 v71, v71
	ds_write_b16 v178, v68
	ds_write_b16 v178, v69 offset:40
	ds_write_b16 v178, v70 offset:5120
	ds_write_b16 v178, v71 offset:5160
	s_waitcnt lgkmcnt(10)
	ds_write_b16 v178, v84 offset:10240
	v_lshl_add_u32 v74, v184, 1, v2
	v_rcp_f32_e32 v70, v66
	v_rcp_f32_e32 v71, v67
	s_waitcnt lgkmcnt(10)
	v_cvt_f32_f16_e32 v76, v241
	v_cvt_f32_f16_sdwa v77, v241 dst_sel:DWORD dst_unused:UNUSED_PAD src0_sel:WORD_1
	s_waitcnt lgkmcnt(9)
	v_cvt_f32_f16_e32 v80, v243
	v_cvt_f32_f16_sdwa v81, v243 dst_sel:DWORD dst_unused:UNUSED_PAD src0_sel:WORD_1
	v_cvt_f32_f16_e32 v74, v240
	v_cvt_f32_f16_e32 v78, v242
	v_cvt_f32_f16_sdwa v79, v242 dst_sel:DWORD dst_unused:UNUSED_PAD src0_sel:WORD_1
	ds_read2st64_b32 v[242:243], v253 offset0:64 offset1:80
	v_cvt_f32_f16_sdwa v75, v240 dst_sel:DWORD dst_unused:UNUSED_PAD src0_sel:WORD_1
	ds_read2st64_b32 v[240:241], v253 offset0:96 offset1:112
	v_pk_mul_f32 v[36:37], v[36:37], v[76:77]
	v_pk_mul_f32 v[68:69], v[66:67], v[80:81]
	v_pk_mul_f32 v[72:73], v[70:71], v[78:79]
	v_pk_mul_f32 v[70:71], v[70:71], v[74:75]
	v_pk_mul_f32 v[74:75], v[40:41], v[36:37]
	v_pk_mul_f32 v[76:77], v[40:41], v[68:69]
	v_cvt_pk_f16_f32 v36, v36, v37
	v_cvt_pk_f16_f32 v37, v68, v69
	v_pk_mul_f32 v[78:79], v[38:39], v[72:73]
	v_pk_mul_f32 v[80:81], v[38:39], v[70:71]
	ds_write2st64_b32 v185, v36, v37 offset1:18
	v_cvt_pk_f16_f32 v36, v74, v75
	v_cvt_pk_f16_f32 v37, v76, v77
	v_pk_mul_f32 v[72:73], v[0:1], v[72:73]
	ds_write2st64_b32 v185, v36, v37 offset0:36 offset1:54
	v_cvt_pk_f16_f32 v36, v78, v79
	v_cvt_pk_f16_f32 v37, v80, v81
	v_lshl_add_u32 v252, v188, 1, v2
	ds_read_b32 v80, v253 offset:32768
	ds_write2st64_b32 v185, v36, v37 offset0:72 offset1:90
	v_cvt_f16_f32_e32 v36, v72
	v_pk_mul_f32 v[70:71], v[0:1], v[70:71]
	v_cvt_f16_f32_e32 v37, v73
	v_cvt_f16_f32_e32 v68, v70
	v_cvt_f16_f32_e32 v69, v71
	s_waitcnt lgkmcnt(14)
	ds_write_b16 v178, v36 offset:2
	s_waitcnt lgkmcnt(14)
	ds_write_b16 v178, v37 offset:42
	s_waitcnt lgkmcnt(14)
	ds_write_b16 v178, v68 offset:5122
	s_waitcnt lgkmcnt(14)
	ds_write_b16 v178, v69 offset:5162
	s_waitcnt lgkmcnt(14)
	ds_write_b16 v178, v82 offset:10242
	v_lshl_add_u32 v72, v186, 1, v2
	v_rcp_f32_e32 v68, v64
	v_rcp_f32_e32 v69, v65
	s_waitcnt lgkmcnt(10)
	v_cvt_f32_f16_e32 v74, v243
	v_cvt_f32_f16_sdwa v75, v243 dst_sel:DWORD dst_unused:UNUSED_PAD src0_sel:WORD_1
	s_waitcnt lgkmcnt(9)
	v_cvt_f32_f16_e32 v78, v241
	v_cvt_f32_f16_sdwa v79, v241 dst_sel:DWORD dst_unused:UNUSED_PAD src0_sel:WORD_1
	v_cvt_f32_f16_e32 v72, v242
	v_cvt_f32_f16_e32 v76, v240
	v_cvt_f32_f16_sdwa v77, v240 dst_sel:DWORD dst_unused:UNUSED_PAD src0_sel:WORD_1
	ds_read2st64_b32 v[240:241], v252 offset0:64 offset1:80
	v_cvt_f32_f16_sdwa v73, v242 dst_sel:DWORD dst_unused:UNUSED_PAD src0_sel:WORD_1
	ds_read2st64_b32 v[242:243], v252 offset0:96 offset1:112
	v_pk_mul_f32 v[36:37], v[66:67], v[74:75]
	v_pk_mul_f32 v[66:67], v[64:65], v[78:79]
	v_pk_mul_f32 v[70:71], v[68:69], v[76:77]
	v_pk_mul_f32 v[68:69], v[68:69], v[72:73]
	v_pk_mul_f32 v[72:73], v[40:41], v[36:37]
	v_pk_mul_f32 v[74:75], v[40:41], v[66:67]
	v_cvt_pk_f16_f32 v36, v36, v37
	v_cvt_pk_f16_f32 v37, v66, v67
	v_pk_mul_f32 v[76:77], v[38:39], v[70:71]
	v_pk_mul_f32 v[78:79], v[38:39], v[68:69]
	ds_write2st64_b32 v187, v36, v37 offset1:18
	v_cvt_pk_f16_f32 v36, v72, v73
	v_cvt_pk_f16_f32 v37, v74, v75
	v_pk_mul_f32 v[70:71], v[0:1], v[70:71]
	ds_write2st64_b32 v187, v36, v37 offset0:36 offset1:54
	v_cvt_pk_f16_f32 v36, v76, v77
	v_cvt_pk_f16_f32 v37, v78, v79
	ds_read_b32 v78, v252 offset:32768
	ds_write2st64_b32 v187, v36, v37 offset0:72 offset1:90
	v_cvt_f16_f32_e32 v36, v70
	v_pk_mul_f32 v[68:69], v[0:1], v[68:69]
	v_cvt_f16_f32_e32 v37, v71
	v_cvt_f16_f32_e32 v66, v68
	v_cvt_f16_f32_e32 v67, v69
	s_waitcnt lgkmcnt(14)
	ds_write_b16 v178, v36 offset:4
	s_waitcnt lgkmcnt(14)
	ds_write_b16 v178, v37 offset:44
	s_waitcnt lgkmcnt(14)
	ds_write_b16 v178, v66 offset:5124
	s_waitcnt lgkmcnt(14)
	ds_write_b16 v178, v67 offset:5164
	s_waitcnt lgkmcnt(14)
	ds_write_b16 v178, v80 offset:10244
	v_lshl_add_u32 v70, v188, 1, v2
	v_rcp_f32_e32 v66, v60
	v_rcp_f32_e32 v67, v61
	s_waitcnt lgkmcnt(10)
	v_cvt_f32_f16_e32 v72, v241
	v_cvt_f32_f16_sdwa v73, v241 dst_sel:DWORD dst_unused:UNUSED_PAD src0_sel:WORD_1
	s_waitcnt lgkmcnt(9)
	v_cvt_f32_f16_e32 v76, v243
	v_cvt_f32_f16_sdwa v77, v243 dst_sel:DWORD dst_unused:UNUSED_PAD src0_sel:WORD_1
	v_cvt_f32_f16_e32 v70, v240
	v_cvt_f32_f16_e32 v74, v242
	v_cvt_f32_f16_sdwa v75, v242 dst_sel:DWORD dst_unused:UNUSED_PAD src0_sel:WORD_1
	v_cvt_f32_f16_sdwa v71, v240 dst_sel:DWORD dst_unused:UNUSED_PAD src0_sel:WORD_1
	v_pk_mul_f32 v[36:37], v[64:65], v[72:73]
	v_pk_mul_f32 v[64:65], v[60:61], v[76:77]
	v_pk_mul_f32 v[68:69], v[66:67], v[74:75]
	v_pk_mul_f32 v[66:67], v[66:67], v[70:71]
	v_pk_mul_f32 v[70:71], v[40:41], v[36:37]
	v_pk_mul_f32 v[72:73], v[40:41], v[64:65]
	v_cvt_pk_f16_f32 v36, v36, v37
	v_cvt_pk_f16_f32 v37, v64, v65
	v_pk_mul_f32 v[74:75], v[38:39], v[68:69]
	v_pk_mul_f32 v[76:77], v[38:39], v[66:67]
	ds_write2st64_b32 v189, v36, v37 offset1:18
	v_cvt_pk_f16_f32 v36, v70, v71
	v_cvt_pk_f16_f32 v37, v72, v73
	v_pk_mul_f32 v[68:69], v[0:1], v[68:69]
	ds_write2st64_b32 v189, v36, v37 offset0:36 offset1:54
	v_cvt_pk_f16_f32 v36, v74, v75
	v_cvt_pk_f16_f32 v37, v76, v77
	ds_write2st64_b32 v189, v36, v37 offset0:72 offset1:90
	v_cvt_f16_f32_e32 v36, v68
	v_pk_mul_f32 v[66:67], v[0:1], v[66:67]
	v_cvt_f16_f32_e32 v37, v69
	v_cvt_f16_f32_e32 v64, v66
	v_cvt_f16_f32_e32 v65, v67
	ds_write_b16 v178, v36 offset:6
	ds_write_b16 v178, v37 offset:46
	ds_write_b16 v178, v64 offset:5126
	s_waitcnt lgkmcnt(14)
	ds_write_b16 v178, v65 offset:5166
	s_nop 0
	s_waitcnt lgkmcnt(13)
	ds_write_b16 v178, v78 offset:10246
	v_perm_b32 v36, v82, v84, s82
	v_perm_b32 v37, v78, v80, s82
	ds_write_b64 v178, v[36:37] offset:10280

.LBB0_369:
	v_cmp_lt_i32_e32 vcc, 2, v176
	s_and_saveexec_b64 s[30:31], vcc
	s_xor_b64 s[70:71], exec, s[30:31]
	s_cbranch_execz .LBB0_371
	v_lshl_add_u32 v253, v206, 1, v2
	v_lshl_add_u32 v252, v208, 1, v2
	ds_read2st64_b32 v[36:37], v253 offset0:64 offset1:80
	ds_read2st64_b32 v[46:47], v253 offset0:96 offset1:112
	ds_read_b32 v60, v253 offset:32768
	ds_read2st64_b32 v[240:241], v252 offset0:64 offset1:80
	ds_read2st64_b32 v[242:243], v252 offset0:96 offset1:112
	ds_read_b32 v61, v252 offset:32768
	v_lshl_add_u32 v48, v206, 1, v2
	s_nop 0
	s_nop 0
	v_rcp_f32_e32 v44, v62
	v_rcp_f32_e32 v45, v63
	v_lshl_add_u32 v253, v210, 1, v2
	s_waitcnt lgkmcnt(4)
	v_cvt_f32_f16_e32 v58, v47
	v_cvt_f32_f16_e32 v50, v37
	v_cvt_f32_f16_sdwa v51, v37 dst_sel:DWORD dst_unused:UNUSED_PAD src0_sel:WORD_1
	v_cvt_f32_f16_sdwa v59, v47 dst_sel:DWORD dst_unused:UNUSED_PAD src0_sel:WORD_1
	v_cvt_f32_f16_e32 v48, v36
	v_cvt_f32_f16_e32 v54, v46
	v_cvt_f32_f16_sdwa v55, v46 dst_sel:DWORD dst_unused:UNUSED_PAD src0_sel:WORD_1
	v_cvt_f32_f16_sdwa v49, v36 dst_sel:DWORD dst_unused:UNUSED_PAD src0_sel:WORD_1
	v_pk_mul_f32 v[36:37], v[42:43], v[50:51]
	v_pk_mul_f32 v[42:43], v[62:63], v[58:59]
	v_pk_mul_f32 v[46:47], v[44:45], v[54:55]
	v_pk_mul_f32 v[44:45], v[44:45], v[48:49]
	v_pk_mul_f32 v[48:49], v[40:41], v[36:37]
	v_pk_mul_f32 v[50:51], v[40:41], v[42:43]
	v_cvt_pk_f16_f32 v36, v36, v37
	v_cvt_pk_f16_f32 v37, v42, v43
	v_pk_mul_f32 v[54:55], v[38:39], v[46:47]
	v_pk_mul_f32 v[58:59], v[38:39], v[44:45]
	ds_write2st64_b32 v207, v36, v37 offset1:18
	v_cvt_pk_f16_f32 v36, v48, v49
	v_cvt_pk_f16_f32 v37, v50, v51
	v_pk_mul_f32 v[46:47], v[0:1], v[46:47]
	ds_write2st64_b32 v207, v36, v37 offset0:36 offset1:54
	v_cvt_pk_f16_f32 v36, v54, v55
	v_cvt_pk_f16_f32 v37, v58, v59
	ds_write2st64_b32 v207, v36, v37 offset0:72 offset1:90
	v_cvt_f16_f32_e32 v36, v46
	v_pk_mul_f32 v[44:45], v[0:1], v[44:45]
	v_cvt_f16_f32_e32 v37, v47
	v_cvt_f16_f32_e32 v42, v44
	v_cvt_f16_f32_e32 v43, v45
	ds_write_b16 v178, v36 offset:24
	ds_write_b16 v178, v37 offset:64
	ds_write_b16 v178, v42 offset:5144
	ds_write_b16 v178, v43 offset:5184
	s_waitcnt lgkmcnt(10)
	ds_write_b16 v178, v60 offset:10264
	v_lshl_add_u32 v46, v208, 1, v2
	v_rcp_f32_e32 v42, v56
	v_rcp_f32_e32 v43, v57
	s_waitcnt lgkmcnt(10)
	v_cvt_f32_f16_e32 v48, v241
	v_cvt_f32_f16_sdwa v49, v241 dst_sel:DWORD dst_unused:UNUSED_PAD src0_sel:WORD_1
	s_waitcnt lgkmcnt(9)
	v_cvt_f32_f16_e32 v54, v243
	v_cvt_f32_f16_sdwa v55, v243 dst_sel:DWORD dst_unused:UNUSED_PAD src0_sel:WORD_1
	v_cvt_f32_f16_e32 v46, v240
	v_cvt_f32_f16_e32 v50, v242
	v_cvt_f32_f16_sdwa v51, v242 dst_sel:DWORD dst_unused:UNUSED_PAD src0_sel:WORD_1
	ds_read2st64_b32 v[242:243], v253 offset0:64 offset1:80
	v_cvt_f32_f16_sdwa v47, v240 dst_sel:DWORD dst_unused:UNUSED_PAD src0_sel:WORD_1
	ds_read2st64_b32 v[240:241], v253 offset0:96 offset1:112
	v_pk_mul_f32 v[36:37], v[62:63], v[48:49]
	v_pk_mul_f32 v[44:45], v[56:57], v[54:55]
	v_pk_mul_f32 v[48:49], v[42:43], v[50:51]
	v_pk_mul_f32 v[42:43], v[42:43], v[46:47]
	v_pk_mul_f32 v[46:47], v[40:41], v[36:37]
	v_pk_mul_f32 v[50:51], v[40:41], v[44:45]
	v_cvt_pk_f16_f32 v36, v36, v37
	v_cvt_pk_f16_f32 v37, v44, v45
	v_pk_mul_f32 v[54:55], v[38:39], v[48:49]
	v_pk_mul_f32 v[58:59], v[38:39], v[42:43]
	ds_write2st64_b32 v209, v36, v37 offset1:18
	v_cvt_pk_f16_f32 v36, v46, v47
	v_cvt_pk_f16_f32 v37, v50, v51
	v_pk_mul_f32 v[48:49], v[0:1], v[48:49]
	ds_write2st64_b32 v209, v36, v37 offset0:36 offset1:54
	v_cvt_pk_f16_f32 v36, v54, v55
	v_cvt_pk_f16_f32 v37, v58, v59
	v_lshl_add_u32 v252, v212, 1, v2
	ds_read_b32 v58, v253 offset:32768
	ds_write2st64_b32 v209, v36, v37 offset0:72 offset1:90
	v_cvt_f16_f32_e32 v36, v48
	v_pk_mul_f32 v[42:43], v[0:1], v[42:43]
	v_cvt_f16_f32_e32 v37, v49
	v_cvt_f16_f32_e32 v42, v42
	v_cvt_f16_f32_e32 v43, v43
	s_waitcnt lgkmcnt(14)
	ds_write_b16 v178, v36 offset:26
	s_waitcnt lgkmcnt(14)
	ds_write_b16 v178, v37 offset:66
	s_waitcnt lgkmcnt(14)
	ds_write_b16 v178, v42 offset:5146
	s_waitcnt lgkmcnt(14)
	ds_write_b16 v178, v43 offset:5186
	s_waitcnt lgkmcnt(14)
	ds_write_b16 v178, v61 offset:10266
	v_lshl_add_u32 v46, v210, 1, v2
	v_rcp_f32_e32 v42, v52
	v_rcp_f32_e32 v43, v53
	v_lshl_add_u32 v2, v212, 1, v2
	s_waitcnt lgkmcnt(10)
	v_cvt_f32_f16_e32 v48, v243
	v_cvt_f32_f16_sdwa v49, v243 dst_sel:DWORD dst_unused:UNUSED_PAD src0_sel:WORD_1
	s_waitcnt lgkmcnt(9)
	v_cvt_f32_f16_e32 v54, v241
	v_cvt_f32_f16_sdwa v55, v241 dst_sel:DWORD dst_unused:UNUSED_PAD src0_sel:WORD_1
	v_cvt_f32_f16_e32 v46, v242
	v_cvt_f32_f16_e32 v50, v240
	v_cvt_f32_f16_sdwa v51, v240 dst_sel:DWORD dst_unused:UNUSED_PAD src0_sel:WORD_1
	ds_read2st64_b32 v[240:241], v252 offset0:64 offset1:80
	v_cvt_f32_f16_sdwa v47, v242 dst_sel:DWORD dst_unused:UNUSED_PAD src0_sel:WORD_1
	ds_read2st64_b32 v[242:243], v2 offset0:96 offset1:112
	v_pk_mul_f32 v[36:37], v[56:57], v[48:49]
	v_pk_mul_f32 v[44:45], v[52:53], v[54:55]
	v_pk_mul_f32 v[48:49], v[42:43], v[50:51]
	v_pk_mul_f32 v[42:43], v[42:43], v[46:47]
	v_pk_mul_f32 v[46:47], v[40:41], v[36:37]
	v_pk_mul_f32 v[50:51], v[40:41], v[44:45]
	v_cvt_pk_f16_f32 v36, v36, v37
	v_cvt_pk_f16_f32 v37, v44, v45
	v_pk_mul_f32 v[54:55], v[38:39], v[48:49]
	v_pk_mul_f32 v[56:57], v[38:39], v[42:43]
	ds_write2st64_b32 v211, v36, v37 offset1:18
	v_cvt_pk_f16_f32 v36, v46, v47
	v_cvt_pk_f16_f32 v37, v50, v51
	v_pk_mul_f32 v[48:49], v[0:1], v[48:49]
	ds_write2st64_b32 v211, v36, v37 offset0:36 offset1:54
	v_cvt_pk_f16_f32 v36, v54, v55
	v_cvt_pk_f16_f32 v37, v56, v57
	ds_write2st64_b32 v211, v36, v37 offset0:72 offset1:90
	v_cvt_f16_f32_e32 v36, v48
	v_pk_mul_f32 v[42:43], v[0:1], v[42:43]
	v_cvt_f16_f32_e32 v37, v49
	v_cvt_f16_f32_e32 v42, v42
	v_cvt_f16_f32_e32 v43, v43
	ds_write_b16 v178, v36 offset:28
	s_waitcnt lgkmcnt(14)
	ds_write_b16 v178, v37 offset:68
	s_waitcnt lgkmcnt(14)
	ds_write_b16 v178, v42 offset:5148
	s_waitcnt lgkmcnt(14)
	ds_write_b16 v178, v43 offset:5188
	s_waitcnt lgkmcnt(14)
	ds_write_b16 v178, v58 offset:10268
	s_waitcnt lgkmcnt(14)
	ds_read_b32 v2, v2 offset:32768
	v_rcp_f32_e32 v42, v0
	v_rcp_f32_e32 v43, v1
	s_waitcnt lgkmcnt(10)
	v_cvt_f32_f16_e32 v48, v241
	v_cvt_f32_f16_sdwa v49, v241 dst_sel:DWORD dst_unused:UNUSED_PAD src0_sel:WORD_1
	s_waitcnt lgkmcnt(9)
	v_cvt_f32_f16_e32 v54, v243
	v_cvt_f32_f16_sdwa v55, v243 dst_sel:DWORD dst_unused:UNUSED_PAD src0_sel:WORD_1
	v_cvt_f32_f16_e32 v46, v240
	v_cvt_f32_f16_e32 v50, v242
	v_cvt_f32_f16_sdwa v51, v242 dst_sel:DWORD dst_unused:UNUSED_PAD src0_sel:WORD_1
	v_cvt_f32_f16_sdwa v47, v240 dst_sel:DWORD dst_unused:UNUSED_PAD src0_sel:WORD_1
	v_pk_mul_f32 v[36:37], v[52:53], v[48:49]
	v_pk_mul_f32 v[44:45], v[0:1], v[54:55]
	v_pk_mul_f32 v[48:49], v[42:43], v[50:51]
	v_pk_mul_f32 v[42:43], v[42:43], v[46:47]
	v_pk_mul_f32 v[46:47], v[40:41], v[36:37]
	v_pk_mul_f32 v[40:41], v[40:41], v[44:45]
	v_cvt_pk_f16_f32 v36, v36, v37
	v_cvt_pk_f16_f32 v37, v44, v45
	v_pk_mul_f32 v[50:51], v[38:39], v[48:49]
	v_pk_mul_f32 v[38:39], v[38:39], v[42:43]
	ds_write2st64_b32 v213, v36, v37 offset1:18
	v_cvt_pk_f16_f32 v36, v46, v47
	v_cvt_pk_f16_f32 v37, v40, v41
	v_pk_mul_f32 v[48:49], v[0:1], v[48:49]
	ds_write2st64_b32 v213, v36, v37 offset0:36 offset1:54
	v_cvt_pk_f16_f32 v36, v50, v51
	v_cvt_pk_f16_f32 v37, v38, v39
	ds_write2st64_b32 v213, v36, v37 offset0:72 offset1:90
	v_cvt_f16_f32_e32 v36, v48
	v_pk_mul_f32 v[42:43], v[0:1], v[42:43]
	v_cvt_f16_f32_e32 v37, v49
	v_cvt_f16_f32_e32 v38, v42
	v_cvt_f16_f32_e32 v39, v43
	ds_write_b16 v178, v36 offset:30
	ds_write_b16 v178, v37 offset:70
	ds_write_b16 v178, v38 offset:5150
	s_waitcnt lgkmcnt(14)
	ds_write_b16 v178, v39 offset:5190
	s_nop 0
	s_waitcnt lgkmcnt(7)
	ds_write_b16 v178, v2 offset:10270
	v_perm_b32 v36, v61, v60, s82
	v_perm_b32 v37, v2, v58, s82
	ds_write_b64 v178, v[36:37] offset:10304
.LBB0_371:
	s_andn2_saveexec_b64 s[70:71], s[70:71]
	s_cbranch_execz .LBB0_373
	v_lshl_add_u32 v253, v198, 1, v2
	v_lshl_add_u32 v252, v200, 1, v2
	ds_read2st64_b32 v[36:37], v253 offset0:64 offset1:80
	ds_read2st64_b32 v[48:49], v253 offset0:96 offset1:112
	ds_read_b32 v64, v253 offset:32768
	ds_read2st64_b32 v[240:241], v252 offset0:64 offset1:80
	ds_read2st64_b32 v[242:243], v252 offset0:96 offset1:112
	v_lshl_add_u32 v52, v198, 1, v2
	s_nop 0
	s_nop 0
	s_nop 0
	v_rcp_f32_e32 v44, v58
	v_rcp_f32_e32 v45, v59
	s_waitcnt lgkmcnt(3)
	v_cvt_f32_f16_e32 v60, v49
	v_cvt_f32_f16_e32 v54, v37
	v_cvt_f32_f16_sdwa v55, v37 dst_sel:DWORD dst_unused:UNUSED_PAD src0_sel:WORD_1
	v_cvt_f32_f16_sdwa v61, v49 dst_sel:DWORD dst_unused:UNUSED_PAD src0_sel:WORD_1
	v_cvt_f32_f16_e32 v52, v36
	v_cvt_f32_f16_e32 v56, v48
	v_cvt_f32_f16_sdwa v57, v48 dst_sel:DWORD dst_unused:UNUSED_PAD src0_sel:WORD_1
	v_cvt_f32_f16_sdwa v53, v36 dst_sel:DWORD dst_unused:UNUSED_PAD src0_sel:WORD_1
	v_pk_mul_f32 v[36:37], v[38:39], v[54:55]
	v_pk_mul_f32 v[48:49], v[58:59], v[60:61]
	v_pk_mul_f32 v[54:55], v[44:45], v[56:57]
	v_pk_mul_f32 v[44:45], v[44:45], v[52:53]
	v_pk_mul_f32 v[52:53], v[40:41], v[36:37]
	v_pk_mul_f32 v[56:57], v[40:41], v[48:49]
	v_cvt_pk_f16_f32 v36, v36, v37
	v_cvt_pk_f16_f32 v37, v48, v49
	v_pk_mul_f32 v[60:61], v[38:39], v[54:55]
	v_pk_mul_f32 v[62:63], v[38:39], v[44:45]
	ds_write2st64_b32 v199, v36, v37 offset1:18
	v_cvt_pk_f16_f32 v36, v52, v53
	v_cvt_pk_f16_f32 v37, v56, v57
	v_pk_mul_f32 v[54:55], v[0:1], v[54:55]
	ds_write2st64_b32 v199, v36, v37 offset0:36 offset1:54
	v_cvt_pk_f16_f32 v36, v60, v61
	v_cvt_pk_f16_f32 v37, v62, v63
	v_lshl_add_u32 v253, v202, 1, v2
	ds_read_b32 v62, v252 offset:32768
	ds_write2st64_b32 v199, v36, v37 offset0:72 offset1:90
	v_cvt_f16_f32_e32 v36, v54
	v_pk_mul_f32 v[44:45], v[0:1], v[44:45]
	v_cvt_f16_f32_e32 v37, v55
	v_cvt_f16_f32_e32 v44, v44
	v_cvt_f16_f32_e32 v45, v45
	ds_write_b16 v178, v36 offset:16
	ds_write_b16 v178, v37 offset:56
	ds_write_b16 v178, v44 offset:5136
	ds_write_b16 v178, v45 offset:5176
	s_waitcnt lgkmcnt(10)
	ds_write_b16 v178, v64 offset:10256
	v_lshl_add_u32 v52, v200, 1, v2
	v_rcp_f32_e32 v44, v50
	v_rcp_f32_e32 v45, v51
	s_waitcnt lgkmcnt(10)
	v_cvt_f32_f16_e32 v54, v241
	v_cvt_f32_f16_sdwa v55, v241 dst_sel:DWORD dst_unused:UNUSED_PAD src0_sel:WORD_1
	s_waitcnt lgkmcnt(9)
	v_cvt_f32_f16_e32 v60, v243
	v_cvt_f32_f16_sdwa v61, v243 dst_sel:DWORD dst_unused:UNUSED_PAD src0_sel:WORD_1
	v_cvt_f32_f16_e32 v52, v240
	v_cvt_f32_f16_e32 v56, v242
	v_cvt_f32_f16_sdwa v57, v242 dst_sel:DWORD dst_unused:UNUSED_PAD src0_sel:WORD_1
	ds_read2st64_b32 v[242:243], v253 offset0:64 offset1:80
	v_cvt_f32_f16_sdwa v53, v240 dst_sel:DWORD dst_unused:UNUSED_PAD src0_sel:WORD_1
	ds_read2st64_b32 v[240:241], v253 offset0:96 offset1:112
	v_pk_mul_f32 v[36:37], v[58:59], v[54:55]
	v_pk_mul_f32 v[48:49], v[50:51], v[60:61]
	v_pk_mul_f32 v[54:55], v[44:45], v[56:57]
	v_pk_mul_f32 v[44:45], v[44:45], v[52:53]
	v_pk_mul_f32 v[52:53], v[40:41], v[36:37]
	v_pk_mul_f32 v[56:57], v[40:41], v[48:49]
	v_cvt_pk_f16_f32 v36, v36, v37
	v_cvt_pk_f16_f32 v37, v48, v49
	v_pk_mul_f32 v[58:59], v[38:39], v[54:55]
	v_pk_mul_f32 v[60:61], v[38:39], v[44:45]
	ds_write2st64_b32 v201, v36, v37 offset1:18
	v_cvt_pk_f16_f32 v36, v52, v53
	v_cvt_pk_f16_f32 v37, v56, v57
	v_pk_mul_f32 v[54:55], v[0:1], v[54:55]
	ds_write2st64_b32 v201, v36, v37 offset0:36 offset1:54
	v_cvt_pk_f16_f32 v36, v58, v59
	v_cvt_pk_f16_f32 v37, v60, v61
	v_lshl_add_u32 v252, v204, 1, v2
	ds_read_b32 v60, v253 offset:32768
	ds_write2st64_b32 v201, v36, v37 offset0:72 offset1:90
	v_cvt_f16_f32_e32 v36, v54
	v_pk_mul_f32 v[44:45], v[0:1], v[44:45]
	v_cvt_f16_f32_e32 v37, v55
	v_cvt_f16_f32_e32 v44, v44
	v_cvt_f16_f32_e32 v45, v45
	s_waitcnt lgkmcnt(14)
	ds_write_b16 v178, v36 offset:18
	s_waitcnt lgkmcnt(14)
	ds_write_b16 v178, v37 offset:58
	s_waitcnt lgkmcnt(14)
	ds_write_b16 v178, v44 offset:5138
	s_waitcnt lgkmcnt(14)
	ds_write_b16 v178, v45 offset:5178
	s_waitcnt lgkmcnt(14)
	ds_write_b16 v178, v62 offset:10258
	v_lshl_add_u32 v52, v202, 1, v2
	v_rcp_f32_e32 v44, v46
	v_rcp_f32_e32 v45, v47
	v_lshl_add_u32 v2, v204, 1, v2
	s_waitcnt lgkmcnt(10)
	v_cvt_f32_f16_e32 v54, v243
	v_cvt_f32_f16_sdwa v55, v243 dst_sel:DWORD dst_unused:UNUSED_PAD src0_sel:WORD_1
	s_waitcnt lgkmcnt(9)
	v_cvt_f32_f16_e32 v58, v241
	v_cvt_f32_f16_sdwa v59, v241 dst_sel:DWORD dst_unused:UNUSED_PAD src0_sel:WORD_1
	v_cvt_f32_f16_e32 v52, v242
	v_cvt_f32_f16_e32 v56, v240
	v_cvt_f32_f16_sdwa v57, v240 dst_sel:DWORD dst_unused:UNUSED_PAD src0_sel:WORD_1
	ds_read2st64_b32 v[240:241], v252 offset0:64 offset1:80
	v_cvt_f32_f16_sdwa v53, v242 dst_sel:DWORD dst_unused:UNUSED_PAD src0_sel:WORD_1
	ds_read2st64_b32 v[242:243], v2 offset0:96 offset1:112
	v_pk_mul_f32 v[36:37], v[50:51], v[54:55]
	v_pk_mul_f32 v[48:49], v[46:47], v[58:59]
	v_pk_mul_f32 v[50:51], v[44:45], v[56:57]
	v_pk_mul_f32 v[44:45], v[44:45], v[52:53]
	v_pk_mul_f32 v[52:53], v[40:41], v[36:37]
	v_pk_mul_f32 v[54:55], v[40:41], v[48:49]
	v_cvt_pk_f16_f32 v36, v36, v37
	v_cvt_pk_f16_f32 v37, v48, v49
	v_pk_mul_f32 v[56:57], v[38:39], v[50:51]
	v_pk_mul_f32 v[58:59], v[38:39], v[44:45]
	ds_write2st64_b32 v203, v36, v37 offset1:18
	v_cvt_pk_f16_f32 v36, v52, v53
	v_cvt_pk_f16_f32 v37, v54, v55
	v_pk_mul_f32 v[50:51], v[0:1], v[50:51]
	ds_write2st64_b32 v203, v36, v37 offset0:36 offset1:54
	v_cvt_pk_f16_f32 v36, v56, v57
	v_cvt_pk_f16_f32 v37, v58, v59
	ds_write2st64_b32 v203, v36, v37 offset0:72 offset1:90
	v_cvt_f16_f32_e32 v36, v50
	v_pk_mul_f32 v[44:45], v[0:1], v[44:45]
	v_cvt_f16_f32_e32 v37, v51
	v_cvt_f16_f32_e32 v44, v44
	v_cvt_f16_f32_e32 v45, v45
	ds_write_b16 v178, v36 offset:20
	s_waitcnt lgkmcnt(14)
	ds_write_b16 v178, v37 offset:60
	s_waitcnt lgkmcnt(14)
	ds_write_b16 v178, v44 offset:5140
	s_waitcnt lgkmcnt(14)
	ds_write_b16 v178, v45 offset:5180
	s_waitcnt lgkmcnt(14)
	ds_write_b16 v178, v60 offset:10260
	s_waitcnt lgkmcnt(14)
	ds_read_b32 v2, v2 offset:32768
	v_rcp_f32_e32 v44, v42
	v_rcp_f32_e32 v45, v43
	s_waitcnt lgkmcnt(10)
	v_cvt_f32_f16_e32 v52, v241
	v_cvt_f32_f16_sdwa v53, v241 dst_sel:DWORD dst_unused:UNUSED_PAD src0_sel:WORD_1
	s_waitcnt lgkmcnt(9)
	v_cvt_f32_f16_e32 v56, v243
	v_cvt_f32_f16_sdwa v57, v243 dst_sel:DWORD dst_unused:UNUSED_PAD src0_sel:WORD_1
	v_cvt_f32_f16_e32 v50, v240
	v_cvt_f32_f16_e32 v54, v242
	v_cvt_f32_f16_sdwa v55, v242 dst_sel:DWORD dst_unused:UNUSED_PAD src0_sel:WORD_1
	v_cvt_f32_f16_sdwa v51, v240 dst_sel:DWORD dst_unused:UNUSED_PAD src0_sel:WORD_1
	v_pk_mul_f32 v[36:37], v[46:47], v[52:53]
	v_pk_mul_f32 v[42:43], v[42:43], v[56:57]
	v_pk_mul_f32 v[46:47], v[44:45], v[54:55]
	v_pk_mul_f32 v[44:45], v[44:45], v[50:51]
	v_pk_mul_f32 v[48:49], v[40:41], v[36:37]
	v_pk_mul_f32 v[40:41], v[40:41], v[42:43]
	v_cvt_pk_f16_f32 v36, v36, v37
	v_cvt_pk_f16_f32 v37, v42, v43
	v_pk_mul_f32 v[50:51], v[38:39], v[46:47]
	v_pk_mul_f32 v[38:39], v[38:39], v[44:45]
	ds_write2st64_b32 v205, v36, v37 offset1:18
	v_cvt_pk_f16_f32 v36, v48, v49
	v_cvt_pk_f16_f32 v37, v40, v41
	v_pk_mul_f32 v[46:47], v[0:1], v[46:47]
	ds_write2st64_b32 v205, v36, v37 offset0:36 offset1:54
	v_cvt_pk_f16_f32 v36, v50, v51
	v_cvt_pk_f16_f32 v37, v38, v39
	ds_write2st64_b32 v205, v36, v37 offset0:72 offset1:90
	v_cvt_f16_f32_e32 v36, v46
	v_pk_mul_f32 v[44:45], v[0:1], v[44:45]
	v_cvt_f16_f32_e32 v37, v47
	v_cvt_f16_f32_e32 v38, v44
	v_cvt_f16_f32_e32 v39, v45
	ds_write_b16 v178, v36 offset:22
	ds_write_b16 v178, v37 offset:62
	ds_write_b16 v178, v38 offset:5142
	s_waitcnt lgkmcnt(14)
	ds_write_b16 v178, v39 offset:5182
	s_nop 0
	s_waitcnt lgkmcnt(7)
	ds_write_b16 v178, v2 offset:10262
	v_perm_b32 v36, v62, v64, s82
	v_perm_b32 v37, v2, v60, s82
	ds_write_b64 v178, v[36:37] offset:10296

.LBB0_374:
	v_cmp_eq_u32_e32 vcc, 1, v176
	s_and_saveexec_b64 s[70:71], vcc
	s_cbranch_execz .LBB0_376
	v_lshl_add_u32 v253, v190, 1, v2
	v_lshl_add_u32 v252, v192, 1, v2
	ds_read2st64_b32 v[36:37], v253 offset0:64 offset1:80
	ds_read2st64_b32 v[46:47], v253 offset0:96 offset1:112
	ds_read_b32 v62, v253 offset:32768
	ds_read2st64_b32 v[240:241], v252 offset0:64 offset1:80
	ds_read2st64_b32 v[242:243], v252 offset0:96 offset1:112
	v_lshl_add_u32 v50, v190, 1, v2
	s_nop 0
	s_nop 0
	s_nop 0
	v_rcp_f32_e32 v42, v54
	v_rcp_f32_e32 v43, v55
	s_waitcnt lgkmcnt(3)
	v_cvt_f32_f16_e32 v58, v47
	v_cvt_f32_f16_e32 v52, v37
	v_cvt_f32_f16_sdwa v53, v37 dst_sel:DWORD dst_unused:UNUSED_PAD src0_sel:WORD_1
	v_cvt_f32_f16_sdwa v59, v47 dst_sel:DWORD dst_unused:UNUSED_PAD src0_sel:WORD_1
	v_cvt_f32_f16_e32 v50, v36
	v_cvt_f32_f16_e32 v56, v46
	v_cvt_f32_f16_sdwa v57, v46 dst_sel:DWORD dst_unused:UNUSED_PAD src0_sel:WORD_1
	v_cvt_f32_f16_sdwa v51, v36 dst_sel:DWORD dst_unused:UNUSED_PAD src0_sel:WORD_1
	v_pk_mul_f32 v[36:37], v[60:61], v[52:53]
	v_pk_mul_f32 v[46:47], v[54:55], v[58:59]
	v_pk_mul_f32 v[52:53], v[42:43], v[56:57]
	v_pk_mul_f32 v[42:43], v[42:43], v[50:51]
	v_pk_mul_f32 v[50:51], v[40:41], v[36:37]
	v_pk_mul_f32 v[56:57], v[40:41], v[46:47]
	v_cvt_pk_f16_f32 v36, v36, v37
	v_cvt_pk_f16_f32 v37, v46, v47
	v_pk_mul_f32 v[58:59], v[38:39], v[52:53]
	v_pk_mul_f32 v[60:61], v[38:39], v[42:43]
	ds_write2st64_b32 v191, v36, v37 offset1:18
	v_cvt_pk_f16_f32 v36, v50, v51
	v_cvt_pk_f16_f32 v37, v56, v57
	v_pk_mul_f32 v[52:53], v[0:1], v[52:53]
	ds_write2st64_b32 v191, v36, v37 offset0:36 offset1:54
	v_cvt_pk_f16_f32 v36, v58, v59
	v_cvt_pk_f16_f32 v37, v60, v61
	v_lshl_add_u32 v253, v194, 1, v2
	ds_read_b32 v60, v252 offset:32768
	ds_write2st64_b32 v191, v36, v37 offset0:72 offset1:90
	v_cvt_f16_f32_e32 v36, v52
	v_pk_mul_f32 v[42:43], v[0:1], v[42:43]
	v_cvt_f16_f32_e32 v37, v53
	v_cvt_f16_f32_e32 v42, v42
	v_cvt_f16_f32_e32 v43, v43
	ds_write_b16 v178, v36 offset:8
	ds_write_b16 v178, v37 offset:48
	ds_write_b16 v178, v42 offset:5128
	ds_write_b16 v178, v43 offset:5168
	s_waitcnt lgkmcnt(10)
	ds_write_b16 v178, v62 offset:10248
	v_lshl_add_u32 v50, v192, 1, v2
	v_rcp_f32_e32 v42, v48
	v_rcp_f32_e32 v43, v49
	s_waitcnt lgkmcnt(10)
	v_cvt_f32_f16_e32 v52, v241
	v_cvt_f32_f16_sdwa v53, v241 dst_sel:DWORD dst_unused:UNUSED_PAD src0_sel:WORD_1
	s_waitcnt lgkmcnt(9)
	v_cvt_f32_f16_e32 v58, v243
	v_cvt_f32_f16_sdwa v59, v243 dst_sel:DWORD dst_unused:UNUSED_PAD src0_sel:WORD_1
	v_cvt_f32_f16_e32 v50, v240
	v_cvt_f32_f16_e32 v56, v242
	v_cvt_f32_f16_sdwa v57, v242 dst_sel:DWORD dst_unused:UNUSED_PAD src0_sel:WORD_1
	ds_read2st64_b32 v[242:243], v253 offset0:64 offset1:80
	v_cvt_f32_f16_sdwa v51, v240 dst_sel:DWORD dst_unused:UNUSED_PAD src0_sel:WORD_1
	ds_read2st64_b32 v[240:241], v253 offset0:96 offset1:112
	v_pk_mul_f32 v[36:37], v[54:55], v[52:53]
	v_pk_mul_f32 v[46:47], v[48:49], v[58:59]
	v_pk_mul_f32 v[52:53], v[42:43], v[56:57]
	v_pk_mul_f32 v[42:43], v[42:43], v[50:51]
	v_pk_mul_f32 v[50:51], v[40:41], v[36:37]
	v_pk_mul_f32 v[54:55], v[40:41], v[46:47]
	v_cvt_pk_f16_f32 v36, v36, v37
	v_cvt_pk_f16_f32 v37, v46, v47
	v_pk_mul_f32 v[56:57], v[38:39], v[52:53]
	v_pk_mul_f32 v[58:59], v[38:39], v[42:43]
	ds_write2st64_b32 v193, v36, v37 offset1:18
	v_cvt_pk_f16_f32 v36, v50, v51
	v_cvt_pk_f16_f32 v37, v54, v55
	v_pk_mul_f32 v[52:53], v[0:1], v[52:53]
	ds_write2st64_b32 v193, v36, v37 offset0:36 offset1:54
	v_cvt_pk_f16_f32 v36, v56, v57
	v_cvt_pk_f16_f32 v37, v58, v59
	v_lshl_add_u32 v252, v196, 1, v2
	ds_read_b32 v58, v253 offset:32768
	ds_write2st64_b32 v193, v36, v37 offset0:72 offset1:90
	v_cvt_f16_f32_e32 v36, v52
	v_pk_mul_f32 v[42:43], v[0:1], v[42:43]
	v_cvt_f16_f32_e32 v37, v53
	v_cvt_f16_f32_e32 v42, v42
	v_cvt_f16_f32_e32 v43, v43
	s_waitcnt lgkmcnt(14)
	ds_write_b16 v178, v36 offset:10
	s_waitcnt lgkmcnt(14)
	ds_write_b16 v178, v37 offset:50
	s_waitcnt lgkmcnt(14)
	ds_write_b16 v178, v42 offset:5130
	s_waitcnt lgkmcnt(14)
	ds_write_b16 v178, v43 offset:5170
	s_waitcnt lgkmcnt(14)
	ds_write_b16 v178, v60 offset:10250
	v_lshl_add_u32 v50, v194, 1, v2
	v_rcp_f32_e32 v42, v44
	v_rcp_f32_e32 v43, v45
	v_lshl_add_u32 v2, v196, 1, v2
	s_waitcnt lgkmcnt(10)
	v_cvt_f32_f16_e32 v52, v243
	v_cvt_f32_f16_sdwa v53, v243 dst_sel:DWORD dst_unused:UNUSED_PAD src0_sel:WORD_1
	s_waitcnt lgkmcnt(9)
	v_cvt_f32_f16_e32 v56, v241
	v_cvt_f32_f16_sdwa v57, v241 dst_sel:DWORD dst_unused:UNUSED_PAD src0_sel:WORD_1
	v_cvt_f32_f16_e32 v50, v242
	v_cvt_f32_f16_e32 v54, v240
	v_cvt_f32_f16_sdwa v55, v240 dst_sel:DWORD dst_unused:UNUSED_PAD src0_sel:WORD_1
	ds_read2st64_b32 v[240:241], v252 offset0:64 offset1:80
	v_cvt_f32_f16_sdwa v51, v242 dst_sel:DWORD dst_unused:UNUSED_PAD src0_sel:WORD_1
	ds_read2st64_b32 v[242:243], v2 offset0:96 offset1:112
	v_pk_mul_f32 v[36:37], v[48:49], v[52:53]
	v_pk_mul_f32 v[46:47], v[44:45], v[56:57]
	v_pk_mul_f32 v[48:49], v[42:43], v[54:55]
	v_pk_mul_f32 v[42:43], v[42:43], v[50:51]
	v_pk_mul_f32 v[50:51], v[40:41], v[36:37]
	v_pk_mul_f32 v[52:53], v[40:41], v[46:47]
	v_cvt_pk_f16_f32 v36, v36, v37
	v_cvt_pk_f16_f32 v37, v46, v47
	v_pk_mul_f32 v[54:55], v[38:39], v[48:49]
	v_pk_mul_f32 v[56:57], v[38:39], v[42:43]
	ds_write2st64_b32 v195, v36, v37 offset1:18
	v_cvt_pk_f16_f32 v36, v50, v51
	v_cvt_pk_f16_f32 v37, v52, v53
	v_pk_mul_f32 v[48:49], v[0:1], v[48:49]
	ds_write2st64_b32 v195, v36, v37 offset0:36 offset1:54
	v_cvt_pk_f16_f32 v36, v54, v55
	v_cvt_pk_f16_f32 v37, v56, v57
	ds_write2st64_b32 v195, v36, v37 offset0:72 offset1:90
	v_cvt_f16_f32_e32 v36, v48
	v_pk_mul_f32 v[42:43], v[0:1], v[42:43]
	v_cvt_f16_f32_e32 v37, v49
	v_cvt_f16_f32_e32 v42, v42
	v_cvt_f16_f32_e32 v43, v43
	ds_write_b16 v178, v36 offset:12
	s_waitcnt lgkmcnt(14)
	ds_write_b16 v178, v37 offset:52
	s_waitcnt lgkmcnt(14)
	ds_write_b16 v178, v42 offset:5132
	s_waitcnt lgkmcnt(14)
	ds_write_b16 v178, v43 offset:5172
	s_waitcnt lgkmcnt(14)
	ds_write_b16 v178, v58 offset:10252
	s_waitcnt lgkmcnt(14)
	ds_read_b32 v2, v2 offset:32768
	s_waitcnt lgkmcnt(10)
	v_cvt_f32_f16_e32 v48, v241
	v_cvt_f32_f16_sdwa v49, v241 dst_sel:DWORD dst_unused:UNUSED_PAD src0_sel:WORD_1
	s_waitcnt lgkmcnt(9)
	v_cvt_f32_f16_e32 v52, v243
	v_cvt_f32_f16_sdwa v53, v243 dst_sel:DWORD dst_unused:UNUSED_PAD src0_sel:WORD_1
	v_cvt_f32_f16_e32 v46, v240
	v_cvt_f32_f16_e32 v50, v242
	v_cvt_f32_f16_sdwa v51, v242 dst_sel:DWORD dst_unused:UNUSED_PAD src0_sel:WORD_1
	v_cvt_f32_f16_sdwa v47, v240 dst_sel:DWORD dst_unused:UNUSED_PAD src0_sel:WORD_1
	v_pk_mul_f32 v[36:37], v[44:45], v[48:49]
	v_pk_mul_f32 v[42:43], v[38:39], v[52:53]
	v_pk_mul_f32 v[44:45], v[40:41], v[50:51]
	v_pk_mul_f32 v[46:47], v[40:41], v[46:47]
	v_pk_mul_f32 v[48:49], v[40:41], v[36:37]
	v_pk_mul_f32 v[40:41], v[40:41], v[42:43]
	v_cvt_pk_f16_f32 v36, v36, v37
	v_cvt_pk_f16_f32 v37, v42, v43
	v_pk_mul_f32 v[50:51], v[38:39], v[44:45]
	v_pk_mul_f32 v[38:39], v[38:39], v[46:47]
	ds_write2st64_b32 v197, v36, v37 offset1:18
	v_cvt_pk_f16_f32 v36, v48, v49
	v_cvt_pk_f16_f32 v37, v40, v41
	v_pk_mul_f32 v[44:45], v[0:1], v[44:45]
	ds_write2st64_b32 v197, v36, v37 offset0:36 offset1:54
	v_cvt_pk_f16_f32 v36, v50, v51
	v_cvt_pk_f16_f32 v37, v38, v39
	ds_write2st64_b32 v197, v36, v37 offset0:72 offset1:90
	v_cvt_f16_f32_e32 v36, v44
	v_pk_mul_f32 v[46:47], v[0:1], v[46:47]
	v_cvt_f16_f32_e32 v37, v45
	v_cvt_f16_f32_e32 v38, v46
	v_cvt_f16_f32_e32 v39, v47
	ds_write_b16 v178, v36 offset:14
	ds_write_b16 v178, v37 offset:54
	ds_write_b16 v178, v38 offset:5134
	s_waitcnt lgkmcnt(14)
	ds_write_b16 v178, v39 offset:5174
	s_nop 0
	s_waitcnt lgkmcnt(7)
	ds_write_b16 v178, v2 offset:10254
	v_perm_b32 v36, v60, v62, s82
	v_perm_b32 v37, v2, v58, s82
	ds_write_b64 v178, v[36:37] offset:10288

.LBB0_421:
	s_or_b64 exec, exec, s[0:1]
	s_nop 5
	v_cvt_f16_f32_e32 v65, v65
	v_cvt_f16_f32_e32 v64, v64
	s_add_i32 s30, s30, 1
	v_cndmask_b32_e64 v68, 0, v65, s[24:25]
	v_cvt_f16_f32_e32 v65, v66
	v_cvt_f16_f32_e32 v66, v67
	v_cndmask_b32_e64 v64, v64, 0, s[22:23]
	v_pack_b32_f16 v64, v64, v68
	v_cndmask_b32_e64 v65, v65, 0, s[26:27]
	v_cndmask_b32_e64 v66, v66, 0, s[28:29]
	v_pack_b32_f16 v65, v65, v66
	ds_write_b64 v115, v[64:65]
	s_waitcnt lgkmcnt(0)
	s_barrier
	ds_read_b128 v[118:121], v116 offset:55360
	ds_read_b128 v[122:125], v117
	ds_read_b128 v[178:181], v117 offset:64
	ds_read_b128 v[182:185], v117 offset:2304
	ds_read_b128 v[186:189], v117 offset:2368
	ds_read_b128 v[190:193], v117 offset:4608
	ds_read_b128 v[194:197], v117 offset:4672
	ds_read_b128 v[198:201], v117 offset:6912
	ds_read_b128 v[64:67], v116 offset:55296
	ds_read_b128 v[202:205], v117 offset:6976
	s_nop 0
	s_nop 0
	s_nop 0
	v_add_u32_e32 v253, 0x1e500, v87
	s_waitcnt lgkmcnt(1)
	v_mfma_f32_16x16x32_f16 v[52:55], v[64:67], v[122:125], v[52:55]
	ds_read_b128 v[206:209], v253
	s_nop 0
	v_add_u32_e32 v68, 0x1e500, v87
	s_nop 0
	v_mfma_f32_16x16x32_f16 v[52:55], v[118:121], v[178:181], v[52:55]
	s_nop 0
	ds_read_b128 v[178:181], v248 offset:46080
	s_nop 0
	v_mfma_f32_16x16x32_f16 v[56:59], v[64:67], v[182:185], v[56:59]
	s_nop 0
	s_nop 3
	ds_read_b128 v[182:185], v248 offset:46144
	v_cvt_pk_f16_f32 v55, v54, v55
	v_cvt_pk_f16_f32 v54, v52, v53
	s_nop 0
	ds_read_b128 v[226:229], v68 offset:64
	v_mfma_f32_16x16x32_f16 v[56:59], v[118:121], v[186:189], v[56:59]
	v_mfma_f32_16x16x32_f16 v[60:63], v[64:67], v[190:193], v[60:63]
	ds_read_b128 v[186:189], v249 offset:48384
	s_nop 0
	s_nop 0
	v_mfma_f32_16x16x32_f16 v[60:63], v[118:121], v[194:197], v[60:63]
	ds_read_b128 v[190:193], v249 offset:48448
	v_mfma_f32_16x16x32_f16 v[48:51], v[64:67], v[198:201], v[48:51]
	ds_read_b128 v[194:197], v68 offset:128
	s_nop 0
	s_nop 0
	s_waitcnt lgkmcnt(7)
	v_mfma_f32_16x16x32_f16 v[48:51], v[118:121], v[202:205], v[48:51]
	s_nop 0
	ds_read_b128 v[198:201], v248 offset:50688
	s_nop 0
	s_waitcnt lgkmcnt(7)
	v_pk_mul_f32 v[8:9], v[8:9], v[206:207]
	v_pk_mul_f32 v[10:11], v[10:11], v[208:209]
	ds_read_b128 v[202:205], v248 offset:50752
	s_nop 0
	s_nop 2
	v_cvt_pk_f16_f32 v51, v50, v51
	ds_read_b128 v[206:209], v68 offset:192
	s_waitcnt lgkmcnt(8)
	v_mfma_f32_16x16x32_f16 v[8:11], v[178:181], v[64:67], v[8:11]
	s_nop 0
	v_cvt_pk_f16_f32 v50, v48, v49
	s_nop 0
	s_waitcnt lgkmcnt(7)
	v_mfma_f32_16x16x32_f16 v[8:11], v[182:185], v[118:121], v[8:11]
	s_waitcnt lgkmcnt(6)
	v_pk_mul_f32 v[4:5], v[4:5], v[226:227]
	v_pk_mul_f32 v[6:7], v[6:7], v[228:229]
	s_nop 0
	s_nop 0
	s_waitcnt lgkmcnt(5)
	v_mfma_f32_16x16x32_f16 v[4:7], v[186:189], v[64:67], v[4:7]
	s_nop 0
	s_nop 0
	s_waitcnt lgkmcnt(4)
	v_mfma_f32_16x16x32_f16 v[4:7], v[190:193], v[118:121], v[4:7]
	s_waitcnt lgkmcnt(3)
	v_pk_mul_f32 v[16:17], v[16:17], v[194:195]
	v_pk_mul_f32 v[18:19], v[18:19], v[196:197]
	s_nop 0
	s_nop 0
	s_waitcnt lgkmcnt(2)
	v_mfma_f32_16x16x32_f16 v[16:19], v[198:201], v[64:67], v[16:19]
	s_nop 0
	s_nop 0
	s_waitcnt lgkmcnt(1)
	v_mfma_f32_16x16x32_f16 v[16:19], v[202:205], v[118:121], v[16:19]
	s_waitcnt lgkmcnt(0)
	v_pk_mul_f32 v[12:13], v[12:13], v[206:207]
	v_pk_mul_f32 v[14:15], v[14:15], v[208:209]
	ds_read_b128 v[122:125], v249 offset:52992
	s_nop 0
	s_waitcnt lgkmcnt(0)
	v_mfma_f32_16x16x32_f16 v[12:15], v[122:125], v[64:67], v[12:15]
	ds_read_b128 v[64:67], v249 offset:53056
	s_nop 0
	s_waitcnt lgkmcnt(0)
	v_mfma_f32_16x16x32_f16 v[12:15], v[64:67], v[118:121], v[12:15]
	v_add_u32_e32 v65, s79, v104
	v_add_u32_e32 v64, s78, v80
	v_add_u32_e32 v66, 0x7ff, v65
	v_cndmask_b32_e64 v66, v66, v64, s[2:3]
	v_add_u32_e32 v52, v66, v81
	v_mad_i64_i32 v[52:53], s[0:1], v52, s91, v[76:77]
	global_store_dwordx2 v[52:53], v[54:55], off
	v_add_u32_e32 v52, 16, v64
	v_add_u32_e32 v53, 0x7ef, v65
	v_cndmask_b32_e64 v54, v53, v52, s[2:3]
	v_add_u32_e32 v54, v54, v81
	v_cvt_pk_f16_f32 v53, v58, v59
	v_cvt_pk_f16_f32 v52, v56, v57
	v_mad_i64_i32 v[54:55], s[0:1], v54, s91, v[76:77]
	global_store_dwordx2 v[54:55], v[52:53], off
	v_add_u32_e32 v52, 32, v64
	v_add_u32_e32 v53, 0x7df, v65
	v_cndmask_b32_e64 v54, v53, v52, s[2:3]
	v_add_u32_e32 v54, v54, v81
	v_cvt_pk_f16_f32 v53, v62, v63
	v_cvt_pk_f16_f32 v52, v60, v61
	v_mad_i64_i32 v[54:55], s[0:1], v54, s91, v[76:77]
	global_store_dwordx2 v[54:55], v[52:53], off
	v_add_u32_e32 v52, 48, v64
	v_add_u32_e32 v53, 0x7cf, v65
	v_cndmask_b32_e64 v52, v53, v52, s[2:3]
	v_add_u32_e32 v48, v52, v81
	s_sub_i32 s79, s79, 64
	s_add_i32 s78, s78, 64
	v_mad_i64_i32 v[48:49], s[0:1], v48, s91, v[76:77]
	s_cmpk_lg_i32 s79, 0xf800
	global_store_dwordx2 v[48:49], v[50:51], off
	s_cbranch_scc0 .LBB0_438

.LBB0_434:
	s_or_b64 exec, exec, s[0:1]
	v_add_u32_e32 v57, s78, v82
	v_add_u32_e32 v56, 0x7ff, v56
	v_cndmask_b32_e64 v56, v56, v57, s[2:3]
	s_waitcnt lgkmcnt(0)
	s_barrier
	ds_read_b128 v[58:61], v83
	ds_read_b128 v[62:65], v88
	ds_read_b128 v[48:51], v83 offset:9216
	s_nop 0
	ds_read_b128 v[66:69], v85
	ds_read_b128 v[52:55], v88 offset:9216
	v_lshrrev_b32_e32 v57, 6, v56
	v_and_b32_e32 v56, 63, v56
	v_cndmask_b32_e64 v56, v56, v57, s[6:7]
	v_lshl_or_b32 v57, v56, 6, v112
	s_nop 0
	v_add_u32_e32 v253, s83, v57
	ds_read_b128 v[122:125], v253
	ds_read_b128 v[118:121], v250 offset:16
	v_add_u32_e32 v75, s83, v57
	s_add_i32 s0, 0, 0x1f600
	v_add_u32_e32 v252, s0, v57
	ds_read_b128 v[126:129], v252
	v_add_u32_e32 v79, s0, v57
	s_waitcnt lgkmcnt(6)
	v_cvt_f32_f16_sdwa v137, v62 dst_sel:DWORD dst_unused:UNUSED_PAD src0_sel:WORD_1
	v_cvt_f32_f16_e32 v136, v62
	v_or_b32_e32 v57, 16, v57
	v_cvt_f32_f16_sdwa v135, v58 dst_sel:DWORD dst_unused:UNUSED_PAD src0_sel:WORD_1
	v_cvt_f32_f16_e32 v134, v58
	s_nop 0
	s_waitcnt lgkmcnt(4)
	v_mul_f32_e32 v56, 0x3fb8aa3b, v66
	v_add_u32_e32 v140, s83, v57
	ds_read_b128 v[130:133], v93
	v_add_u32_e32 v141, s0, v57
	v_mul_f32_e32 v57, 0x3fb8aa3b, v67
	v_exp_f32_e32 v56, v56
	v_exp_f32_e32 v57, v57
	v_pk_mul_f32 v[136:137], v[136:137], s[68:69] op_sel_hi:[1,0]
	v_pk_mul_f32 v[134:135], v[134:135], s[68:69] op_sel_hi:[1,0]
	s_nop 0
	s_waitcnt lgkmcnt(1)
	v_pk_mul_f32 v[136:137], v[136:137], v[126:127]
	v_rcp_f32_e32 v66, v56
	v_cndmask_b32_e64 v137, v137, -v137, s[8:9]
	v_cndmask_b32_e64 v136, v136, -v136, s[8:9]
	v_pk_fma_f32 v[134:135], v[134:135], v[122:123], v[136:137]
	v_cvt_f32_f16_sdwa v137, v48 dst_sel:DWORD dst_unused:UNUSED_PAD src0_sel:WORD_1
	v_pk_mul_f32 v[138:139], v[134:135], v[56:57]
	v_cvt_f32_f16_sdwa v135, v52 dst_sel:DWORD dst_unused:UNUSED_PAD src0_sel:WORD_1
	v_cvt_f32_f16_e32 v134, v52
	v_cvt_f32_f16_e32 v136, v48
	s_nop 0
	v_rcp_f32_e32 v67, v57
	v_pk_mul_f32 v[126:127], v[126:127], v[134:135]
	v_add3_u32 v52, v72, v89, v247
	v_cndmask_b32_e64 v127, v127, -v127, s[8:9]
	v_cndmask_b32_e64 v126, v126, -v126, s[8:9]
	v_pk_fma_f32 v[122:123], v[122:123], v[136:137], v[126:127]
	ds_read_b128 v[134:137], v94
	v_pk_mul_f32 v[126:127], v[122:123], v[66:67]
	v_cvt_f32_f16_e32 v58, v63
	s_nop 0
	s_waitcnt lgkmcnt(1)
	v_fma_mixlo_f16 v48, v130, v126, 0
	ds_write_b16 v52, v48 offset:46080
	v_fma_mixlo_f16 v48, v131, v127, 0
	ds_write_b16 v113, v48 offset:46080
	v_mul_f32_e32 v48, 0x3fb8aa3b, v68
	v_exp_f32_e32 v66, v48
	v_mul_f32_e32 v48, 0x3fb8aa3b, v69
	v_cvt_f32_f16_sdwa v69, v59 dst_sel:DWORD dst_unused:UNUSED_PAD src0_sel:WORD_1
	v_cvt_f32_f16_e32 v68, v59
	v_cvt_f32_f16_sdwa v59, v63 dst_sel:DWORD dst_unused:UNUSED_PAD src0_sel:WORD_1
	v_exp_f32_e32 v67, v48
	v_cvt_f32_f16_e32 v52, v49
	v_pk_mul_f32 v[68:69], v[68:69], s[68:69] op_sel_hi:[1,0]
	v_pk_mul_f32 v[58:59], v[58:59], s[68:69] op_sel_hi:[1,0]
	v_rcp_f32_e32 v62, v66
	v_pk_mul_f32 v[58:59], v[58:59], v[128:129]
	v_rcp_f32_e32 v63, v67
	v_cndmask_b32_e64 v59, v59, -v59, s[8:9]
	v_cndmask_b32_e64 v58, v58, -v58, s[8:9]
	v_pk_fma_f32 v[58:59], v[68:69], v[124:125], v[58:59]
	v_cvt_pk_f16_f32 v56, v138, v139
	v_pk_mul_f32 v[130:131], v[58:59], v[66:67]
	v_cvt_f32_f16_sdwa v59, v53 dst_sel:DWORD dst_unused:UNUSED_PAD src0_sel:WORD_1
	v_cvt_f32_f16_e32 v58, v53
	v_cvt_f32_f16_sdwa v53, v49 dst_sel:DWORD dst_unused:UNUSED_PAD src0_sel:WORD_1
	v_cvt_pk_f16_f32 v57, v130, v131
	v_pk_mul_f32 v[48:49], v[128:129], v[58:59]
	s_nop 0
	v_cndmask_b32_e64 v49, v49, -v49, s[8:9]
	v_cndmask_b32_e64 v48, v48, -v48, s[8:9]
	v_pk_fma_f32 v[48:49], v[124:125], v[52:53], v[48:49]
	v_cvt_f32_f16_sdwa v59, v60 dst_sel:DWORD dst_unused:UNUSED_PAD src0_sel:WORD_1
	v_pk_mul_f32 v[48:49], v[48:49], v[62:63]
	v_cvt_f32_f16_sdwa v63, v64 dst_sel:DWORD dst_unused:UNUSED_PAD src0_sel:WORD_1
	v_fma_mixlo_f16 v52, v132, v48, 0
	ds_write_b16 v113, v52 offset:46224
	v_fma_mixlo_f16 v52, v133, v49, 0
	ds_write_b16 v113, v52 offset:46368
	ds_read_b128 v[122:125], v141
	ds_read_b128 v[66:69], v140
	v_cvt_f32_f16_e32 v62, v64
	v_cvt_f32_f16_e32 v58, v60
	v_mul_f32_e32 v52, 0x3fb8aa3b, v118
	v_mul_f32_e32 v53, 0x3fb8aa3b, v119
	v_pk_mul_f32 v[62:63], v[62:63], s[68:69] op_sel_hi:[1,0]
	v_exp_f32_e32 v52, v52
	s_nop 0
	s_waitcnt lgkmcnt(1)
	v_pk_mul_f32 v[62:63], v[62:63], v[122:123]
	v_exp_f32_e32 v53, v53
	v_pk_mul_f32 v[58:59], v[58:59], s[68:69] op_sel_hi:[1,0]
	v_cndmask_b32_e64 v63, v63, -v63, s[8:9]
	v_cndmask_b32_e64 v62, v62, -v62, s[8:9]
	s_waitcnt lgkmcnt(0)
	v_pk_fma_f32 v[58:59], v[58:59], v[66:67], v[62:63]
	v_cvt_f32_f16_sdwa v63, v54 dst_sel:DWORD dst_unused:UNUSED_PAD src0_sel:WORD_1
	v_cvt_f32_f16_e32 v62, v54
	v_cvt_f32_f16_sdwa v129, v50 dst_sel:DWORD dst_unused:UNUSED_PAD src0_sel:WORD_1
	v_cvt_f32_f16_e32 v128, v50
	v_rcp_f32_e32 v118, v52
	v_rcp_f32_e32 v119, v53
	v_pk_mul_f32 v[62:63], v[122:123], v[62:63]
	v_cvt_f32_f16_e32 v60, v65
	v_cndmask_b32_e64 v63, v63, -v63, s[8:9]
	v_cndmask_b32_e64 v62, v62, -v62, s[8:9]
	v_pk_fma_f32 v[62:63], v[66:67], v[128:129], v[62:63]
	v_pk_mul_f32 v[52:53], v[58:59], v[52:53]
	v_pk_mul_f32 v[66:67], v[62:63], v[118:119]
	v_cvt_f32_f16_sdwa v119, v61 dst_sel:DWORD dst_unused:UNUSED_PAD src0_sel:WORD_1
	v_fma_mixlo_f16 v50, v134, v66, 0
	v_cvt_f32_f16_e32 v118, v61
	v_cvt_f32_f16_sdwa v61, v65 dst_sel:DWORD dst_unused:UNUSED_PAD src0_sel:WORD_1
	ds_write_b16 v113, v50 offset:46512
	v_fma_mixlo_f16 v50, v135, v67, 0
	ds_write_b16 v113, v50 offset:46656
	v_mul_f32_e32 v50, 0x3fb8aa3b, v120
	v_exp_f32_e32 v62, v50
	v_mul_f32_e32 v50, 0x3fb8aa3b, v121
	v_exp_f32_e32 v63, v50
	v_pk_mul_f32 v[60:61], v[60:61], s[68:69] op_sel_hi:[1,0]
	v_pk_mul_f32 v[118:119], v[118:119], s[68:69] op_sel_hi:[1,0]
	v_pk_mul_f32 v[60:61], v[60:61], v[124:125]
	v_rcp_f32_e32 v64, v62
	v_cndmask_b32_e64 v61, v61, -v61, s[8:9]
	v_cndmask_b32_e64 v60, v60, -v60, s[8:9]
	v_pk_fma_f32 v[60:61], v[118:119], v[68:69], v[60:61]
	v_rcp_f32_e32 v65, v63
	v_pk_mul_f32 v[60:61], v[60:61], v[62:63]
	v_bfe_u32 v62, v131, 16, 1
	v_bfe_u32 v63, v130, 16, 1
	v_bfe_u32 v75, v53, 16, 1
	v_bfe_u32 v79, v52, 16, 1
	v_cvt_pk_f16_f32 v58, v52, v53
	v_bfe_u32 v50, v61, 16, 1
	v_add3_u32 v120, v130, v63, s34
	v_add3_u32 v62, v131, v62, s34
	v_add3_u32 v52, v52, v79, s34
	v_add3_u32 v53, v53, v75, s34
	v_cvt_pk_f16_f32 v59, v60, v61
	v_bfe_u32 v54, v60, 16, 1
	v_add3_u32 v50, v61, v50, s34
	v_perm_b32 v61, v62, v120, s82
	v_perm_b32 v62, v53, v52, s82
	v_cvt_f32_f16_sdwa v53, v55 dst_sel:DWORD dst_unused:UNUSED_PAD src0_sel:WORD_1
	v_cvt_f32_f16_e32 v52, v55
	v_add3_u32 v54, v60, v54, s34
	v_perm_b32 v63, v50, v54, s82
	v_cvt_f32_f16_sdwa v55, v51 dst_sel:DWORD dst_unused:UNUSED_PAD src0_sel:WORD_1
	v_cvt_f32_f16_e32 v54, v51
	v_pk_mul_f32 v[50:51], v[124:125], v[52:53]
	v_bfe_u32 v118, v139, 16, 1
	v_cndmask_b32_e64 v51, v51, -v51, s[8:9]
	v_cndmask_b32_e64 v50, v50, -v50, s[8:9]
	v_pk_fma_f32 v[50:51], v[68:69], v[54:55], v[50:51]
	v_bfe_u32 v119, v138, 16, 1
	v_pk_mul_f32 v[52:53], v[50:51], v[64:65]
	v_bfe_u32 v51, v48, 16, 1
	v_fma_mixlo_f16 v50, v136, v52, 0
	v_bfe_u32 v54, v53, 16, 1
	v_bfe_u32 v55, v52, 16, 1
	ds_write_b16 v113, v50 offset:46800
	v_bfe_u32 v50, v49, 16, 1
	v_bfe_u32 v64, v67, 16, 1
	v_bfe_u32 v65, v66, 16, 1
	v_bfe_u32 v68, v127, 16, 1
	v_bfe_u32 v69, v126, 16, 1
	v_add3_u32 v52, v52, v55, s34
	v_add3_u32 v54, v53, v54, s34
	v_add3_u32 v60, v138, v119, s34
	v_add3_u32 v118, v139, v118, s34
	v_add3_u32 v48, v48, v51, s34
	v_add3_u32 v49, v49, v50, s34
	v_add3_u32 v55, v126, v69, s34
	v_add3_u32 v68, v127, v68, s34
	v_add3_u32 v50, v66, v65, s34
	v_add3_u32 v64, v67, v64, s34
	v_perm_b32 v51, v54, v52, s82
	v_fma_mixlo_f16 v52, v137, v53, 0
	v_perm_b32 v60, v118, v60, s82
	v_perm_b32 v49, v49, v48, s82
	v_perm_b32 v50, v64, v50, s82
	v_perm_b32 v48, v68, v55, s82
	ds_write_b16 v113, v52 offset:46944
	ds_write_b128 v83, v[60:63] offset:18432
	ds_write_b128 v83, v[48:51] offset:27648
	ds_write_b128 v83, v[56:59] offset:36864
	v_add_u32_e32 v56, v73, v0
	s_nop 0
	s_barrier
	v_add_u32_e32 v253, v86, v95
	ds_read_b128 v[52:55], v253 offset:36864
	ds_read_b128 v[64:67], v56 offset:64
	ds_read_b128 v[178:181], v253 offset:36928
	ds_read_b128 v[60:63], v253 offset:39168
	ds_read_b128 v[118:121], v253 offset:39232
	ds_read_b128 v[122:125], v253 offset:41472
	ds_read_b128 v[126:129], v253 offset:41536
	ds_read_b128 v[130:133], v253 offset:43776
	ds_read_b128 v[134:137], v253 offset:43840
	ds_read_b128 v[48:51], v56
	v_add_u32_e32 v68, v86, v95
	s_waitcnt lgkmcnt(0)
	v_mfma_f32_16x16x32_f16 v[52:55], v[48:51], v[52:55], 0
	v_add_u32_e32 v75, v92, v0
	v_mov_b32_e32 v68, 0
	v_mov_b32_e32 v69, 0
	s_nop 0
	v_mfma_f32_16x16x32_f16 v[60:63], v[48:51], v[60:63], 0
	s_nop 0
	v_mfma_f32_16x16x32_f16 v[122:125], v[48:51], v[122:125], 0
	s_nop 0
	v_mfma_f32_16x16x32_f16 v[48:51], v[48:51], v[130:133], 0
	v_mfma_f32_16x16x32_f16 v[52:55], v[64:67], v[178:181], v[52:55]
	v_mfma_f32_16x16x32_f16 v[56:59], v[64:67], v[118:121], v[60:63]
	v_mfma_f32_16x16x32_f16 v[60:63], v[64:67], v[126:129], v[122:125]
	s_nop 0
	v_mfma_f32_16x16x32_f16 v[48:51], v[64:67], v[134:137], v[48:51]
	v_mov_b32_e32 v64, 0
	v_mov_b32_e32 v66, 0
	v_mov_b32_e32 v67, 0
	s_and_saveexec_b64 s[0:1], s[10:11]
	s_cbranch_execz .LBB0_436
	v_add_u32_e32 v253, v86, v98
	ds_read_b128 v[66:69], v75 offset:18432
	ds_read_b128 v[118:121], v253 offset:27648
	v_add_u32_e32 v65, v86, v98
	s_nop 0
	s_nop 0
	s_nop 0
	s_waitcnt lgkmcnt(0)
	v_mfma_f32_16x16x32_bf16 v[66:69], v[118:121], v[66:69], 0
	ds_read_b128 v[122:125], v65 offset:27712
	ds_read_b128 v[118:121], v75 offset:18496
	s_nop 0
	s_nop 0
	s_waitcnt lgkmcnt(0)
	v_mfma_f32_16x16x32_bf16 v[66:69], v[122:125], v[118:121], v[66:69]

.LBB0_455:
	s_andn2_b64 vcc, exec, s[24:25]
	s_mov_b64 s[26:27], -1
	s_cbranch_vccnz .LBB0_463
	s_and_b32 s26, s76, 1
	v_lshl_add_u32 v0, s26, 13, v227
	ds_read2_b64 v[36:39], v0 offset1:32
	v_mad_u32_u24 v2, s26, v165, v228
	s_waitcnt lgkmcnt(0)
	v_pk_mul_f32 v[66:67], v[36:37], v[38:39]
	v_xor_b32_e32 v90, 16, v0
	ds_read2_b64 v[38:41], v90 offset0:64 offset1:96
	s_waitcnt lgkmcnt(0)
	v_pk_mul_f32 v[64:65], v[66:67], v[38:39]
	s_nop 0
	v_pk_mul_f32 v[60:61], v[64:65], v[40:41]
	v_xor_b32_e32 v91, 32, v0
	ds_read2_b64 v[38:41], v91 offset0:128 offset1:160
	s_waitcnt lgkmcnt(0)
	v_pk_mul_f32 v[54:55], v[60:61], v[38:39]
	s_nop 0
	v_pk_mul_f32 v[48:49], v[54:55], v[40:41]
	v_xor_b32_e32 v92, 48, v0
	ds_read2_b64 v[38:41], v92 offset0:192 offset1:224
	v_add_u32_e32 v0, 0x800, v0
	v_xor_b32_e32 v91, 32, v0
	ds_read2_b64 v[68:71], v91 offset0:128 offset1:160
	s_waitcnt lgkmcnt(1)
	v_pk_mul_f32 v[44:45], v[48:49], v[38:39]
	s_nop 0
	v_pk_mul_f32 v[38:39], v[44:45], v[40:41]
	ds_read2_b64 v[40:43], v0 offset1:32
	s_waitcnt lgkmcnt(0)
	v_pk_mul_f32 v[58:59], v[38:39], v[40:41]
	s_nop 0
	v_pk_mul_f32 v[50:51], v[58:59], v[42:43]
	v_xor_b32_e32 v90, 16, v0
	ds_read2_b64 v[40:43], v90 offset0:64 offset1:96
	s_waitcnt lgkmcnt(0)
	v_pk_mul_f32 v[46:47], v[50:51], v[40:41]
	s_nop 0
	v_pk_mul_f32 v[42:43], v[46:47], v[42:43]
	v_rcp_f32_e32 v40, v38
	v_pk_mul_f32 v[62:63], v[42:43], v[68:69]
	v_rcp_f32_e32 v41, v39
	v_pk_mul_f32 v[56:57], v[62:63], v[70:71]
	v_xor_b32_e32 v92, 48, v0
	ds_read2_b64 v[68:71], v92 offset0:192 offset1:224
	s_waitcnt lgkmcnt(0)
	v_pk_mul_f32 v[52:53], v[56:57], v[68:69]
	s_nop 0
	v_pk_mul_f32 v[0:1], v[52:53], v[70:71]
	s_and_saveexec_b64 s[26:27], s[4:5]
	s_cbranch_execz .LBB0_458
	v_lshl_add_u32 v253, v173, 1, v2
	v_lshl_add_u32 v252, v180, 1, v2
	ds_read2st64_b32 v[72:73], v253 offset0:96 offset1:112
	ds_read2st64_b32 v[68:69], v253 offset0:64 offset1:80
	ds_read_b32 v84, v253 offset:32768
	ds_read2st64_b32 v[232:233], v252 offset0:64 offset1:80
	ds_read2st64_b32 v[234:235], v252 offset0:96 offset1:112
	v_lshl_add_u32 v74, v173, 1, v2
	s_nop 0
	s_nop 0
	v_rcp_f32_e32 v70, v36
	v_rcp_f32_e32 v71, v37
	s_waitcnt lgkmcnt(4)
	v_cvt_f32_f16_e32 v78, v73
	v_cvt_f32_f16_sdwa v79, v73 dst_sel:DWORD dst_unused:UNUSED_PAD src0_sel:WORD_1
	s_waitcnt lgkmcnt(3)
	v_cvt_f32_f16_e32 v74, v68
	v_cvt_f32_f16_sdwa v75, v68 dst_sel:DWORD dst_unused:UNUSED_PAD src0_sel:WORD_1
	v_cvt_f32_f16_e32 v76, v72
	v_cvt_f32_f16_sdwa v77, v72 dst_sel:DWORD dst_unused:UNUSED_PAD src0_sel:WORD_1
	v_cvt_f32_f16_e32 v72, v69
	v_cvt_f32_f16_sdwa v73, v69 dst_sel:DWORD dst_unused:UNUSED_PAD src0_sel:WORD_1
	v_pk_mul_f32 v[78:79], v[36:37], v[78:79]
	v_pk_mul_f32 v[76:77], v[70:71], v[76:77]
	v_pk_mul_f32 v[70:71], v[70:71], v[74:75]
	v_pk_mul_f32 v[72:73], v[40:41], v[72:73]
	v_pk_mul_f32 v[74:75], v[40:41], v[78:79]
	v_cvt_pk_f16_f32 v68, v78, v79
	v_pk_mul_f32 v[80:81], v[38:39], v[76:77]
	v_pk_mul_f32 v[82:83], v[38:39], v[70:71]
	ds_write2st64_b32 v179, v69, v68 offset1:18
	v_cvt_pk_f16_f32 v68, v72, v73
	v_cvt_pk_f16_f32 v69, v74, v75
	v_pk_mul_f32 v[76:77], v[0:1], v[76:77]
	ds_write2st64_b32 v179, v68, v69 offset0:36 offset1:54
	v_cvt_pk_f16_f32 v68, v80, v81
	v_cvt_pk_f16_f32 v69, v82, v83
	v_lshl_add_u32 v253, v182, 1, v2
	ds_read_b32 v82, v252 offset:32768
	ds_read2st64_b32 v[236:237], v253 offset0:64 offset1:80
	ds_read2st64_b32 v[240:241], v253 offset0:96 offset1:112
	ds_write2st64_b32 v179, v68, v69 offset0:72 offset1:90
	v_cvt_f16_f32_e32 v68, v76
	v_pk_mul_f32 v[70:71], v[0:1], v[70:71]
	v_cvt_f16_f32_e32 v69, v77
	v_cvt_f16_f32_e32 v70, v70
	v_cvt_f16_f32_e32 v71, v71
	ds_write_b16 v174, v68
	ds_write_b16 v174, v69 offset:40
	ds_write_b16 v174, v70 offset:5120
	ds_write_b16 v174, v71 offset:5160
	s_waitcnt lgkmcnt(12)
	ds_write_b16 v174, v84 offset:10240
	v_lshl_add_u32 v74, v180, 1, v2
	v_rcp_f32_e32 v70, v66
	v_rcp_f32_e32 v71, v67
	s_waitcnt lgkmcnt(12)
	v_cvt_f32_f16_e32 v76, v233
	v_cvt_f32_f16_sdwa v77, v233 dst_sel:DWORD dst_unused:UNUSED_PAD src0_sel:WORD_1
	s_waitcnt lgkmcnt(11)
	v_cvt_f32_f16_e32 v80, v235
	v_cvt_f32_f16_sdwa v81, v235 dst_sel:DWORD dst_unused:UNUSED_PAD src0_sel:WORD_1
	v_cvt_f32_f16_e32 v74, v232
	v_cvt_f32_f16_e32 v78, v234
	v_cvt_f32_f16_sdwa v79, v234 dst_sel:DWORD dst_unused:UNUSED_PAD src0_sel:WORD_1
	v_cvt_f32_f16_sdwa v75, v232 dst_sel:DWORD dst_unused:UNUSED_PAD src0_sel:WORD_1
	v_pk_mul_f32 v[36:37], v[36:37], v[76:77]
	v_pk_mul_f32 v[68:69], v[66:67], v[80:81]
	v_pk_mul_f32 v[72:73], v[70:71], v[78:79]
	v_pk_mul_f32 v[70:71], v[70:71], v[74:75]
	v_pk_mul_f32 v[74:75], v[40:41], v[36:37]
	v_pk_mul_f32 v[76:77], v[40:41], v[68:69]
	v_cvt_pk_f16_f32 v36, v36, v37
	v_cvt_pk_f16_f32 v37, v68, v69
	v_pk_mul_f32 v[78:79], v[38:39], v[72:73]
	v_pk_mul_f32 v[80:81], v[38:39], v[70:71]
	ds_write2st64_b32 v181, v36, v37 offset1:18
	v_cvt_pk_f16_f32 v36, v74, v75
	v_cvt_pk_f16_f32 v37, v76, v77
	v_pk_mul_f32 v[72:73], v[0:1], v[72:73]
	ds_write2st64_b32 v181, v36, v37 offset0:36 offset1:54
	v_cvt_pk_f16_f32 v36, v78, v79
	v_cvt_pk_f16_f32 v37, v80, v81
	v_lshl_add_u32 v252, v184, 1, v2
	ds_read_b32 v80, v253 offset:32768
	ds_read2st64_b32 v[242:243], v252 offset0:64 offset1:80
	s_waitcnt lgkmcnt(14)
	ds_read2st64_b32 v[234:235], v252 offset0:96 offset1:112
	s_waitcnt lgkmcnt(14)
	ds_write2st64_b32 v181, v36, v37 offset0:72 offset1:90
	v_cvt_f16_f32_e32 v36, v72
	v_pk_mul_f32 v[70:71], v[0:1], v[70:71]
	v_cvt_f16_f32_e32 v37, v73
	v_cvt_f16_f32_e32 v68, v70
	v_cvt_f16_f32_e32 v69, v71
	s_waitcnt lgkmcnt(14)
	ds_write_b16 v174, v36 offset:2
	s_waitcnt lgkmcnt(14)
	ds_write_b16 v174, v37 offset:42
	s_waitcnt lgkmcnt(14)
	ds_write_b16 v174, v68 offset:5122
	s_waitcnt lgkmcnt(14)
	ds_write_b16 v174, v69 offset:5162
	s_waitcnt lgkmcnt(14)
	ds_write_b16 v174, v82 offset:10242
	v_lshl_add_u32 v72, v182, 1, v2
	v_rcp_f32_e32 v68, v64
	v_rcp_f32_e32 v69, v65
	v_cvt_f32_f16_e32 v74, v237
	v_cvt_f32_f16_sdwa v75, v237 dst_sel:DWORD dst_unused:UNUSED_PAD src0_sel:WORD_1
	v_cvt_f32_f16_e32 v78, v241
	v_cvt_f32_f16_sdwa v79, v241 dst_sel:DWORD dst_unused:UNUSED_PAD src0_sel:WORD_1
	v_cvt_f32_f16_e32 v72, v236
	v_cvt_f32_f16_e32 v76, v240
	v_cvt_f32_f16_sdwa v77, v240 dst_sel:DWORD dst_unused:UNUSED_PAD src0_sel:WORD_1
	v_cvt_f32_f16_sdwa v73, v236 dst_sel:DWORD dst_unused:UNUSED_PAD src0_sel:WORD_1
	v_pk_mul_f32 v[36:37], v[66:67], v[74:75]
	v_pk_mul_f32 v[66:67], v[64:65], v[78:79]
	v_pk_mul_f32 v[70:71], v[68:69], v[76:77]
	v_pk_mul_f32 v[68:69], v[68:69], v[72:73]
	v_pk_mul_f32 v[72:73], v[40:41], v[36:37]
	v_pk_mul_f32 v[74:75], v[40:41], v[66:67]
	v_cvt_pk_f16_f32 v36, v36, v37
	v_cvt_pk_f16_f32 v37, v66, v67
	v_pk_mul_f32 v[76:77], v[38:39], v[70:71]
	v_pk_mul_f32 v[78:79], v[38:39], v[68:69]
	s_waitcnt lgkmcnt(14)
	ds_write2st64_b32 v183, v36, v37 offset1:18
	v_cvt_pk_f16_f32 v36, v72, v73
	v_cvt_pk_f16_f32 v37, v74, v75
	v_pk_mul_f32 v[70:71], v[0:1], v[70:71]
	s_waitcnt lgkmcnt(14)
	ds_write2st64_b32 v183, v36, v37 offset0:36 offset1:54
	v_cvt_pk_f16_f32 v36, v76, v77
	v_cvt_pk_f16_f32 v37, v78, v79
	s_waitcnt lgkmcnt(14)
	ds_read_b32 v78, v252 offset:32768
	s_waitcnt lgkmcnt(14)
	ds_write2st64_b32 v183, v36, v37 offset0:72 offset1:90
	v_cvt_f16_f32_e32 v36, v70
	v_pk_mul_f32 v[68:69], v[0:1], v[68:69]
	v_cvt_f16_f32_e32 v37, v71
	v_cvt_f16_f32_e32 v66, v68
	v_cvt_f16_f32_e32 v67, v69
	s_waitcnt lgkmcnt(14)
	ds_write_b16 v174, v36 offset:4
	s_waitcnt lgkmcnt(14)
	ds_write_b16 v174, v37 offset:44
	s_waitcnt lgkmcnt(14)
	ds_write_b16 v174, v66 offset:5124
	s_waitcnt lgkmcnt(14)
	ds_write_b16 v174, v67 offset:5164
	s_waitcnt lgkmcnt(14)
	ds_write_b16 v174, v80 offset:10244
	v_lshl_add_u32 v70, v184, 1, v2
	v_rcp_f32_e32 v66, v60
	v_rcp_f32_e32 v67, v61
	v_cvt_f32_f16_e32 v72, v243
	v_cvt_f32_f16_sdwa v73, v243 dst_sel:DWORD dst_unused:UNUSED_PAD src0_sel:WORD_1
	v_cvt_f32_f16_e32 v76, v235
	v_cvt_f32_f16_sdwa v77, v235 dst_sel:DWORD dst_unused:UNUSED_PAD src0_sel:WORD_1
	v_cvt_f32_f16_e32 v70, v242
	v_cvt_f32_f16_e32 v74, v234
	v_cvt_f32_f16_sdwa v75, v234 dst_sel:DWORD dst_unused:UNUSED_PAD src0_sel:WORD_1
	v_cvt_f32_f16_sdwa v71, v242 dst_sel:DWORD dst_unused:UNUSED_PAD src0_sel:WORD_1
	v_pk_mul_f32 v[36:37], v[64:65], v[72:73]
	v_pk_mul_f32 v[64:65], v[60:61], v[76:77]
	v_pk_mul_f32 v[68:69], v[66:67], v[74:75]
	v_pk_mul_f32 v[66:67], v[66:67], v[70:71]
	v_pk_mul_f32 v[70:71], v[40:41], v[36:37]
	v_pk_mul_f32 v[72:73], v[40:41], v[64:65]
	v_cvt_pk_f16_f32 v36, v36, v37
	v_cvt_pk_f16_f32 v37, v64, v65
	v_pk_mul_f32 v[74:75], v[38:39], v[68:69]
	v_pk_mul_f32 v[76:77], v[38:39], v[66:67]
	s_waitcnt lgkmcnt(14)
	ds_write2st64_b32 v185, v36, v37 offset1:18
	v_cvt_pk_f16_f32 v36, v70, v71
	v_cvt_pk_f16_f32 v37, v72, v73
	v_pk_mul_f32 v[68:69], v[0:1], v[68:69]
	s_waitcnt lgkmcnt(14)
	ds_write2st64_b32 v185, v36, v37 offset0:36 offset1:54
	v_cvt_pk_f16_f32 v36, v74, v75
	v_cvt_pk_f16_f32 v37, v76, v77
	s_waitcnt lgkmcnt(14)
	ds_write2st64_b32 v185, v36, v37 offset0:72 offset1:90
	v_cvt_f16_f32_e32 v36, v68
	v_pk_mul_f32 v[66:67], v[0:1], v[66:67]
	v_cvt_f16_f32_e32 v37, v69
	v_cvt_f16_f32_e32 v64, v66
	v_cvt_f16_f32_e32 v65, v67
	s_waitcnt lgkmcnt(14)
	ds_write_b16 v174, v36 offset:6
	s_waitcnt lgkmcnt(14)
	ds_write_b16 v174, v37 offset:46
	s_waitcnt lgkmcnt(14)
	ds_write_b16 v174, v64 offset:5126
	s_waitcnt lgkmcnt(14)
	ds_write_b16 v174, v65 offset:5166
	s_nop 0
	s_waitcnt lgkmcnt(13)
	ds_write_b16 v174, v78 offset:10246
	v_perm_b32 v36, v82, v84, s82
	v_perm_b32 v37, v78, v80, s82
	ds_write_b64 v174, v[36:37] offset:10280

.LBB0_468:
	v_cmp_lt_i32_e32 vcc, 2, v172
	s_and_saveexec_b64 s[28:29], vcc
	s_xor_b64 s[28:29], exec, s[28:29]
	s_cbranch_execz .LBB0_470
	v_lshl_add_u32 v253, v202, 1, v2
	v_lshl_add_u32 v252, v204, 1, v2
	ds_read2st64_b32 v[36:37], v253 offset0:64 offset1:80
	ds_read2st64_b32 v[46:47], v253 offset0:96 offset1:112
	ds_read_b32 v60, v253 offset:32768
	ds_read2st64_b32 v[232:233], v252 offset0:64 offset1:80
	ds_read2st64_b32 v[234:235], v252 offset0:96 offset1:112
	ds_read_b32 v61, v252 offset:32768
	v_lshl_add_u32 v48, v202, 1, v2
	s_nop 0
	s_nop 0
	v_rcp_f32_e32 v44, v62
	v_rcp_f32_e32 v45, v63
	v_lshl_add_u32 v253, v206, 1, v2
	ds_read2st64_b32 v[236:237], v253 offset0:64 offset1:80
	s_waitcnt lgkmcnt(5)
	v_cvt_f32_f16_e32 v58, v47
	v_cvt_f32_f16_e32 v50, v37
	v_cvt_f32_f16_sdwa v51, v37 dst_sel:DWORD dst_unused:UNUSED_PAD src0_sel:WORD_1
	ds_read2st64_b32 v[240:241], v253 offset0:96 offset1:112
	v_cvt_f32_f16_sdwa v59, v47 dst_sel:DWORD dst_unused:UNUSED_PAD src0_sel:WORD_1
	v_cvt_f32_f16_e32 v48, v36
	v_cvt_f32_f16_e32 v54, v46
	v_cvt_f32_f16_sdwa v55, v46 dst_sel:DWORD dst_unused:UNUSED_PAD src0_sel:WORD_1
	v_cvt_f32_f16_sdwa v49, v36 dst_sel:DWORD dst_unused:UNUSED_PAD src0_sel:WORD_1
	v_pk_mul_f32 v[36:37], v[42:43], v[50:51]
	v_pk_mul_f32 v[42:43], v[62:63], v[58:59]
	v_pk_mul_f32 v[46:47], v[44:45], v[54:55]
	v_pk_mul_f32 v[44:45], v[44:45], v[48:49]
	v_pk_mul_f32 v[48:49], v[40:41], v[36:37]
	v_pk_mul_f32 v[50:51], v[40:41], v[42:43]
	v_cvt_pk_f16_f32 v36, v36, v37
	v_cvt_pk_f16_f32 v37, v42, v43
	v_pk_mul_f32 v[54:55], v[38:39], v[46:47]
	v_pk_mul_f32 v[58:59], v[38:39], v[44:45]
	ds_write2st64_b32 v203, v36, v37 offset1:18
	v_cvt_pk_f16_f32 v36, v48, v49
	v_cvt_pk_f16_f32 v37, v50, v51
	v_pk_mul_f32 v[46:47], v[0:1], v[46:47]
	ds_write2st64_b32 v203, v36, v37 offset0:36 offset1:54
	v_cvt_pk_f16_f32 v36, v54, v55
	v_cvt_pk_f16_f32 v37, v58, v59
	ds_write2st64_b32 v203, v36, v37 offset0:72 offset1:90
	v_cvt_f16_f32_e32 v36, v46
	v_pk_mul_f32 v[44:45], v[0:1], v[44:45]
	v_cvt_f16_f32_e32 v37, v47
	v_cvt_f16_f32_e32 v42, v44
	v_cvt_f16_f32_e32 v43, v45
	ds_write_b16 v174, v36 offset:24
	ds_write_b16 v174, v37 offset:64
	ds_write_b16 v174, v42 offset:5144
	ds_write_b16 v174, v43 offset:5184
	s_waitcnt lgkmcnt(12)
	ds_write_b16 v174, v60 offset:10264
	v_lshl_add_u32 v46, v204, 1, v2
	v_rcp_f32_e32 v42, v56
	v_rcp_f32_e32 v43, v57
	s_waitcnt lgkmcnt(12)
	v_cvt_f32_f16_e32 v48, v233
	v_cvt_f32_f16_sdwa v49, v233 dst_sel:DWORD dst_unused:UNUSED_PAD src0_sel:WORD_1
	s_waitcnt lgkmcnt(11)
	v_cvt_f32_f16_e32 v54, v235
	v_cvt_f32_f16_sdwa v55, v235 dst_sel:DWORD dst_unused:UNUSED_PAD src0_sel:WORD_1
	v_cvt_f32_f16_e32 v46, v232
	v_cvt_f32_f16_e32 v50, v234
	v_cvt_f32_f16_sdwa v51, v234 dst_sel:DWORD dst_unused:UNUSED_PAD src0_sel:WORD_1
	v_cvt_f32_f16_sdwa v47, v232 dst_sel:DWORD dst_unused:UNUSED_PAD src0_sel:WORD_1
	v_pk_mul_f32 v[36:37], v[62:63], v[48:49]
	v_pk_mul_f32 v[44:45], v[56:57], v[54:55]
	v_pk_mul_f32 v[48:49], v[42:43], v[50:51]
	v_pk_mul_f32 v[42:43], v[42:43], v[46:47]
	v_pk_mul_f32 v[46:47], v[40:41], v[36:37]
	v_pk_mul_f32 v[50:51], v[40:41], v[44:45]
	v_cvt_pk_f16_f32 v36, v36, v37
	v_cvt_pk_f16_f32 v37, v44, v45
	v_pk_mul_f32 v[54:55], v[38:39], v[48:49]
	v_pk_mul_f32 v[58:59], v[38:39], v[42:43]
	ds_write2st64_b32 v205, v36, v37 offset1:18
	v_cvt_pk_f16_f32 v36, v46, v47
	v_cvt_pk_f16_f32 v37, v50, v51
	v_pk_mul_f32 v[48:49], v[0:1], v[48:49]
	ds_write2st64_b32 v205, v36, v37 offset0:36 offset1:54
	v_cvt_pk_f16_f32 v36, v54, v55
	v_cvt_pk_f16_f32 v37, v58, v59
	v_lshl_add_u32 v252, v208, 1, v2
	ds_read_b32 v58, v253 offset:32768
	ds_read2st64_b32 v[242:243], v252 offset0:64 offset1:80
	s_waitcnt lgkmcnt(14)
	ds_read2st64_b32 v[234:235], v252 offset0:96 offset1:112
	s_waitcnt lgkmcnt(14)
	ds_write2st64_b32 v205, v36, v37 offset0:72 offset1:90
	v_cvt_f16_f32_e32 v36, v48
	v_pk_mul_f32 v[42:43], v[0:1], v[42:43]
	v_cvt_f16_f32_e32 v37, v49
	v_cvt_f16_f32_e32 v42, v42
	v_cvt_f16_f32_e32 v43, v43
	s_waitcnt lgkmcnt(14)
	ds_write_b16 v174, v36 offset:26
	s_waitcnt lgkmcnt(14)
	ds_write_b16 v174, v37 offset:66
	s_waitcnt lgkmcnt(14)
	ds_write_b16 v174, v42 offset:5146
	s_waitcnt lgkmcnt(14)
	ds_write_b16 v174, v43 offset:5186
	s_waitcnt lgkmcnt(14)
	ds_write_b16 v174, v61 offset:10266
	v_lshl_add_u32 v46, v206, 1, v2
	v_rcp_f32_e32 v42, v52
	v_rcp_f32_e32 v43, v53
	v_lshl_add_u32 v2, v208, 1, v2
	v_cvt_f32_f16_e32 v48, v237
	v_cvt_f32_f16_sdwa v49, v237 dst_sel:DWORD dst_unused:UNUSED_PAD src0_sel:WORD_1
	v_cvt_f32_f16_e32 v54, v241
	v_cvt_f32_f16_sdwa v55, v241 dst_sel:DWORD dst_unused:UNUSED_PAD src0_sel:WORD_1
	v_cvt_f32_f16_e32 v46, v236
	v_cvt_f32_f16_e32 v50, v240
	v_cvt_f32_f16_sdwa v51, v240 dst_sel:DWORD dst_unused:UNUSED_PAD src0_sel:WORD_1
	v_cvt_f32_f16_sdwa v47, v236 dst_sel:DWORD dst_unused:UNUSED_PAD src0_sel:WORD_1
	v_pk_mul_f32 v[36:37], v[56:57], v[48:49]
	v_pk_mul_f32 v[44:45], v[52:53], v[54:55]
	v_pk_mul_f32 v[48:49], v[42:43], v[50:51]
	v_pk_mul_f32 v[42:43], v[42:43], v[46:47]
	v_pk_mul_f32 v[46:47], v[40:41], v[36:37]
	v_pk_mul_f32 v[50:51], v[40:41], v[44:45]
	v_cvt_pk_f16_f32 v36, v36, v37
	v_cvt_pk_f16_f32 v37, v44, v45
	v_pk_mul_f32 v[54:55], v[38:39], v[48:49]
	v_pk_mul_f32 v[56:57], v[38:39], v[42:43]
	s_waitcnt lgkmcnt(14)
	ds_write2st64_b32 v207, v36, v37 offset1:18
	v_cvt_pk_f16_f32 v36, v46, v47
	v_cvt_pk_f16_f32 v37, v50, v51
	v_pk_mul_f32 v[48:49], v[0:1], v[48:49]
	s_waitcnt lgkmcnt(14)
	ds_write2st64_b32 v207, v36, v37 offset0:36 offset1:54
	v_cvt_pk_f16_f32 v36, v54, v55
	v_cvt_pk_f16_f32 v37, v56, v57
	s_waitcnt lgkmcnt(14)
	ds_write2st64_b32 v207, v36, v37 offset0:72 offset1:90
	v_cvt_f16_f32_e32 v36, v48
	v_pk_mul_f32 v[42:43], v[0:1], v[42:43]
	v_cvt_f16_f32_e32 v37, v49
	v_cvt_f16_f32_e32 v42, v42
	v_cvt_f16_f32_e32 v43, v43
	s_waitcnt lgkmcnt(14)
	ds_write_b16 v174, v36 offset:28
	s_waitcnt lgkmcnt(14)
	ds_write_b16 v174, v37 offset:68
	s_waitcnt lgkmcnt(14)
	ds_write_b16 v174, v42 offset:5148
	s_waitcnt lgkmcnt(14)
	ds_write_b16 v174, v43 offset:5188
	s_waitcnt lgkmcnt(14)
	ds_write_b16 v174, v58 offset:10268
	s_waitcnt lgkmcnt(14)
	ds_read_b32 v2, v252 offset:32768
	v_rcp_f32_e32 v42, v0
	v_rcp_f32_e32 v43, v1
	v_cvt_f32_f16_e32 v48, v243
	v_cvt_f32_f16_sdwa v49, v243 dst_sel:DWORD dst_unused:UNUSED_PAD src0_sel:WORD_1
	v_cvt_f32_f16_e32 v54, v235
	v_cvt_f32_f16_sdwa v55, v235 dst_sel:DWORD dst_unused:UNUSED_PAD src0_sel:WORD_1
	v_cvt_f32_f16_e32 v46, v242
	v_cvt_f32_f16_e32 v50, v234
	v_cvt_f32_f16_sdwa v51, v234 dst_sel:DWORD dst_unused:UNUSED_PAD src0_sel:WORD_1
	v_cvt_f32_f16_sdwa v47, v242 dst_sel:DWORD dst_unused:UNUSED_PAD src0_sel:WORD_1
	v_pk_mul_f32 v[36:37], v[52:53], v[48:49]
	v_pk_mul_f32 v[44:45], v[0:1], v[54:55]
	v_pk_mul_f32 v[48:49], v[42:43], v[50:51]
	v_pk_mul_f32 v[42:43], v[42:43], v[46:47]
	v_pk_mul_f32 v[46:47], v[40:41], v[36:37]
	v_pk_mul_f32 v[40:41], v[40:41], v[44:45]
	v_cvt_pk_f16_f32 v36, v36, v37
	v_cvt_pk_f16_f32 v37, v44, v45
	v_pk_mul_f32 v[50:51], v[38:39], v[48:49]
	v_pk_mul_f32 v[38:39], v[38:39], v[42:43]
	s_waitcnt lgkmcnt(14)
	ds_write2st64_b32 v209, v36, v37 offset1:18
	v_cvt_pk_f16_f32 v36, v46, v47
	v_cvt_pk_f16_f32 v37, v40, v41
	v_pk_mul_f32 v[48:49], v[0:1], v[48:49]
	s_waitcnt lgkmcnt(14)
	ds_write2st64_b32 v209, v36, v37 offset0:36 offset1:54
	v_cvt_pk_f16_f32 v36, v50, v51
	v_cvt_pk_f16_f32 v37, v38, v39
	s_waitcnt lgkmcnt(14)
	ds_write2st64_b32 v209, v36, v37 offset0:72 offset1:90
	v_cvt_f16_f32_e32 v36, v48
	v_pk_mul_f32 v[42:43], v[0:1], v[42:43]
	v_cvt_f16_f32_e32 v37, v49
	v_cvt_f16_f32_e32 v38, v42
	v_cvt_f16_f32_e32 v39, v43
	s_waitcnt lgkmcnt(14)
	ds_write_b16 v174, v36 offset:30
	s_waitcnt lgkmcnt(14)
	ds_write_b16 v174, v37 offset:70
	s_waitcnt lgkmcnt(14)
	ds_write_b16 v174, v38 offset:5150
	s_waitcnt lgkmcnt(14)
	ds_write_b16 v174, v39 offset:5190
	s_nop 0
	s_waitcnt lgkmcnt(7)
	ds_write_b16 v174, v2 offset:10270
	v_perm_b32 v36, v61, v60, s82
	v_perm_b32 v37, v2, v58, s82
	ds_write_b64 v174, v[36:37] offset:10304
.LBB0_470:
	s_andn2_saveexec_b64 s[28:29], s[28:29]
	s_cbranch_execz .LBB0_472
	v_lshl_add_u32 v253, v194, 1, v2
	v_lshl_add_u32 v252, v196, 1, v2
	ds_read2st64_b32 v[36:37], v253 offset0:64 offset1:80
	ds_read2st64_b32 v[48:49], v253 offset0:96 offset1:112
	ds_read_b32 v64, v253 offset:32768
	ds_read2st64_b32 v[232:233], v252 offset0:64 offset1:80
	ds_read2st64_b32 v[234:235], v252 offset0:96 offset1:112
	v_lshl_add_u32 v52, v194, 1, v2
	s_nop 0
	s_nop 0
	s_nop 0
	v_rcp_f32_e32 v44, v58
	v_rcp_f32_e32 v45, v59
	s_waitcnt lgkmcnt(3)
	v_cvt_f32_f16_e32 v60, v49
	v_cvt_f32_f16_e32 v54, v37
	v_cvt_f32_f16_sdwa v55, v37 dst_sel:DWORD dst_unused:UNUSED_PAD src0_sel:WORD_1
	v_cvt_f32_f16_sdwa v61, v49 dst_sel:DWORD dst_unused:UNUSED_PAD src0_sel:WORD_1
	v_cvt_f32_f16_e32 v52, v36
	v_cvt_f32_f16_e32 v56, v48
	v_cvt_f32_f16_sdwa v57, v48 dst_sel:DWORD dst_unused:UNUSED_PAD src0_sel:WORD_1
	v_cvt_f32_f16_sdwa v53, v36 dst_sel:DWORD dst_unused:UNUSED_PAD src0_sel:WORD_1
	v_pk_mul_f32 v[36:37], v[38:39], v[54:55]
	v_pk_mul_f32 v[48:49], v[58:59], v[60:61]
	v_pk_mul_f32 v[54:55], v[44:45], v[56:57]
	v_pk_mul_f32 v[44:45], v[44:45], v[52:53]
	v_pk_mul_f32 v[52:53], v[40:41], v[36:37]
	v_pk_mul_f32 v[56:57], v[40:41], v[48:49]
	v_cvt_pk_f16_f32 v36, v36, v37
	v_cvt_pk_f16_f32 v37, v48, v49
	v_pk_mul_f32 v[60:61], v[38:39], v[54:55]
	v_pk_mul_f32 v[62:63], v[38:39], v[44:45]
	ds_write2st64_b32 v195, v36, v37 offset1:18
	v_cvt_pk_f16_f32 v36, v52, v53
	v_cvt_pk_f16_f32 v37, v56, v57
	v_pk_mul_f32 v[54:55], v[0:1], v[54:55]
	ds_write2st64_b32 v195, v36, v37 offset0:36 offset1:54
	v_cvt_pk_f16_f32 v36, v60, v61
	v_cvt_pk_f16_f32 v37, v62, v63
	v_lshl_add_u32 v253, v198, 1, v2
	ds_read_b32 v62, v252 offset:32768
	ds_read2st64_b32 v[236:237], v253 offset0:64 offset1:80
	ds_read2st64_b32 v[240:241], v253 offset0:96 offset1:112
	ds_write2st64_b32 v195, v36, v37 offset0:72 offset1:90
	v_cvt_f16_f32_e32 v36, v54
	v_pk_mul_f32 v[44:45], v[0:1], v[44:45]
	v_cvt_f16_f32_e32 v37, v55
	v_cvt_f16_f32_e32 v44, v44
	v_cvt_f16_f32_e32 v45, v45
	ds_write_b16 v174, v36 offset:16
	ds_write_b16 v174, v37 offset:56
	ds_write_b16 v174, v44 offset:5136
	ds_write_b16 v174, v45 offset:5176
	s_waitcnt lgkmcnt(12)
	ds_write_b16 v174, v64 offset:10256
	v_lshl_add_u32 v52, v196, 1, v2
	v_rcp_f32_e32 v44, v50
	v_rcp_f32_e32 v45, v51
	s_waitcnt lgkmcnt(12)
	v_cvt_f32_f16_e32 v54, v233
	v_cvt_f32_f16_sdwa v55, v233 dst_sel:DWORD dst_unused:UNUSED_PAD src0_sel:WORD_1
	s_waitcnt lgkmcnt(11)
	v_cvt_f32_f16_e32 v60, v235
	v_cvt_f32_f16_sdwa v61, v235 dst_sel:DWORD dst_unused:UNUSED_PAD src0_sel:WORD_1
	v_cvt_f32_f16_e32 v52, v232
	v_cvt_f32_f16_e32 v56, v234
	v_cvt_f32_f16_sdwa v57, v234 dst_sel:DWORD dst_unused:UNUSED_PAD src0_sel:WORD_1
	v_cvt_f32_f16_sdwa v53, v232 dst_sel:DWORD dst_unused:UNUSED_PAD src0_sel:WORD_1
	v_pk_mul_f32 v[36:37], v[58:59], v[54:55]
	v_pk_mul_f32 v[48:49], v[50:51], v[60:61]
	v_pk_mul_f32 v[54:55], v[44:45], v[56:57]
	v_pk_mul_f32 v[44:45], v[44:45], v[52:53]
	v_pk_mul_f32 v[52:53], v[40:41], v[36:37]
	v_pk_mul_f32 v[56:57], v[40:41], v[48:49]
	v_cvt_pk_f16_f32 v36, v36, v37
	v_cvt_pk_f16_f32 v37, v48, v49
	v_pk_mul_f32 v[58:59], v[38:39], v[54:55]
	v_pk_mul_f32 v[60:61], v[38:39], v[44:45]
	ds_write2st64_b32 v197, v36, v37 offset1:18
	v_cvt_pk_f16_f32 v36, v52, v53
	v_cvt_pk_f16_f32 v37, v56, v57
	v_pk_mul_f32 v[54:55], v[0:1], v[54:55]
	ds_write2st64_b32 v197, v36, v37 offset0:36 offset1:54
	v_cvt_pk_f16_f32 v36, v58, v59
	v_cvt_pk_f16_f32 v37, v60, v61
	v_lshl_add_u32 v252, v200, 1, v2
	ds_read_b32 v60, v253 offset:32768
	ds_read2st64_b32 v[242:243], v252 offset0:64 offset1:80
	s_waitcnt lgkmcnt(14)
	ds_read2st64_b32 v[234:235], v252 offset0:96 offset1:112
	s_waitcnt lgkmcnt(14)
	ds_write2st64_b32 v197, v36, v37 offset0:72 offset1:90
	v_cvt_f16_f32_e32 v36, v54
	v_pk_mul_f32 v[44:45], v[0:1], v[44:45]
	v_cvt_f16_f32_e32 v37, v55
	v_cvt_f16_f32_e32 v44, v44
	v_cvt_f16_f32_e32 v45, v45
	s_waitcnt lgkmcnt(14)
	ds_write_b16 v174, v36 offset:18
	s_waitcnt lgkmcnt(14)
	ds_write_b16 v174, v37 offset:58
	s_waitcnt lgkmcnt(14)
	ds_write_b16 v174, v44 offset:5138
	s_waitcnt lgkmcnt(14)
	ds_write_b16 v174, v45 offset:5178
	s_waitcnt lgkmcnt(14)
	ds_write_b16 v174, v62 offset:10258
	v_lshl_add_u32 v52, v198, 1, v2
	v_rcp_f32_e32 v44, v46
	v_rcp_f32_e32 v45, v47
	v_lshl_add_u32 v2, v200, 1, v2
	v_cvt_f32_f16_e32 v54, v237
	v_cvt_f32_f16_sdwa v55, v237 dst_sel:DWORD dst_unused:UNUSED_PAD src0_sel:WORD_1
	v_cvt_f32_f16_e32 v58, v241
	v_cvt_f32_f16_sdwa v59, v241 dst_sel:DWORD dst_unused:UNUSED_PAD src0_sel:WORD_1
	v_cvt_f32_f16_e32 v52, v236
	v_cvt_f32_f16_e32 v56, v240
	v_cvt_f32_f16_sdwa v57, v240 dst_sel:DWORD dst_unused:UNUSED_PAD src0_sel:WORD_1
	v_cvt_f32_f16_sdwa v53, v236 dst_sel:DWORD dst_unused:UNUSED_PAD src0_sel:WORD_1
	v_pk_mul_f32 v[36:37], v[50:51], v[54:55]
	v_pk_mul_f32 v[48:49], v[46:47], v[58:59]
	v_pk_mul_f32 v[50:51], v[44:45], v[56:57]
	v_pk_mul_f32 v[44:45], v[44:45], v[52:53]
	v_pk_mul_f32 v[52:53], v[40:41], v[36:37]
	v_pk_mul_f32 v[54:55], v[40:41], v[48:49]
	v_cvt_pk_f16_f32 v36, v36, v37
	v_cvt_pk_f16_f32 v37, v48, v49
	v_pk_mul_f32 v[56:57], v[38:39], v[50:51]
	v_pk_mul_f32 v[58:59], v[38:39], v[44:45]
	s_waitcnt lgkmcnt(14)
	ds_write2st64_b32 v199, v36, v37 offset1:18
	v_cvt_pk_f16_f32 v36, v52, v53
	v_cvt_pk_f16_f32 v37, v54, v55
	v_pk_mul_f32 v[50:51], v[0:1], v[50:51]
	s_waitcnt lgkmcnt(14)
	ds_write2st64_b32 v199, v36, v37 offset0:36 offset1:54
	v_cvt_pk_f16_f32 v36, v56, v57
	v_cvt_pk_f16_f32 v37, v58, v59
	s_waitcnt lgkmcnt(14)
	ds_write2st64_b32 v199, v36, v37 offset0:72 offset1:90
	v_cvt_f16_f32_e32 v36, v50
	v_pk_mul_f32 v[44:45], v[0:1], v[44:45]
	v_cvt_f16_f32_e32 v37, v51
	v_cvt_f16_f32_e32 v44, v44
	v_cvt_f16_f32_e32 v45, v45
	s_waitcnt lgkmcnt(14)
	ds_write_b16 v174, v36 offset:20
	s_waitcnt lgkmcnt(14)
	ds_write_b16 v174, v37 offset:60
	s_waitcnt lgkmcnt(14)
	ds_write_b16 v174, v44 offset:5140
	s_waitcnt lgkmcnt(14)
	ds_write_b16 v174, v45 offset:5180
	s_waitcnt lgkmcnt(14)
	ds_write_b16 v174, v60 offset:10260
	s_waitcnt lgkmcnt(14)
	ds_read_b32 v2, v252 offset:32768
	v_rcp_f32_e32 v44, v42
	v_rcp_f32_e32 v45, v43
	v_cvt_f32_f16_e32 v52, v243
	v_cvt_f32_f16_sdwa v53, v243 dst_sel:DWORD dst_unused:UNUSED_PAD src0_sel:WORD_1
	v_cvt_f32_f16_e32 v56, v235
	v_cvt_f32_f16_sdwa v57, v235 dst_sel:DWORD dst_unused:UNUSED_PAD src0_sel:WORD_1
	v_cvt_f32_f16_e32 v50, v242
	v_cvt_f32_f16_e32 v54, v234
	v_cvt_f32_f16_sdwa v55, v234 dst_sel:DWORD dst_unused:UNUSED_PAD src0_sel:WORD_1
	v_cvt_f32_f16_sdwa v51, v242 dst_sel:DWORD dst_unused:UNUSED_PAD src0_sel:WORD_1
	v_pk_mul_f32 v[36:37], v[46:47], v[52:53]
	v_pk_mul_f32 v[42:43], v[42:43], v[56:57]
	v_pk_mul_f32 v[46:47], v[44:45], v[54:55]
	v_pk_mul_f32 v[44:45], v[44:45], v[50:51]
	v_pk_mul_f32 v[48:49], v[40:41], v[36:37]
	v_pk_mul_f32 v[40:41], v[40:41], v[42:43]
	v_cvt_pk_f16_f32 v36, v36, v37
	v_cvt_pk_f16_f32 v37, v42, v43
	v_pk_mul_f32 v[50:51], v[38:39], v[46:47]
	v_pk_mul_f32 v[38:39], v[38:39], v[44:45]
	s_waitcnt lgkmcnt(14)
	ds_write2st64_b32 v201, v36, v37 offset1:18
	v_cvt_pk_f16_f32 v36, v48, v49
	v_cvt_pk_f16_f32 v37, v40, v41
	v_pk_mul_f32 v[46:47], v[0:1], v[46:47]
	s_waitcnt lgkmcnt(14)
	ds_write2st64_b32 v201, v36, v37 offset0:36 offset1:54
	v_cvt_pk_f16_f32 v36, v50, v51
	v_cvt_pk_f16_f32 v37, v38, v39
	s_waitcnt lgkmcnt(14)
	ds_write2st64_b32 v201, v36, v37 offset0:72 offset1:90
	v_cvt_f16_f32_e32 v36, v46
	v_pk_mul_f32 v[44:45], v[0:1], v[44:45]
	v_cvt_f16_f32_e32 v37, v47
	v_cvt_f16_f32_e32 v38, v44
	v_cvt_f16_f32_e32 v39, v45
	s_waitcnt lgkmcnt(14)
	ds_write_b16 v174, v36 offset:22
	s_waitcnt lgkmcnt(14)
	ds_write_b16 v174, v37 offset:62
	s_waitcnt lgkmcnt(14)
	ds_write_b16 v174, v38 offset:5142
	s_waitcnt lgkmcnt(14)
	ds_write_b16 v174, v39 offset:5182
	s_nop 0
	s_waitcnt lgkmcnt(7)
	ds_write_b16 v174, v2 offset:10262
	v_perm_b32 v36, v62, v64, s82
	v_perm_b32 v37, v2, v60, s82
	ds_write_b64 v174, v[36:37] offset:10296

.LBB0_473:
	v_cmp_eq_u32_e32 vcc, 1, v172
	s_and_saveexec_b64 s[28:29], vcc
	s_cbranch_execz .LBB0_475
	v_lshl_add_u32 v253, v186, 1, v2
	v_lshl_add_u32 v252, v188, 1, v2
	ds_read2st64_b32 v[36:37], v253 offset0:64 offset1:80
	ds_read2st64_b32 v[46:47], v253 offset0:96 offset1:112
	ds_read_b32 v62, v253 offset:32768
	ds_read2st64_b32 v[232:233], v252 offset0:64 offset1:80
	ds_read2st64_b32 v[234:235], v252 offset0:96 offset1:112
	v_lshl_add_u32 v50, v186, 1, v2
	s_nop 0
	s_nop 0
	s_nop 0
	v_rcp_f32_e32 v42, v54
	v_rcp_f32_e32 v43, v55
	s_waitcnt lgkmcnt(3)
	v_cvt_f32_f16_e32 v58, v47
	v_cvt_f32_f16_e32 v52, v37
	v_cvt_f32_f16_sdwa v53, v37 dst_sel:DWORD dst_unused:UNUSED_PAD src0_sel:WORD_1
	v_cvt_f32_f16_sdwa v59, v47 dst_sel:DWORD dst_unused:UNUSED_PAD src0_sel:WORD_1
	v_cvt_f32_f16_e32 v50, v36
	v_cvt_f32_f16_e32 v56, v46
	v_cvt_f32_f16_sdwa v57, v46 dst_sel:DWORD dst_unused:UNUSED_PAD src0_sel:WORD_1
	v_cvt_f32_f16_sdwa v51, v36 dst_sel:DWORD dst_unused:UNUSED_PAD src0_sel:WORD_1
	v_pk_mul_f32 v[36:37], v[60:61], v[52:53]
	v_pk_mul_f32 v[46:47], v[54:55], v[58:59]
	v_pk_mul_f32 v[52:53], v[42:43], v[56:57]
	v_pk_mul_f32 v[42:43], v[42:43], v[50:51]
	v_pk_mul_f32 v[50:51], v[40:41], v[36:37]
	v_pk_mul_f32 v[56:57], v[40:41], v[46:47]
	v_cvt_pk_f16_f32 v36, v36, v37
	v_cvt_pk_f16_f32 v37, v46, v47
	v_pk_mul_f32 v[58:59], v[38:39], v[52:53]
	v_pk_mul_f32 v[60:61], v[38:39], v[42:43]
	ds_write2st64_b32 v187, v36, v37 offset1:18
	v_cvt_pk_f16_f32 v36, v50, v51
	v_cvt_pk_f16_f32 v37, v56, v57
	v_pk_mul_f32 v[52:53], v[0:1], v[52:53]
	ds_write2st64_b32 v187, v36, v37 offset0:36 offset1:54
	v_cvt_pk_f16_f32 v36, v58, v59
	v_cvt_pk_f16_f32 v37, v60, v61
	v_lshl_add_u32 v253, v190, 1, v2
	ds_read_b32 v60, v252 offset:32768
	ds_read2st64_b32 v[236:237], v253 offset0:64 offset1:80
	ds_read2st64_b32 v[240:241], v253 offset0:96 offset1:112
	ds_write2st64_b32 v187, v36, v37 offset0:72 offset1:90
	v_cvt_f16_f32_e32 v36, v52
	v_pk_mul_f32 v[42:43], v[0:1], v[42:43]
	v_cvt_f16_f32_e32 v37, v53
	v_cvt_f16_f32_e32 v42, v42
	v_cvt_f16_f32_e32 v43, v43
	ds_write_b16 v174, v36 offset:8
	ds_write_b16 v174, v37 offset:48
	ds_write_b16 v174, v42 offset:5128
	ds_write_b16 v174, v43 offset:5168
	s_waitcnt lgkmcnt(12)
	ds_write_b16 v174, v62 offset:10248
	v_lshl_add_u32 v50, v188, 1, v2
	v_rcp_f32_e32 v42, v48
	v_rcp_f32_e32 v43, v49
	s_waitcnt lgkmcnt(12)
	v_cvt_f32_f16_e32 v52, v233
	v_cvt_f32_f16_sdwa v53, v233 dst_sel:DWORD dst_unused:UNUSED_PAD src0_sel:WORD_1
	s_waitcnt lgkmcnt(11)
	v_cvt_f32_f16_e32 v58, v235
	v_cvt_f32_f16_sdwa v59, v235 dst_sel:DWORD dst_unused:UNUSED_PAD src0_sel:WORD_1
	v_cvt_f32_f16_e32 v50, v232
	v_cvt_f32_f16_e32 v56, v234
	v_cvt_f32_f16_sdwa v57, v234 dst_sel:DWORD dst_unused:UNUSED_PAD src0_sel:WORD_1
	v_cvt_f32_f16_sdwa v51, v232 dst_sel:DWORD dst_unused:UNUSED_PAD src0_sel:WORD_1
	v_pk_mul_f32 v[36:37], v[54:55], v[52:53]
	v_pk_mul_f32 v[46:47], v[48:49], v[58:59]
	v_pk_mul_f32 v[52:53], v[42:43], v[56:57]
	v_pk_mul_f32 v[42:43], v[42:43], v[50:51]
	v_pk_mul_f32 v[50:51], v[40:41], v[36:37]
	v_pk_mul_f32 v[54:55], v[40:41], v[46:47]
	v_cvt_pk_f16_f32 v36, v36, v37
	v_cvt_pk_f16_f32 v37, v46, v47
	v_pk_mul_f32 v[56:57], v[38:39], v[52:53]
	v_pk_mul_f32 v[58:59], v[38:39], v[42:43]
	ds_write2st64_b32 v189, v36, v37 offset1:18
	v_cvt_pk_f16_f32 v36, v50, v51
	v_cvt_pk_f16_f32 v37, v54, v55
	v_pk_mul_f32 v[52:53], v[0:1], v[52:53]
	ds_write2st64_b32 v189, v36, v37 offset0:36 offset1:54
	v_cvt_pk_f16_f32 v36, v56, v57
	v_cvt_pk_f16_f32 v37, v58, v59
	v_lshl_add_u32 v252, v192, 1, v2
	ds_read_b32 v58, v253 offset:32768
	ds_read2st64_b32 v[242:243], v252 offset0:64 offset1:80
	s_waitcnt lgkmcnt(14)
	ds_read2st64_b32 v[234:235], v252 offset0:96 offset1:112
	s_waitcnt lgkmcnt(14)
	ds_write2st64_b32 v189, v36, v37 offset0:72 offset1:90
	v_cvt_f16_f32_e32 v36, v52
	v_pk_mul_f32 v[42:43], v[0:1], v[42:43]
	v_cvt_f16_f32_e32 v37, v53
	v_cvt_f16_f32_e32 v42, v42
	v_cvt_f16_f32_e32 v43, v43
	s_waitcnt lgkmcnt(14)
	ds_write_b16 v174, v36 offset:10
	s_waitcnt lgkmcnt(14)
	ds_write_b16 v174, v37 offset:50
	s_waitcnt lgkmcnt(14)
	ds_write_b16 v174, v42 offset:5130
	s_waitcnt lgkmcnt(14)
	ds_write_b16 v174, v43 offset:5170
	s_waitcnt lgkmcnt(14)
	ds_write_b16 v174, v60 offset:10250
	v_lshl_add_u32 v50, v190, 1, v2
	v_rcp_f32_e32 v42, v44
	v_rcp_f32_e32 v43, v45
	v_lshl_add_u32 v2, v192, 1, v2
	v_cvt_f32_f16_e32 v52, v237
	v_cvt_f32_f16_sdwa v53, v237 dst_sel:DWORD dst_unused:UNUSED_PAD src0_sel:WORD_1
	v_cvt_f32_f16_e32 v56, v241
	v_cvt_f32_f16_sdwa v57, v241 dst_sel:DWORD dst_unused:UNUSED_PAD src0_sel:WORD_1
	v_cvt_f32_f16_e32 v50, v236
	v_cvt_f32_f16_e32 v54, v240
	v_cvt_f32_f16_sdwa v55, v240 dst_sel:DWORD dst_unused:UNUSED_PAD src0_sel:WORD_1
	v_cvt_f32_f16_sdwa v51, v236 dst_sel:DWORD dst_unused:UNUSED_PAD src0_sel:WORD_1
	v_pk_mul_f32 v[36:37], v[48:49], v[52:53]
	v_pk_mul_f32 v[46:47], v[44:45], v[56:57]
	v_pk_mul_f32 v[48:49], v[42:43], v[54:55]
	v_pk_mul_f32 v[42:43], v[42:43], v[50:51]
	v_pk_mul_f32 v[50:51], v[40:41], v[36:37]
	v_pk_mul_f32 v[52:53], v[40:41], v[46:47]
	v_cvt_pk_f16_f32 v36, v36, v37
	v_cvt_pk_f16_f32 v37, v46, v47
	v_pk_mul_f32 v[54:55], v[38:39], v[48:49]
	v_pk_mul_f32 v[56:57], v[38:39], v[42:43]
	s_waitcnt lgkmcnt(14)
	ds_write2st64_b32 v191, v36, v37 offset1:18
	v_cvt_pk_f16_f32 v36, v50, v51
	v_cvt_pk_f16_f32 v37, v52, v53
	v_pk_mul_f32 v[48:49], v[0:1], v[48:49]
	s_waitcnt lgkmcnt(14)
	ds_write2st64_b32 v191, v36, v37 offset0:36 offset1:54
	v_cvt_pk_f16_f32 v36, v54, v55
	v_cvt_pk_f16_f32 v37, v56, v57
	s_waitcnt lgkmcnt(14)
	ds_write2st64_b32 v191, v36, v37 offset0:72 offset1:90
	v_cvt_f16_f32_e32 v36, v48
	v_pk_mul_f32 v[42:43], v[0:1], v[42:43]
	v_cvt_f16_f32_e32 v37, v49
	v_cvt_f16_f32_e32 v42, v42
	v_cvt_f16_f32_e32 v43, v43
	s_waitcnt lgkmcnt(14)
	ds_write_b16 v174, v36 offset:12
	s_waitcnt lgkmcnt(14)
	ds_write_b16 v174, v37 offset:52
	s_waitcnt lgkmcnt(14)
	ds_write_b16 v174, v42 offset:5132
	s_waitcnt lgkmcnt(14)
	ds_write_b16 v174, v43 offset:5172
	s_waitcnt lgkmcnt(14)
	ds_write_b16 v174, v58 offset:10252
	s_waitcnt lgkmcnt(14)
	ds_read_b32 v2, v252 offset:32768
	v_cvt_f32_f16_e32 v48, v243
	v_cvt_f32_f16_sdwa v49, v243 dst_sel:DWORD dst_unused:UNUSED_PAD src0_sel:WORD_1
	v_cvt_f32_f16_e32 v52, v235
	v_cvt_f32_f16_sdwa v53, v235 dst_sel:DWORD dst_unused:UNUSED_PAD src0_sel:WORD_1
	v_cvt_f32_f16_e32 v46, v242
	v_cvt_f32_f16_e32 v50, v234
	v_cvt_f32_f16_sdwa v51, v234 dst_sel:DWORD dst_unused:UNUSED_PAD src0_sel:WORD_1
	v_cvt_f32_f16_sdwa v47, v242 dst_sel:DWORD dst_unused:UNUSED_PAD src0_sel:WORD_1
	v_pk_mul_f32 v[36:37], v[44:45], v[48:49]
	v_pk_mul_f32 v[42:43], v[38:39], v[52:53]
	v_pk_mul_f32 v[44:45], v[40:41], v[50:51]
	v_pk_mul_f32 v[46:47], v[40:41], v[46:47]
	v_pk_mul_f32 v[48:49], v[40:41], v[36:37]
	v_pk_mul_f32 v[40:41], v[40:41], v[42:43]
	v_cvt_pk_f16_f32 v36, v36, v37
	v_cvt_pk_f16_f32 v37, v42, v43
	v_pk_mul_f32 v[50:51], v[38:39], v[44:45]
	v_pk_mul_f32 v[38:39], v[38:39], v[46:47]
	s_waitcnt lgkmcnt(14)
	ds_write2st64_b32 v193, v36, v37 offset1:18
	v_cvt_pk_f16_f32 v36, v48, v49
	v_cvt_pk_f16_f32 v37, v40, v41
	v_pk_mul_f32 v[44:45], v[0:1], v[44:45]
	s_waitcnt lgkmcnt(14)
	ds_write2st64_b32 v193, v36, v37 offset0:36 offset1:54
	v_cvt_pk_f16_f32 v36, v50, v51
	v_cvt_pk_f16_f32 v37, v38, v39
	s_waitcnt lgkmcnt(14)
	ds_write2st64_b32 v193, v36, v37 offset0:72 offset1:90
	v_cvt_f16_f32_e32 v36, v44
	v_pk_mul_f32 v[46:47], v[0:1], v[46:47]
	v_cvt_f16_f32_e32 v37, v45
	v_cvt_f16_f32_e32 v38, v46
	v_cvt_f16_f32_e32 v39, v47
	s_waitcnt lgkmcnt(14)
	ds_write_b16 v174, v36 offset:14
	s_waitcnt lgkmcnt(14)
	ds_write_b16 v174, v37 offset:54
	s_waitcnt lgkmcnt(14)
	ds_write_b16 v174, v38 offset:5134
	s_waitcnt lgkmcnt(14)
	ds_write_b16 v174, v39 offset:5174
	s_nop 0
	s_waitcnt lgkmcnt(7)
	ds_write_b16 v174, v2 offset:10254
	v_perm_b32 v36, v60, v62, s82
	v_perm_b32 v37, v2, v58, s82
	ds_write_b64 v174, v[36:37] offset:10288

.LBB0_900:
	s_or_b64 exec, exec, s[0:1]
	s_nop 5
	v_cvt_f16_f32_e32 v2, v52
	v_cvt_f16_f32_e32 v52, v53
	v_cvt_f16_f32_e32 v53, v54
	v_cvt_f16_f32_e32 v54, v55
	v_cndmask_b32_e64 v2, v2, 0, s[18:19]
	v_cndmask_b32_e64 v52, 0, v52, s[20:21]
	v_cndmask_b32_e64 v53, v53, 0, s[22:23]
	v_cndmask_b32_e64 v54, v54, 0, s[24:25]
	v_pack_b32_f16 v53, v53, v54
	v_pack_b32_f16 v52, v2, v52
	ds_write_b64 v123, v[52:53]
	s_waitcnt lgkmcnt(0)
	s_barrier
	ds_read_b128 v[126:129], v124 offset:55360
	ds_read_b128 v[52:55], v125
	ds_read_b128 v[162:165], v125 offset:64
	ds_read_b128 v[178:181], v125 offset:2304
	ds_read_b128 v[182:185], v125 offset:2368
	ds_read_b128 v[186:189], v125 offset:4608
	ds_read_b128 v[190:193], v125 offset:4672
	ds_read_b128 v[68:71], v124 offset:55296
	s_nop 0
	s_nop 0
	ds_read_b128 v[194:197], v125 offset:6912
	s_nop 0
	s_waitcnt lgkmcnt(1)
	v_mfma_f32_16x16x32_f16 v[48:51], v[68:71], v[52:55], v[48:51]
	s_nop 0
	v_add_u32_e32 v2, 0x1e500, v96
	ds_read_b128 v[198:201], v125 offset:6976
	s_add_i32 s28, s28, 1
	s_nop 0
	v_mfma_f32_16x16x32_f16 v[52:55], v[126:129], v[162:165], v[48:51]
	ds_read_b128 v[162:165], v2
	s_nop 2
	s_nop 0
	s_nop 0
	v_mfma_f32_16x16x32_f16 v[48:51], v[68:71], v[178:181], v[56:59]
	s_nop 2
	s_nop 0
	ds_read_b128 v[178:181], v248 offset:46080
	v_cvt_pk_f16_f32 v55, v54, v55
	v_cvt_pk_f16_f32 v54, v52, v53
	s_nop 0
	v_mfma_f32_16x16x32_f16 v[56:59], v[126:129], v[182:185], v[48:51]
	ds_read_b128 v[182:185], v248 offset:46144
	s_nop 2
	s_nop 0
	s_nop 0
	ds_read_b128 v[202:205], v2 offset:64
	v_mfma_f32_16x16x32_f16 v[48:51], v[68:71], v[186:189], v[60:63]
	s_nop 2
	s_nop 0
	s_nop 0
	ds_read_b128 v[186:189], v249 offset:48384
	v_mfma_f32_16x16x32_f16 v[60:63], v[126:129], v[190:193], v[48:51]
	s_nop 2
	s_nop 0
	ds_read_b128 v[190:193], v249 offset:48448
	s_nop 0
	s_waitcnt lgkmcnt(7)
	v_mfma_f32_16x16x32_f16 v[48:51], v[68:71], v[194:197], v[64:67]
	s_nop 2
	ds_read_b128 v[194:197], v2 offset:128
	s_nop 0
	s_nop 0
	s_waitcnt lgkmcnt(7)
	v_mfma_f32_16x16x32_f16 v[48:51], v[126:129], v[198:201], v[48:51]
	s_nop 0
	ds_read_b128 v[198:201], v248 offset:50688
	s_nop 0
	s_waitcnt lgkmcnt(7)
	v_pk_mul_f32 v[44:45], v[44:45], v[162:163]
	v_pk_mul_f32 v[46:47], v[46:47], v[164:165]
	ds_read_b128 v[162:165], v248 offset:50752
	s_nop 0
	s_nop 2
	v_cvt_pk_f16_f32 v51, v50, v51
	s_nop 0
	s_waitcnt lgkmcnt(7)
	v_mfma_f32_16x16x32_f16 v[44:47], v[178:181], v[68:71], v[44:47]
	ds_read_b128 v[178:181], v2 offset:192
	s_nop 0
	v_cvt_pk_f16_f32 v50, v48, v49
	s_nop 0
	s_waitcnt lgkmcnt(7)
	v_mfma_f32_16x16x32_f16 v[44:47], v[182:185], v[126:129], v[44:47]
	ds_read_b128 v[182:185], v249 offset:52992
	s_waitcnt lgkmcnt(7)
	v_pk_mul_f32 v[32:33], v[32:33], v[202:203]
	v_pk_mul_f32 v[34:35], v[34:35], v[204:205]
	s_nop 0
	s_nop 0
	s_waitcnt lgkmcnt(6)
	v_mfma_f32_16x16x32_f16 v[32:35], v[186:189], v[68:71], v[32:35]
	s_nop 0
	s_nop 0
	s_waitcnt lgkmcnt(5)
	v_mfma_f32_16x16x32_f16 v[32:35], v[190:193], v[126:129], v[32:35]
	s_waitcnt lgkmcnt(4)
	v_pk_mul_f32 v[40:41], v[40:41], v[194:195]
	v_pk_mul_f32 v[42:43], v[42:43], v[196:197]
	s_nop 0
	s_nop 0
	s_waitcnt lgkmcnt(3)
	v_mfma_f32_16x16x32_f16 v[40:43], v[198:201], v[68:71], v[40:43]
	s_nop 0
	s_nop 0
	s_waitcnt lgkmcnt(2)
	v_mfma_f32_16x16x32_f16 v[40:43], v[162:165], v[126:129], v[40:43]
	v_add_u32_e32 v2, s26, v91
	s_add_i32 s26, s26, 64
	s_waitcnt lgkmcnt(1)
	v_pk_mul_f32 v[36:37], v[36:37], v[178:179]
	v_pk_mul_f32 v[38:39], v[38:39], v[180:181]
	s_nop 0
	s_nop 0
	s_waitcnt lgkmcnt(0)
	v_mfma_f32_16x16x32_f16 v[36:39], v[182:185], v[68:71], v[36:39]
	ds_read_b128 v[64:67], v249 offset:53056
	s_nop 0
	s_waitcnt lgkmcnt(0)
	v_mfma_f32_16x16x32_f16 v[36:39], v[64:67], v[126:129], v[36:39]
	v_add_u32_e32 v64, s27, v112
	v_add_u32_e32 v65, 0xff, v64
	v_cndmask_b32_e64 v65, v65, v2, s[2:3]
	v_add_u32_e32 v52, v65, v89
	v_mad_i64_i32 v[52:53], s[0:1], v52, s88, v[82:83]
	global_store_dwordx2 v[52:53], v[54:55], off
	v_add_u32_e32 v52, 16, v2
	v_add_u32_e32 v53, 0xef, v64
	v_cndmask_b32_e64 v54, v53, v52, s[2:3]
	v_add_u32_e32 v54, v54, v89
	v_cvt_pk_f16_f32 v53, v58, v59
	v_cvt_pk_f16_f32 v52, v56, v57
	v_mad_i64_i32 v[54:55], s[0:1], v54, s88, v[82:83]
	global_store_dwordx2 v[54:55], v[52:53], off
	v_add_u32_e32 v52, 32, v2
	v_add_u32_e32 v53, 0xdf, v64
	v_cndmask_b32_e64 v54, v53, v52, s[2:3]
	v_add_u32_e32 v54, v54, v89
	v_cvt_pk_f16_f32 v53, v62, v63
	v_cvt_pk_f16_f32 v52, v60, v61
	v_mad_i64_i32 v[54:55], s[0:1], v54, s88, v[82:83]
	global_store_dwordx2 v[54:55], v[52:53], off
	v_add_u32_e32 v2, 48, v2
	v_add_u32_e32 v52, 0xcf, v64
	v_cndmask_b32_e64 v2, v52, v2, s[2:3]
	v_add_u32_e32 v2, v2, v89
	s_sub_i32 s27, s27, 64
	v_mad_i64_i32 v[48:49], s[0:1], v2, s88, v[82:83]
	s_cmpk_lg_i32 s27, 0xff00
	global_store_dwordx2 v[48:49], v[50:51], off
	s_cbranch_scc0 .LBB0_1058

.LBB0_909:
	v_add_u32_e32 v243, v93, v106
	ds_read_b128 v[48:51], v243
	ds_read_b128 v[52:55], v243 offset:64
	v_add_u32_e32 v2, v93, v106
	s_nop 0
	s_nop 0
	s_nop 0
	s_waitcnt lgkmcnt(1)
	v_mfma_f32_16x16x32_f16 v[48:51], v[48:51], v[24:27], 0
	s_nop 0
	s_waitcnt lgkmcnt(0)
	v_mfma_f32_16x16x32_f16 v[48:51], v[52:55], v[28:31], v[48:51]
	s_nop 7
	ds_write_b128 v107, v[48:51]
	s_and_saveexec_b64 s[0:1], s[68:69]
	s_cbranch_execz .LBB0_911
	v_mul_f32_e32 v2, 0x3fb8aa3b, v48
	v_exp_f32_e32 v48, v2
	v_mul_f32_e32 v2, 0x3fb8aa3b, v49
	v_exp_f32_e32 v49, v2
	v_mul_f32_e32 v2, 0x3fb8aa3b, v50
	v_exp_f32_e32 v50, v2
	v_mul_f32_e32 v2, 0x3fb8aa3b, v51
	v_exp_f32_e32 v51, v2
	ds_write_b128 v110, v[48:51]
.LBB0_911:
	s_or_b64 exec, exec, s[0:1]
	v_add_u32_e32 v243, v93, v108
	ds_read_b128 v[48:51], v243
	ds_read_b128 v[52:55], v243 offset:64
	v_add_u32_e32 v2, v93, v108
	s_nop 0
	s_nop 0
	s_nop 0
	s_waitcnt lgkmcnt(1)
	v_mfma_f32_16x16x32_f16 v[48:51], v[48:51], v[24:27], 0
	s_nop 0
	s_waitcnt lgkmcnt(0)
	v_mfma_f32_16x16x32_f16 v[48:51], v[52:55], v[28:31], v[48:51]
	s_nop 7
	ds_write_b128 v109, v[48:51]
	s_and_saveexec_b64 s[0:1], s[68:69]
	s_cbranch_execz .LBB0_913
	v_mul_f32_e32 v2, 0x3fb8aa3b, v48
	v_exp_f32_e32 v48, v2
	v_mul_f32_e32 v2, 0x3fb8aa3b, v49
	v_exp_f32_e32 v49, v2
	v_mul_f32_e32 v2, 0x3fb8aa3b, v50
	v_exp_f32_e32 v50, v2
	v_mul_f32_e32 v2, 0x3fb8aa3b, v51
	v_exp_f32_e32 v51, v2
	ds_write_b128 v111, v[48:51]
.LBB0_913:
	s_or_b64 exec, exec, s[0:1]
	s_waitcnt lgkmcnt(0)
	s_barrier
	ds_read_b128 v[52:55], v92 offset:9216
	ds_read_b128 v[60:63], v94
	ds_read_b128 v[48:51], v92
	s_nop 0
	s_nop 0
	ds_read_b128 v[68:71], v101
	ds_read_b128 v[56:59], v250 offset:16
	s_nop 0
	v_add_u32_e32 v81, v95, v103
	s_nop 0
	s_waitcnt lgkmcnt(4)
	v_cvt_f32_f16_sdwa v67, v52 dst_sel:DWORD dst_unused:UNUSED_PAD src0_sel:WORD_1
	s_nop 0
	s_waitcnt lgkmcnt(3)
	v_mul_f32_e32 v2, 0x3fb8aa3b, v60
	v_exp_f32_e32 v60, v2
	v_mul_f32_e32 v2, 0x3fb8aa3b, v61
	v_exp_f32_e32 v61, v2
	v_cvt_f32_f16_e32 v66, v52
	v_rcp_f32_e32 v64, v60
	v_add3_u32 v52, v78, v97, v247
	v_rcp_f32_e32 v65, v61
	v_cvt_f32_f16_sdwa v127, v54 dst_sel:DWORD dst_unused:UNUSED_PAD src0_sel:WORD_1
	v_cvt_f32_f16_e32 v126, v54
	v_pk_mul_f32 v[66:67], v[64:65], v[66:67]
	s_waitcnt lgkmcnt(2)
	v_cvt_f32_f16_sdwa v65, v48 dst_sel:DWORD dst_unused:UNUSED_PAD src0_sel:WORD_1
	v_cvt_f32_f16_e32 v64, v48
	s_nop 0
	s_waitcnt lgkmcnt(1)
	v_fma_mixlo_f16 v2, v68, v66, 0
	ds_write_b16 v52, v2 offset:46080
	v_fma_mixlo_f16 v2, v69, v67, 0
	v_pk_mul_f32 v[64:65], v[64:65], s[72:73] op_sel_hi:[1,0]
	ds_write_b16 v121, v2 offset:46080
	v_mul_f32_e32 v2, 0x3fb8aa3b, v62
	v_pk_mul_f32 v[64:65], v[64:65], v[60:61]
	v_exp_f32_e32 v60, v2
	v_mul_f32_e32 v2, 0x3fb8aa3b, v63
	v_exp_f32_e32 v61, v2
	v_cvt_f32_f16_sdwa v69, v53 dst_sel:DWORD dst_unused:UNUSED_PAD src0_sel:WORD_1
	v_rcp_f32_e32 v62, v60
	v_cvt_f32_f16_e32 v68, v53
	v_rcp_f32_e32 v63, v61
	v_cvt_f32_f16_sdwa v53, v49 dst_sel:DWORD dst_unused:UNUSED_PAD src0_sel:WORD_1
	v_cvt_f32_f16_e32 v52, v49
	v_cvt_pk_f16_f32 v48, v64, v65
	v_pk_mul_f32 v[68:69], v[62:63], v[68:69]
	v_pk_mul_f32 v[52:53], v[52:53], s[72:73] op_sel_hi:[1,0]
	v_fma_mixlo_f16 v2, v70, v68, 0
	ds_write_b16 v121, v2 offset:46224
	v_fma_mixlo_f16 v2, v71, v69, 0
	ds_write_b16 v121, v2 offset:46368
	s_waitcnt lgkmcnt(4)
	v_mul_f32_e32 v2, 0x3fb8aa3b, v56
	v_exp_f32_e32 v56, v2
	v_mul_f32_e32 v2, 0x3fb8aa3b, v57
	v_exp_f32_e32 v57, v2
	v_pk_mul_f32 v[52:53], v[52:53], v[60:61]
	ds_read_b128 v[60:63], v102
	v_rcp_f32_e32 v70, v56
	s_nop 0
	v_rcp_f32_e32 v71, v57
	v_cvt_pk_f16_f32 v49, v52, v53
	v_pk_mul_f32 v[70:71], v[70:71], v[126:127]
	s_nop 0
	s_waitcnt lgkmcnt(0)
	v_fma_mixlo_f16 v2, v60, v70, 0
	ds_write_b16 v121, v2 offset:46512
	v_fma_mixlo_f16 v2, v61, v71, 0
	ds_write_b16 v121, v2 offset:46656
	v_mul_f32_e32 v2, 0x3fb8aa3b, v58
	v_cvt_f32_f16_sdwa v127, v50 dst_sel:DWORD dst_unused:UNUSED_PAD src0_sel:WORD_1
	v_cvt_f32_f16_e32 v126, v50
	v_exp_f32_e32 v58, v2
	v_mul_f32_e32 v2, 0x3fb8aa3b, v59
	v_exp_f32_e32 v59, v2
	v_pk_mul_f32 v[126:127], v[126:127], s[72:73] op_sel_hi:[1,0]
	v_cvt_f32_f16_sdwa v61, v55 dst_sel:DWORD dst_unused:UNUSED_PAD src0_sel:WORD_1
	v_pk_mul_f32 v[126:127], v[126:127], v[56:57]
	v_rcp_f32_e32 v56, v58
	v_rcp_f32_e32 v57, v59
	v_cvt_f32_f16_e32 v60, v55
	v_bfe_u32 v55, v71, 16, 1
	v_add3_u32 v55, v71, v55, s34
	v_cvt_pk_f16_f32 v50, v126, v127
	v_pk_mul_f32 v[128:129], v[56:57], v[60:61]
	v_bfe_u32 v56, v70, 16, 1
	v_fma_mixlo_f16 v2, v62, v128, 0
	ds_write_b16 v121, v2 offset:46800
	v_bfe_u32 v2, v129, 16, 1
	v_bfe_u32 v54, v128, 16, 1
	v_bfe_u32 v57, v69, 16, 1
	v_bfe_u32 v60, v68, 16, 1
	v_bfe_u32 v61, v67, 16, 1
	v_bfe_u32 v62, v66, 16, 1
	v_add3_u32 v62, v66, v62, s34
	v_add3_u32 v61, v67, v61, s34
	v_add3_u32 v60, v68, v60, s34
	v_add3_u32 v66, v69, v57, s34
	v_add3_u32 v56, v70, v56, s34
	v_add3_u32 v54, v128, v54, s34
	v_add3_u32 v2, v129, v2, s34
	v_perm_b32 v57, v2, v54, s35
	v_perm_b32 v56, v55, v56, s35
	v_perm_b32 v55, v66, v60, s35
	v_perm_b32 v54, v61, v62, s35
	v_cvt_f32_f16_sdwa v61, v51 dst_sel:DWORD dst_unused:UNUSED_PAD src0_sel:WORD_1
	v_cvt_f32_f16_e32 v60, v51
	v_bfe_u32 v62, v126, 16, 1
	v_bfe_u32 v66, v53, 16, 1
	v_bfe_u32 v67, v52, 16, 1
	v_pk_mul_f32 v[60:61], v[60:61], s[72:73] op_sel_hi:[1,0]
	v_bfe_u32 v68, v65, 16, 1
	v_pk_mul_f32 v[58:59], v[60:61], v[58:59]
	v_bfe_u32 v61, v127, 16, 1
	v_bfe_u32 v2, v59, 16, 1
	v_bfe_u32 v60, v58, 16, 1
	v_cvt_pk_f16_f32 v51, v58, v59
	v_bfe_u32 v69, v64, 16, 1
	v_add3_u32 v58, v58, v60, s34
	v_add3_u32 v2, v59, v2, s34
	v_add3_u32 v64, v64, v69, s34
	v_add3_u32 v65, v65, v68, s34
	v_add3_u32 v52, v52, v67, s34
	v_add3_u32 v53, v53, v66, s34
	v_add3_u32 v62, v126, v62, s34
	v_add3_u32 v66, v127, v61, s34
	v_perm_b32 v61, v2, v58, s35
	v_fma_mixlo_f16 v2, v63, v129, 0
	v_perm_b32 v60, v66, v62, s35
	v_perm_b32 v59, v53, v52, s35
	v_perm_b32 v58, v65, v64, s35
	ds_write_b16 v121, v2 offset:46944
	ds_write_b128 v92, v[58:61] offset:18432
	ds_write_b128 v92, v[54:57] offset:27648
	ds_write_b128 v92, v[48:51] offset:36864
	v_add_u32_e32 v2, v79, v72
	s_nop 0
	s_barrier
	ds_read_b128 v[52:55], v81 offset:36864
	ds_read_b128 v[56:59], v81 offset:39168
	ds_read_b128 v[60:63], v81 offset:41472
	ds_read_b128 v[64:67], v81 offset:43776
	ds_read_b128 v[68:71], v2 offset:64
	ds_read_b128 v[162:165], v81 offset:36928
	ds_read_b128 v[178:181], v81 offset:39232
	ds_read_b128 v[182:185], v81 offset:41536
	ds_read_b128 v[48:51], v2
	s_nop 0
	s_nop 0
	s_nop 0
	s_nop 0
	s_nop 0
	s_waitcnt lgkmcnt(0)
	v_mfma_f32_16x16x32_f16 v[52:55], v[48:51], v[52:55], 0
	s_nop 0
	v_mfma_f32_16x16x32_f16 v[56:59], v[48:51], v[56:59], 0
	s_nop 0
	v_mfma_f32_16x16x32_f16 v[60:63], v[48:51], v[60:63], 0
	s_nop 0
	v_mfma_f32_16x16x32_f16 v[64:67], v[48:51], v[64:67], 0
	s_nop 0
	s_nop 0
	v_add_u32_e32 v2, v100, v72
	s_nop 0
	v_mfma_f32_16x16x32_f16 v[48:51], v[68:71], v[162:165], v[52:55]
	s_nop 2
	s_nop 0
	s_nop 0
	v_mfma_f32_16x16x32_f16 v[56:59], v[68:71], v[178:181], v[56:59]
	s_nop 0
	s_nop 0
	v_mfma_f32_16x16x32_f16 v[60:63], v[68:71], v[182:185], v[60:63]
	ds_read_b128 v[52:55], v81 offset:43840
	s_nop 0
	s_waitcnt lgkmcnt(0)
	v_mfma_f32_16x16x32_f16 v[64:67], v[68:71], v[52:55], v[64:67]
	v_mov_b32_e32 v52, 0
	v_mov_b32_e32 v68, 0
	v_mov_b32_e32 v69, 0
	v_mov_b32_e32 v70, 0
	v_mov_b32_e32 v71, 0
	s_and_saveexec_b64 s[0:1], s[6:7]
	s_cbranch_execz .LBB0_915
	v_add_u32_e32 v243, v95, v106
	ds_read_b128 v[68:71], v2 offset:18432
	ds_read_b128 v[126:129], v243 offset:27648
	v_add_u32_e32 v53, v95, v106
	s_nop 0
	s_nop 0
	s_nop 0
	s_waitcnt lgkmcnt(0)
	v_mfma_f32_16x16x32_bf16 v[68:71], v[126:129], v[68:71], 0
	ds_read_b128 v[130:133], v53 offset:27712
	ds_read_b128 v[126:129], v2 offset:18496
	s_nop 0
	s_nop 0
	s_waitcnt lgkmcnt(0)
	v_mfma_f32_16x16x32_bf16 v[68:71], v[130:133], v[126:129], v[68:71]
.LBB0_915:
	s_or_b64 exec, exec, s[0:1]
	s_nop 6
	v_cvt_f16_f32_e32 v53, v68
	v_cvt_f16_f32_e32 v54, v69
	v_cvt_f16_f32_e32 v55, v70
	v_cvt_f16_f32_e32 v68, v71
	v_cndmask_b32_e64 v53, v53, 0, s[10:11]
	v_cndmask_b32_e64 v54, 0, v54, s[12:13]
	v_cndmask_b32_e64 v55, v55, 0, s[14:15]
	v_cndmask_b32_e64 v68, v68, 0, s[16:17]
	v_pack_b32_f16 v55, v55, v68
	v_pack_b32_f16 v54, v53, v54
	ds_write_b64 v122, v[54:55]
	v_mov_b32_e32 v53, 0
	v_mov_b32_e32 v54, 0
	v_mov_b32_e32 v55, 0
	s_and_saveexec_b64 s[0:1], s[8:9]
	s_cbranch_execz .LBB0_900
	v_add_u32_e32 v243, v95, v108
	ds_read_b128 v[52:55], v2 offset:18432
	ds_read_b128 v[68:71], v243 offset:27648
	v_add_u32_e32 v81, v95, v108
	s_nop 0
	s_nop 0
	s_nop 0
	s_waitcnt lgkmcnt(0)
	v_mfma_f32_16x16x32_bf16 v[52:55], v[68:71], v[52:55], 0
	ds_read_b128 v[126:129], v81 offset:27712
	ds_read_b128 v[68:71], v2 offset:18496
	s_nop 0
	s_nop 0
	s_waitcnt lgkmcnt(0)
	v_mfma_f32_16x16x32_bf16 v[52:55], v[126:129], v[68:71], v[52:55]
	s_branch .LBB0_900

.LBB0_929:
	s_and_b32 s27, s26, 1
	v_lshl_add_u32 v0, s27, 13, v234
	ds_read2_b64 v[36:39], v0 offset1:32
	v_mad_u32_u24 v2, s27, v167, v235
	s_waitcnt lgkmcnt(0)
	v_pk_mul_f32 v[66:67], v[36:37], v[38:39]
	v_xor_b32_e32 v90, 16, v0
	ds_read2_b64 v[38:41], v90 offset0:64 offset1:96
	s_waitcnt lgkmcnt(0)
	v_pk_mul_f32 v[64:65], v[66:67], v[38:39]
	s_nop 0
	v_pk_mul_f32 v[60:61], v[64:65], v[40:41]
	v_xor_b32_e32 v91, 32, v0
	ds_read2_b64 v[38:41], v91 offset0:128 offset1:160
	s_waitcnt lgkmcnt(0)
	v_pk_mul_f32 v[54:55], v[60:61], v[38:39]
	s_nop 0
	v_pk_mul_f32 v[48:49], v[54:55], v[40:41]
	v_xor_b32_e32 v92, 48, v0
	ds_read2_b64 v[38:41], v92 offset0:192 offset1:224
	v_add_u32_e32 v0, 0x800, v0
	v_xor_b32_e32 v91, 32, v0
	ds_read2_b64 v[68:71], v91 offset0:128 offset1:160
	s_waitcnt lgkmcnt(1)
	v_pk_mul_f32 v[44:45], v[48:49], v[38:39]
	s_nop 0
	v_pk_mul_f32 v[38:39], v[44:45], v[40:41]
	ds_read2_b64 v[40:43], v0 offset1:32
	s_waitcnt lgkmcnt(0)
	v_pk_mul_f32 v[58:59], v[38:39], v[40:41]
	s_nop 0
	v_pk_mul_f32 v[50:51], v[58:59], v[42:43]
	v_xor_b32_e32 v90, 16, v0
	ds_read2_b64 v[40:43], v90 offset0:64 offset1:96
	s_waitcnt lgkmcnt(0)
	v_pk_mul_f32 v[46:47], v[50:51], v[40:41]
	s_nop 0
	v_pk_mul_f32 v[42:43], v[46:47], v[42:43]
	v_rcp_f32_e32 v40, v38
	v_pk_mul_f32 v[62:63], v[42:43], v[68:69]
	v_rcp_f32_e32 v41, v39
	v_pk_mul_f32 v[56:57], v[62:63], v[70:71]
	v_xor_b32_e32 v92, 48, v0
	ds_read2_b64 v[68:71], v92 offset0:192 offset1:224
	s_waitcnt lgkmcnt(0)
	v_pk_mul_f32 v[52:53], v[56:57], v[68:69]
	s_nop 0
	v_pk_mul_f32 v[0:1], v[52:53], v[70:71]
	s_and_saveexec_b64 s[28:29], s[4:5]
	s_cbranch_execz .LBB0_931
	v_lshl_add_u32 v243, v179, 1, v2
	v_lshl_add_u32 v242, v186, 1, v2
	ds_read2st64_b32 v[72:73], v243 offset0:96 offset1:112
	ds_read2st64_b32 v[68:69], v243 offset0:64 offset1:80
	ds_read_b32 v84, v243 offset:32768
	ds_read2st64_b32 v[162:163], v242 offset0:64 offset1:80
	ds_read2st64_b32 v[164:165], v242 offset0:96 offset1:112
	v_lshl_add_u32 v74, v179, 1, v2
	s_nop 0
	s_nop 0
	v_rcp_f32_e32 v70, v36
	v_rcp_f32_e32 v71, v37
	s_waitcnt lgkmcnt(4)
	v_cvt_f32_f16_e32 v78, v73
	v_cvt_f32_f16_sdwa v79, v73 dst_sel:DWORD dst_unused:UNUSED_PAD src0_sel:WORD_1
	s_waitcnt lgkmcnt(3)
	v_cvt_f32_f16_e32 v74, v68
	v_cvt_f32_f16_sdwa v75, v68 dst_sel:DWORD dst_unused:UNUSED_PAD src0_sel:WORD_1
	v_cvt_f32_f16_e32 v76, v72
	v_cvt_f32_f16_sdwa v77, v72 dst_sel:DWORD dst_unused:UNUSED_PAD src0_sel:WORD_1
	v_cvt_f32_f16_e32 v72, v69
	v_cvt_f32_f16_sdwa v73, v69 dst_sel:DWORD dst_unused:UNUSED_PAD src0_sel:WORD_1
	v_pk_mul_f32 v[78:79], v[36:37], v[78:79]
	v_pk_mul_f32 v[76:77], v[70:71], v[76:77]
	v_pk_mul_f32 v[70:71], v[70:71], v[74:75]
	v_pk_mul_f32 v[72:73], v[40:41], v[72:73]
	v_pk_mul_f32 v[74:75], v[40:41], v[78:79]
	v_cvt_pk_f16_f32 v68, v78, v79
	v_pk_mul_f32 v[80:81], v[38:39], v[76:77]
	v_pk_mul_f32 v[82:83], v[38:39], v[70:71]
	ds_write2st64_b32 v185, v69, v68 offset1:18
	v_cvt_pk_f16_f32 v68, v72, v73
	v_cvt_pk_f16_f32 v69, v74, v75
	v_pk_mul_f32 v[76:77], v[0:1], v[76:77]
	ds_write2st64_b32 v185, v68, v69 offset0:36 offset1:54
	v_cvt_pk_f16_f32 v68, v80, v81
	v_cvt_pk_f16_f32 v69, v82, v83
	v_lshl_add_u32 v243, v188, 1, v2
	ds_read_b32 v82, v242 offset:32768
	ds_write2st64_b32 v185, v68, v69 offset0:72 offset1:90
	v_cvt_f16_f32_e32 v68, v76
	v_pk_mul_f32 v[70:71], v[0:1], v[70:71]
	v_cvt_f16_f32_e32 v69, v77
	v_cvt_f16_f32_e32 v70, v70
	v_cvt_f16_f32_e32 v71, v71
	ds_write_b16 v180, v68
	ds_write_b16 v180, v69 offset:40
	ds_write_b16 v180, v70 offset:5120
	ds_write_b16 v180, v71 offset:5160
	s_waitcnt lgkmcnt(10)
	ds_write_b16 v180, v84 offset:10240
	v_lshl_add_u32 v74, v186, 1, v2
	v_rcp_f32_e32 v70, v66
	v_rcp_f32_e32 v71, v67
	s_waitcnt lgkmcnt(10)
	v_cvt_f32_f16_e32 v76, v163
	v_cvt_f32_f16_sdwa v77, v163 dst_sel:DWORD dst_unused:UNUSED_PAD src0_sel:WORD_1
	s_waitcnt lgkmcnt(9)
	v_cvt_f32_f16_e32 v80, v165
	v_cvt_f32_f16_sdwa v81, v165 dst_sel:DWORD dst_unused:UNUSED_PAD src0_sel:WORD_1
	v_cvt_f32_f16_e32 v74, v162
	v_cvt_f32_f16_e32 v78, v164
	v_cvt_f32_f16_sdwa v79, v164 dst_sel:DWORD dst_unused:UNUSED_PAD src0_sel:WORD_1
	ds_read2st64_b32 v[164:165], v243 offset0:64 offset1:80
	v_cvt_f32_f16_sdwa v75, v162 dst_sel:DWORD dst_unused:UNUSED_PAD src0_sel:WORD_1
	ds_read2st64_b32 v[162:163], v243 offset0:96 offset1:112
	v_pk_mul_f32 v[36:37], v[36:37], v[76:77]
	v_pk_mul_f32 v[68:69], v[66:67], v[80:81]
	v_pk_mul_f32 v[72:73], v[70:71], v[78:79]
	v_pk_mul_f32 v[70:71], v[70:71], v[74:75]
	v_pk_mul_f32 v[74:75], v[40:41], v[36:37]
	v_pk_mul_f32 v[76:77], v[40:41], v[68:69]
	v_cvt_pk_f16_f32 v36, v36, v37
	v_cvt_pk_f16_f32 v37, v68, v69
	v_pk_mul_f32 v[78:79], v[38:39], v[72:73]
	v_pk_mul_f32 v[80:81], v[38:39], v[70:71]
	ds_write2st64_b32 v187, v36, v37 offset1:18
	v_cvt_pk_f16_f32 v36, v74, v75
	v_cvt_pk_f16_f32 v37, v76, v77
	v_pk_mul_f32 v[72:73], v[0:1], v[72:73]
	ds_write2st64_b32 v187, v36, v37 offset0:36 offset1:54
	v_cvt_pk_f16_f32 v36, v78, v79
	v_cvt_pk_f16_f32 v37, v80, v81
	v_lshl_add_u32 v242, v190, 1, v2
	ds_read_b32 v80, v243 offset:32768
	ds_write2st64_b32 v187, v36, v37 offset0:72 offset1:90
	v_cvt_f16_f32_e32 v36, v72
	v_pk_mul_f32 v[70:71], v[0:1], v[70:71]
	v_cvt_f16_f32_e32 v37, v73
	v_cvt_f16_f32_e32 v68, v70
	v_cvt_f16_f32_e32 v69, v71
	s_waitcnt lgkmcnt(14)
	ds_write_b16 v180, v36 offset:2
	s_waitcnt lgkmcnt(14)
	ds_write_b16 v180, v37 offset:42
	s_waitcnt lgkmcnt(14)
	ds_write_b16 v180, v68 offset:5122
	s_waitcnt lgkmcnt(14)
	ds_write_b16 v180, v69 offset:5162
	s_waitcnt lgkmcnt(14)
	ds_write_b16 v180, v82 offset:10242
	v_lshl_add_u32 v72, v188, 1, v2
	v_rcp_f32_e32 v68, v64
	v_rcp_f32_e32 v69, v65
	s_waitcnt lgkmcnt(10)
	v_cvt_f32_f16_e32 v74, v165
	v_cvt_f32_f16_sdwa v75, v165 dst_sel:DWORD dst_unused:UNUSED_PAD src0_sel:WORD_1
	s_waitcnt lgkmcnt(9)
	v_cvt_f32_f16_e32 v78, v163
	v_cvt_f32_f16_sdwa v79, v163 dst_sel:DWORD dst_unused:UNUSED_PAD src0_sel:WORD_1
	v_cvt_f32_f16_e32 v72, v164
	v_cvt_f32_f16_e32 v76, v162
	v_cvt_f32_f16_sdwa v77, v162 dst_sel:DWORD dst_unused:UNUSED_PAD src0_sel:WORD_1
	ds_read2st64_b32 v[162:163], v242 offset0:64 offset1:80
	v_cvt_f32_f16_sdwa v73, v164 dst_sel:DWORD dst_unused:UNUSED_PAD src0_sel:WORD_1
	ds_read2st64_b32 v[164:165], v242 offset0:96 offset1:112
	v_pk_mul_f32 v[36:37], v[66:67], v[74:75]
	v_pk_mul_f32 v[66:67], v[64:65], v[78:79]
	v_pk_mul_f32 v[70:71], v[68:69], v[76:77]
	v_pk_mul_f32 v[68:69], v[68:69], v[72:73]
	v_pk_mul_f32 v[72:73], v[40:41], v[36:37]
	v_pk_mul_f32 v[74:75], v[40:41], v[66:67]
	v_cvt_pk_f16_f32 v36, v36, v37
	v_cvt_pk_f16_f32 v37, v66, v67
	v_pk_mul_f32 v[76:77], v[38:39], v[70:71]
	v_pk_mul_f32 v[78:79], v[38:39], v[68:69]
	ds_write2st64_b32 v189, v36, v37 offset1:18
	v_cvt_pk_f16_f32 v36, v72, v73
	v_cvt_pk_f16_f32 v37, v74, v75
	v_pk_mul_f32 v[70:71], v[0:1], v[70:71]
	ds_write2st64_b32 v189, v36, v37 offset0:36 offset1:54
	v_cvt_pk_f16_f32 v36, v76, v77
	v_cvt_pk_f16_f32 v37, v78, v79
	ds_read_b32 v78, v242 offset:32768
	ds_write2st64_b32 v189, v36, v37 offset0:72 offset1:90
	v_cvt_f16_f32_e32 v36, v70
	v_pk_mul_f32 v[68:69], v[0:1], v[68:69]
	v_cvt_f16_f32_e32 v37, v71
	v_cvt_f16_f32_e32 v66, v68
	v_cvt_f16_f32_e32 v67, v69
	s_waitcnt lgkmcnt(14)
	ds_write_b16 v180, v36 offset:4
	s_waitcnt lgkmcnt(14)
	ds_write_b16 v180, v37 offset:44
	s_waitcnt lgkmcnt(14)
	ds_write_b16 v180, v66 offset:5124
	s_waitcnt lgkmcnt(14)
	ds_write_b16 v180, v67 offset:5164
	s_waitcnt lgkmcnt(14)
	ds_write_b16 v180, v80 offset:10244
	v_lshl_add_u32 v70, v190, 1, v2
	v_rcp_f32_e32 v66, v60
	v_rcp_f32_e32 v67, v61
	s_waitcnt lgkmcnt(10)
	v_cvt_f32_f16_e32 v72, v163
	v_cvt_f32_f16_sdwa v73, v163 dst_sel:DWORD dst_unused:UNUSED_PAD src0_sel:WORD_1
	s_waitcnt lgkmcnt(9)
	v_cvt_f32_f16_e32 v76, v165
	v_cvt_f32_f16_sdwa v77, v165 dst_sel:DWORD dst_unused:UNUSED_PAD src0_sel:WORD_1
	v_cvt_f32_f16_e32 v70, v162
	v_cvt_f32_f16_e32 v74, v164
	v_cvt_f32_f16_sdwa v75, v164 dst_sel:DWORD dst_unused:UNUSED_PAD src0_sel:WORD_1
	v_cvt_f32_f16_sdwa v71, v162 dst_sel:DWORD dst_unused:UNUSED_PAD src0_sel:WORD_1
	v_pk_mul_f32 v[36:37], v[64:65], v[72:73]
	v_pk_mul_f32 v[64:65], v[60:61], v[76:77]
	v_pk_mul_f32 v[68:69], v[66:67], v[74:75]
	v_pk_mul_f32 v[66:67], v[66:67], v[70:71]
	v_pk_mul_f32 v[70:71], v[40:41], v[36:37]
	v_pk_mul_f32 v[72:73], v[40:41], v[64:65]
	v_cvt_pk_f16_f32 v36, v36, v37
	v_cvt_pk_f16_f32 v37, v64, v65
	v_pk_mul_f32 v[74:75], v[38:39], v[68:69]
	v_pk_mul_f32 v[76:77], v[38:39], v[66:67]
	ds_write2st64_b32 v191, v36, v37 offset1:18
	v_cvt_pk_f16_f32 v36, v70, v71
	v_cvt_pk_f16_f32 v37, v72, v73
	v_pk_mul_f32 v[68:69], v[0:1], v[68:69]
	ds_write2st64_b32 v191, v36, v37 offset0:36 offset1:54
	v_cvt_pk_f16_f32 v36, v74, v75
	v_cvt_pk_f16_f32 v37, v76, v77
	ds_write2st64_b32 v191, v36, v37 offset0:72 offset1:90
	v_cvt_f16_f32_e32 v36, v68
	v_pk_mul_f32 v[66:67], v[0:1], v[66:67]
	v_cvt_f16_f32_e32 v37, v69
	v_cvt_f16_f32_e32 v64, v66
	v_cvt_f16_f32_e32 v65, v67
	ds_write_b16 v180, v36 offset:6
	ds_write_b16 v180, v37 offset:46
	ds_write_b16 v180, v64 offset:5126
	s_waitcnt lgkmcnt(14)
	ds_write_b16 v180, v65 offset:5166
	s_nop 0
	s_waitcnt lgkmcnt(13)
	ds_write_b16 v180, v78 offset:10246
	v_perm_b32 v36, v82, v84, s35
	v_perm_b32 v37, v78, v80, s35
	ds_write_b64 v180, v[36:37] offset:10280

.LBB0_942:
	v_cmp_lt_i32_e32 vcc, 2, v178
	s_and_saveexec_b64 s[30:31], vcc
	s_xor_b64 s[68:69], exec, s[30:31]
	s_cbranch_execz .LBB0_944
	v_lshl_add_u32 v243, v208, 1, v2
	v_lshl_add_u32 v242, v210, 1, v2
	ds_read2st64_b32 v[36:37], v243 offset0:64 offset1:80
	ds_read2st64_b32 v[46:47], v243 offset0:96 offset1:112
	ds_read_b32 v60, v243 offset:32768
	ds_read2st64_b32 v[162:163], v242 offset0:64 offset1:80
	ds_read2st64_b32 v[164:165], v242 offset0:96 offset1:112
	ds_read_b32 v61, v242 offset:32768
	v_lshl_add_u32 v48, v208, 1, v2
	s_nop 0
	s_nop 0
	v_rcp_f32_e32 v44, v62
	v_rcp_f32_e32 v45, v63
	v_lshl_add_u32 v243, v212, 1, v2
	s_waitcnt lgkmcnt(4)
	v_cvt_f32_f16_e32 v58, v47
	v_cvt_f32_f16_e32 v50, v37
	v_cvt_f32_f16_sdwa v51, v37 dst_sel:DWORD dst_unused:UNUSED_PAD src0_sel:WORD_1
	v_cvt_f32_f16_sdwa v59, v47 dst_sel:DWORD dst_unused:UNUSED_PAD src0_sel:WORD_1
	v_cvt_f32_f16_e32 v48, v36
	v_cvt_f32_f16_e32 v54, v46
	v_cvt_f32_f16_sdwa v55, v46 dst_sel:DWORD dst_unused:UNUSED_PAD src0_sel:WORD_1
	v_cvt_f32_f16_sdwa v49, v36 dst_sel:DWORD dst_unused:UNUSED_PAD src0_sel:WORD_1
	v_pk_mul_f32 v[36:37], v[42:43], v[50:51]
	v_pk_mul_f32 v[42:43], v[62:63], v[58:59]
	v_pk_mul_f32 v[46:47], v[44:45], v[54:55]
	v_pk_mul_f32 v[44:45], v[44:45], v[48:49]
	v_pk_mul_f32 v[48:49], v[40:41], v[36:37]
	v_pk_mul_f32 v[50:51], v[40:41], v[42:43]
	v_cvt_pk_f16_f32 v36, v36, v37
	v_cvt_pk_f16_f32 v37, v42, v43
	v_pk_mul_f32 v[54:55], v[38:39], v[46:47]
	v_pk_mul_f32 v[58:59], v[38:39], v[44:45]
	ds_write2st64_b32 v209, v36, v37 offset1:18
	v_cvt_pk_f16_f32 v36, v48, v49
	v_cvt_pk_f16_f32 v37, v50, v51
	v_pk_mul_f32 v[46:47], v[0:1], v[46:47]
	ds_write2st64_b32 v209, v36, v37 offset0:36 offset1:54
	v_cvt_pk_f16_f32 v36, v54, v55
	v_cvt_pk_f16_f32 v37, v58, v59
	ds_write2st64_b32 v209, v36, v37 offset0:72 offset1:90
	v_cvt_f16_f32_e32 v36, v46
	v_pk_mul_f32 v[44:45], v[0:1], v[44:45]
	v_cvt_f16_f32_e32 v37, v47
	v_cvt_f16_f32_e32 v42, v44
	v_cvt_f16_f32_e32 v43, v45
	ds_write_b16 v180, v36 offset:24
	ds_write_b16 v180, v37 offset:64
	ds_write_b16 v180, v42 offset:5144
	ds_write_b16 v180, v43 offset:5184
	s_waitcnt lgkmcnt(10)
	ds_write_b16 v180, v60 offset:10264
	v_lshl_add_u32 v46, v210, 1, v2
	v_rcp_f32_e32 v42, v56
	v_rcp_f32_e32 v43, v57
	s_waitcnt lgkmcnt(10)
	v_cvt_f32_f16_e32 v48, v163
	v_cvt_f32_f16_sdwa v49, v163 dst_sel:DWORD dst_unused:UNUSED_PAD src0_sel:WORD_1
	s_waitcnt lgkmcnt(9)
	v_cvt_f32_f16_e32 v54, v165
	v_cvt_f32_f16_sdwa v55, v165 dst_sel:DWORD dst_unused:UNUSED_PAD src0_sel:WORD_1
	v_cvt_f32_f16_e32 v46, v162
	v_cvt_f32_f16_e32 v50, v164
	v_cvt_f32_f16_sdwa v51, v164 dst_sel:DWORD dst_unused:UNUSED_PAD src0_sel:WORD_1
	ds_read2st64_b32 v[164:165], v243 offset0:64 offset1:80
	v_cvt_f32_f16_sdwa v47, v162 dst_sel:DWORD dst_unused:UNUSED_PAD src0_sel:WORD_1
	ds_read2st64_b32 v[162:163], v243 offset0:96 offset1:112
	v_pk_mul_f32 v[36:37], v[62:63], v[48:49]
	v_pk_mul_f32 v[44:45], v[56:57], v[54:55]
	v_pk_mul_f32 v[48:49], v[42:43], v[50:51]
	v_pk_mul_f32 v[42:43], v[42:43], v[46:47]
	v_pk_mul_f32 v[46:47], v[40:41], v[36:37]
	v_pk_mul_f32 v[50:51], v[40:41], v[44:45]
	v_cvt_pk_f16_f32 v36, v36, v37
	v_cvt_pk_f16_f32 v37, v44, v45
	v_pk_mul_f32 v[54:55], v[38:39], v[48:49]
	v_pk_mul_f32 v[58:59], v[38:39], v[42:43]
	ds_write2st64_b32 v211, v36, v37 offset1:18
	v_cvt_pk_f16_f32 v36, v46, v47
	v_cvt_pk_f16_f32 v37, v50, v51
	v_pk_mul_f32 v[48:49], v[0:1], v[48:49]
	ds_write2st64_b32 v211, v36, v37 offset0:36 offset1:54
	v_cvt_pk_f16_f32 v36, v54, v55
	v_cvt_pk_f16_f32 v37, v58, v59
	v_lshl_add_u32 v242, v214, 1, v2
	ds_read_b32 v58, v243 offset:32768
	ds_write2st64_b32 v211, v36, v37 offset0:72 offset1:90
	v_cvt_f16_f32_e32 v36, v48
	v_pk_mul_f32 v[42:43], v[0:1], v[42:43]
	v_cvt_f16_f32_e32 v37, v49
	v_cvt_f16_f32_e32 v42, v42
	v_cvt_f16_f32_e32 v43, v43
	s_waitcnt lgkmcnt(14)
	ds_write_b16 v180, v36 offset:26
	s_waitcnt lgkmcnt(14)
	ds_write_b16 v180, v37 offset:66
	s_waitcnt lgkmcnt(14)
	ds_write_b16 v180, v42 offset:5146
	s_waitcnt lgkmcnt(14)
	ds_write_b16 v180, v43 offset:5186
	s_waitcnt lgkmcnt(14)
	ds_write_b16 v180, v61 offset:10266
	v_lshl_add_u32 v46, v212, 1, v2
	v_rcp_f32_e32 v42, v52
	v_rcp_f32_e32 v43, v53
	v_lshl_add_u32 v2, v214, 1, v2
	s_waitcnt lgkmcnt(10)
	v_cvt_f32_f16_e32 v48, v165
	v_cvt_f32_f16_sdwa v49, v165 dst_sel:DWORD dst_unused:UNUSED_PAD src0_sel:WORD_1
	s_waitcnt lgkmcnt(9)
	v_cvt_f32_f16_e32 v54, v163
	v_cvt_f32_f16_sdwa v55, v163 dst_sel:DWORD dst_unused:UNUSED_PAD src0_sel:WORD_1
	v_cvt_f32_f16_e32 v46, v164
	v_cvt_f32_f16_e32 v50, v162
	v_cvt_f32_f16_sdwa v51, v162 dst_sel:DWORD dst_unused:UNUSED_PAD src0_sel:WORD_1
	ds_read2st64_b32 v[162:163], v242 offset0:64 offset1:80
	v_cvt_f32_f16_sdwa v47, v164 dst_sel:DWORD dst_unused:UNUSED_PAD src0_sel:WORD_1
	ds_read2st64_b32 v[164:165], v2 offset0:96 offset1:112
	v_pk_mul_f32 v[36:37], v[56:57], v[48:49]
	v_pk_mul_f32 v[44:45], v[52:53], v[54:55]
	v_pk_mul_f32 v[48:49], v[42:43], v[50:51]
	v_pk_mul_f32 v[42:43], v[42:43], v[46:47]
	v_pk_mul_f32 v[46:47], v[40:41], v[36:37]
	v_pk_mul_f32 v[50:51], v[40:41], v[44:45]
	v_cvt_pk_f16_f32 v36, v36, v37
	v_cvt_pk_f16_f32 v37, v44, v45
	v_pk_mul_f32 v[54:55], v[38:39], v[48:49]
	v_pk_mul_f32 v[56:57], v[38:39], v[42:43]
	ds_write2st64_b32 v213, v36, v37 offset1:18
	v_cvt_pk_f16_f32 v36, v46, v47
	v_cvt_pk_f16_f32 v37, v50, v51
	v_pk_mul_f32 v[48:49], v[0:1], v[48:49]
	ds_write2st64_b32 v213, v36, v37 offset0:36 offset1:54
	v_cvt_pk_f16_f32 v36, v54, v55
	v_cvt_pk_f16_f32 v37, v56, v57
	ds_write2st64_b32 v213, v36, v37 offset0:72 offset1:90
	v_cvt_f16_f32_e32 v36, v48
	v_pk_mul_f32 v[42:43], v[0:1], v[42:43]
	v_cvt_f16_f32_e32 v37, v49
	v_cvt_f16_f32_e32 v42, v42
	v_cvt_f16_f32_e32 v43, v43
	ds_write_b16 v180, v36 offset:28
	s_waitcnt lgkmcnt(14)
	ds_write_b16 v180, v37 offset:68
	s_waitcnt lgkmcnt(14)
	ds_write_b16 v180, v42 offset:5148
	s_waitcnt lgkmcnt(14)
	ds_write_b16 v180, v43 offset:5188
	s_waitcnt lgkmcnt(14)
	ds_write_b16 v180, v58 offset:10268
	s_waitcnt lgkmcnt(14)
	ds_read_b32 v2, v2 offset:32768
	v_rcp_f32_e32 v42, v0
	v_rcp_f32_e32 v43, v1
	s_waitcnt lgkmcnt(10)
	v_cvt_f32_f16_e32 v48, v163
	v_cvt_f32_f16_sdwa v49, v163 dst_sel:DWORD dst_unused:UNUSED_PAD src0_sel:WORD_1
	s_waitcnt lgkmcnt(9)
	v_cvt_f32_f16_e32 v54, v165
	v_cvt_f32_f16_sdwa v55, v165 dst_sel:DWORD dst_unused:UNUSED_PAD src0_sel:WORD_1
	v_cvt_f32_f16_e32 v46, v162
	v_cvt_f32_f16_e32 v50, v164
	v_cvt_f32_f16_sdwa v51, v164 dst_sel:DWORD dst_unused:UNUSED_PAD src0_sel:WORD_1
	v_cvt_f32_f16_sdwa v47, v162 dst_sel:DWORD dst_unused:UNUSED_PAD src0_sel:WORD_1
	v_pk_mul_f32 v[36:37], v[52:53], v[48:49]
	v_pk_mul_f32 v[44:45], v[0:1], v[54:55]
	v_pk_mul_f32 v[48:49], v[42:43], v[50:51]
	v_pk_mul_f32 v[42:43], v[42:43], v[46:47]
	v_pk_mul_f32 v[46:47], v[40:41], v[36:37]
	v_pk_mul_f32 v[40:41], v[40:41], v[44:45]
	v_cvt_pk_f16_f32 v36, v36, v37
	v_cvt_pk_f16_f32 v37, v44, v45
	v_pk_mul_f32 v[50:51], v[38:39], v[48:49]
	v_pk_mul_f32 v[38:39], v[38:39], v[42:43]
	ds_write2st64_b32 v215, v36, v37 offset1:18
	v_cvt_pk_f16_f32 v36, v46, v47
	v_cvt_pk_f16_f32 v37, v40, v41
	v_pk_mul_f32 v[48:49], v[0:1], v[48:49]
	ds_write2st64_b32 v215, v36, v37 offset0:36 offset1:54
	v_cvt_pk_f16_f32 v36, v50, v51
	v_cvt_pk_f16_f32 v37, v38, v39
	ds_write2st64_b32 v215, v36, v37 offset0:72 offset1:90
	v_cvt_f16_f32_e32 v36, v48
	v_pk_mul_f32 v[42:43], v[0:1], v[42:43]
	v_cvt_f16_f32_e32 v37, v49
	v_cvt_f16_f32_e32 v38, v42
	v_cvt_f16_f32_e32 v39, v43
	ds_write_b16 v180, v36 offset:30
	ds_write_b16 v180, v37 offset:70
	ds_write_b16 v180, v38 offset:5150
	s_waitcnt lgkmcnt(14)
	ds_write_b16 v180, v39 offset:5190
	s_nop 0
	s_waitcnt lgkmcnt(7)
	ds_write_b16 v180, v2 offset:10270
	v_perm_b32 v36, v61, v60, s35
	v_perm_b32 v37, v2, v58, s35
	ds_write_b64 v180, v[36:37] offset:10304
.LBB0_944:
	s_andn2_saveexec_b64 s[68:69], s[68:69]
	s_cbranch_execz .LBB0_946
	v_lshl_add_u32 v243, v200, 1, v2
	v_lshl_add_u32 v242, v202, 1, v2
	ds_read2st64_b32 v[36:37], v243 offset0:64 offset1:80
	ds_read2st64_b32 v[48:49], v243 offset0:96 offset1:112
	ds_read_b32 v64, v243 offset:32768
	ds_read2st64_b32 v[162:163], v242 offset0:64 offset1:80
	ds_read2st64_b32 v[164:165], v242 offset0:96 offset1:112
	v_lshl_add_u32 v52, v200, 1, v2
	s_nop 0
	s_nop 0
	s_nop 0
	v_rcp_f32_e32 v44, v58
	v_rcp_f32_e32 v45, v59
	s_waitcnt lgkmcnt(3)
	v_cvt_f32_f16_e32 v60, v49
	v_cvt_f32_f16_e32 v54, v37
	v_cvt_f32_f16_sdwa v55, v37 dst_sel:DWORD dst_unused:UNUSED_PAD src0_sel:WORD_1
	v_cvt_f32_f16_sdwa v61, v49 dst_sel:DWORD dst_unused:UNUSED_PAD src0_sel:WORD_1
	v_cvt_f32_f16_e32 v52, v36
	v_cvt_f32_f16_e32 v56, v48
	v_cvt_f32_f16_sdwa v57, v48 dst_sel:DWORD dst_unused:UNUSED_PAD src0_sel:WORD_1
	v_cvt_f32_f16_sdwa v53, v36 dst_sel:DWORD dst_unused:UNUSED_PAD src0_sel:WORD_1
	v_pk_mul_f32 v[36:37], v[38:39], v[54:55]
	v_pk_mul_f32 v[48:49], v[58:59], v[60:61]
	v_pk_mul_f32 v[54:55], v[44:45], v[56:57]
	v_pk_mul_f32 v[44:45], v[44:45], v[52:53]
	v_pk_mul_f32 v[52:53], v[40:41], v[36:37]
	v_pk_mul_f32 v[56:57], v[40:41], v[48:49]
	v_cvt_pk_f16_f32 v36, v36, v37
	v_cvt_pk_f16_f32 v37, v48, v49
	v_pk_mul_f32 v[60:61], v[38:39], v[54:55]
	v_pk_mul_f32 v[62:63], v[38:39], v[44:45]
	ds_write2st64_b32 v201, v36, v37 offset1:18
	v_cvt_pk_f16_f32 v36, v52, v53
	v_cvt_pk_f16_f32 v37, v56, v57
	v_pk_mul_f32 v[54:55], v[0:1], v[54:55]
	ds_write2st64_b32 v201, v36, v37 offset0:36 offset1:54
	v_cvt_pk_f16_f32 v36, v60, v61
	v_cvt_pk_f16_f32 v37, v62, v63
	v_lshl_add_u32 v243, v204, 1, v2
	ds_read_b32 v62, v242 offset:32768
	ds_write2st64_b32 v201, v36, v37 offset0:72 offset1:90
	v_cvt_f16_f32_e32 v36, v54
	v_pk_mul_f32 v[44:45], v[0:1], v[44:45]
	v_cvt_f16_f32_e32 v37, v55
	v_cvt_f16_f32_e32 v44, v44
	v_cvt_f16_f32_e32 v45, v45
	ds_write_b16 v180, v36 offset:16
	ds_write_b16 v180, v37 offset:56
	ds_write_b16 v180, v44 offset:5136
	ds_write_b16 v180, v45 offset:5176
	s_waitcnt lgkmcnt(10)
	ds_write_b16 v180, v64 offset:10256
	v_lshl_add_u32 v52, v202, 1, v2
	v_rcp_f32_e32 v44, v50
	v_rcp_f32_e32 v45, v51
	s_waitcnt lgkmcnt(10)
	v_cvt_f32_f16_e32 v54, v163
	v_cvt_f32_f16_sdwa v55, v163 dst_sel:DWORD dst_unused:UNUSED_PAD src0_sel:WORD_1
	s_waitcnt lgkmcnt(9)
	v_cvt_f32_f16_e32 v60, v165
	v_cvt_f32_f16_sdwa v61, v165 dst_sel:DWORD dst_unused:UNUSED_PAD src0_sel:WORD_1
	v_cvt_f32_f16_e32 v52, v162
	v_cvt_f32_f16_e32 v56, v164
	v_cvt_f32_f16_sdwa v57, v164 dst_sel:DWORD dst_unused:UNUSED_PAD src0_sel:WORD_1
	ds_read2st64_b32 v[164:165], v243 offset0:64 offset1:80
	v_cvt_f32_f16_sdwa v53, v162 dst_sel:DWORD dst_unused:UNUSED_PAD src0_sel:WORD_1
	ds_read2st64_b32 v[162:163], v243 offset0:96 offset1:112
	v_pk_mul_f32 v[36:37], v[58:59], v[54:55]
	v_pk_mul_f32 v[48:49], v[50:51], v[60:61]
	v_pk_mul_f32 v[54:55], v[44:45], v[56:57]
	v_pk_mul_f32 v[44:45], v[44:45], v[52:53]
	v_pk_mul_f32 v[52:53], v[40:41], v[36:37]
	v_pk_mul_f32 v[56:57], v[40:41], v[48:49]
	v_cvt_pk_f16_f32 v36, v36, v37
	v_cvt_pk_f16_f32 v37, v48, v49
	v_pk_mul_f32 v[58:59], v[38:39], v[54:55]
	v_pk_mul_f32 v[60:61], v[38:39], v[44:45]
	ds_write2st64_b32 v203, v36, v37 offset1:18
	v_cvt_pk_f16_f32 v36, v52, v53
	v_cvt_pk_f16_f32 v37, v56, v57
	v_pk_mul_f32 v[54:55], v[0:1], v[54:55]
	ds_write2st64_b32 v203, v36, v37 offset0:36 offset1:54
	v_cvt_pk_f16_f32 v36, v58, v59
	v_cvt_pk_f16_f32 v37, v60, v61
	v_lshl_add_u32 v242, v206, 1, v2
	ds_read_b32 v60, v243 offset:32768
	ds_write2st64_b32 v203, v36, v37 offset0:72 offset1:90
	v_cvt_f16_f32_e32 v36, v54
	v_pk_mul_f32 v[44:45], v[0:1], v[44:45]
	v_cvt_f16_f32_e32 v37, v55
	v_cvt_f16_f32_e32 v44, v44
	v_cvt_f16_f32_e32 v45, v45
	s_waitcnt lgkmcnt(14)
	ds_write_b16 v180, v36 offset:18
	s_waitcnt lgkmcnt(14)
	ds_write_b16 v180, v37 offset:58
	s_waitcnt lgkmcnt(14)
	ds_write_b16 v180, v44 offset:5138
	s_waitcnt lgkmcnt(14)
	ds_write_b16 v180, v45 offset:5178
	s_waitcnt lgkmcnt(14)
	ds_write_b16 v180, v62 offset:10258
	v_lshl_add_u32 v52, v204, 1, v2
	v_rcp_f32_e32 v44, v46
	v_rcp_f32_e32 v45, v47
	v_lshl_add_u32 v2, v206, 1, v2
	s_waitcnt lgkmcnt(10)
	v_cvt_f32_f16_e32 v54, v165
	v_cvt_f32_f16_sdwa v55, v165 dst_sel:DWORD dst_unused:UNUSED_PAD src0_sel:WORD_1
	s_waitcnt lgkmcnt(9)
	v_cvt_f32_f16_e32 v58, v163
	v_cvt_f32_f16_sdwa v59, v163 dst_sel:DWORD dst_unused:UNUSED_PAD src0_sel:WORD_1
	v_cvt_f32_f16_e32 v52, v164
	v_cvt_f32_f16_e32 v56, v162
	v_cvt_f32_f16_sdwa v57, v162 dst_sel:DWORD dst_unused:UNUSED_PAD src0_sel:WORD_1
	ds_read2st64_b32 v[162:163], v242 offset0:64 offset1:80
	v_cvt_f32_f16_sdwa v53, v164 dst_sel:DWORD dst_unused:UNUSED_PAD src0_sel:WORD_1
	ds_read2st64_b32 v[164:165], v2 offset0:96 offset1:112
	v_pk_mul_f32 v[36:37], v[50:51], v[54:55]
	v_pk_mul_f32 v[48:49], v[46:47], v[58:59]
	v_pk_mul_f32 v[50:51], v[44:45], v[56:57]
	v_pk_mul_f32 v[44:45], v[44:45], v[52:53]
	v_pk_mul_f32 v[52:53], v[40:41], v[36:37]
	v_pk_mul_f32 v[54:55], v[40:41], v[48:49]
	v_cvt_pk_f16_f32 v36, v36, v37
	v_cvt_pk_f16_f32 v37, v48, v49
	v_pk_mul_f32 v[56:57], v[38:39], v[50:51]
	v_pk_mul_f32 v[58:59], v[38:39], v[44:45]
	ds_write2st64_b32 v205, v36, v37 offset1:18
	v_cvt_pk_f16_f32 v36, v52, v53
	v_cvt_pk_f16_f32 v37, v54, v55
	v_pk_mul_f32 v[50:51], v[0:1], v[50:51]
	ds_write2st64_b32 v205, v36, v37 offset0:36 offset1:54
	v_cvt_pk_f16_f32 v36, v56, v57
	v_cvt_pk_f16_f32 v37, v58, v59
	ds_write2st64_b32 v205, v36, v37 offset0:72 offset1:90
	v_cvt_f16_f32_e32 v36, v50
	v_pk_mul_f32 v[44:45], v[0:1], v[44:45]
	v_cvt_f16_f32_e32 v37, v51
	v_cvt_f16_f32_e32 v44, v44
	v_cvt_f16_f32_e32 v45, v45
	ds_write_b16 v180, v36 offset:20
	s_waitcnt lgkmcnt(14)
	ds_write_b16 v180, v37 offset:60
	s_waitcnt lgkmcnt(14)
	ds_write_b16 v180, v44 offset:5140
	s_waitcnt lgkmcnt(14)
	ds_write_b16 v180, v45 offset:5180
	s_waitcnt lgkmcnt(14)
	ds_write_b16 v180, v60 offset:10260
	s_waitcnt lgkmcnt(14)
	ds_read_b32 v2, v2 offset:32768
	v_rcp_f32_e32 v44, v42
	v_rcp_f32_e32 v45, v43
	s_waitcnt lgkmcnt(10)
	v_cvt_f32_f16_e32 v52, v163
	v_cvt_f32_f16_sdwa v53, v163 dst_sel:DWORD dst_unused:UNUSED_PAD src0_sel:WORD_1
	s_waitcnt lgkmcnt(9)
	v_cvt_f32_f16_e32 v56, v165
	v_cvt_f32_f16_sdwa v57, v165 dst_sel:DWORD dst_unused:UNUSED_PAD src0_sel:WORD_1
	v_cvt_f32_f16_e32 v50, v162
	v_cvt_f32_f16_e32 v54, v164
	v_cvt_f32_f16_sdwa v55, v164 dst_sel:DWORD dst_unused:UNUSED_PAD src0_sel:WORD_1
	v_cvt_f32_f16_sdwa v51, v162 dst_sel:DWORD dst_unused:UNUSED_PAD src0_sel:WORD_1
	v_pk_mul_f32 v[36:37], v[46:47], v[52:53]
	v_pk_mul_f32 v[42:43], v[42:43], v[56:57]
	v_pk_mul_f32 v[46:47], v[44:45], v[54:55]
	v_pk_mul_f32 v[44:45], v[44:45], v[50:51]
	v_pk_mul_f32 v[48:49], v[40:41], v[36:37]
	v_pk_mul_f32 v[40:41], v[40:41], v[42:43]
	v_cvt_pk_f16_f32 v36, v36, v37
	v_cvt_pk_f16_f32 v37, v42, v43
	v_pk_mul_f32 v[50:51], v[38:39], v[46:47]
	v_pk_mul_f32 v[38:39], v[38:39], v[44:45]
	ds_write2st64_b32 v207, v36, v37 offset1:18
	v_cvt_pk_f16_f32 v36, v48, v49
	v_cvt_pk_f16_f32 v37, v40, v41
	v_pk_mul_f32 v[46:47], v[0:1], v[46:47]
	ds_write2st64_b32 v207, v36, v37 offset0:36 offset1:54
	v_cvt_pk_f16_f32 v36, v50, v51
	v_cvt_pk_f16_f32 v37, v38, v39
	ds_write2st64_b32 v207, v36, v37 offset0:72 offset1:90
	v_cvt_f16_f32_e32 v36, v46
	v_pk_mul_f32 v[44:45], v[0:1], v[44:45]
	v_cvt_f16_f32_e32 v37, v47
	v_cvt_f16_f32_e32 v38, v44
	v_cvt_f16_f32_e32 v39, v45
	ds_write_b16 v180, v36 offset:22
	ds_write_b16 v180, v37 offset:62
	ds_write_b16 v180, v38 offset:5142
	s_waitcnt lgkmcnt(14)
	ds_write_b16 v180, v39 offset:5182
	s_nop 0
	s_waitcnt lgkmcnt(7)
	ds_write_b16 v180, v2 offset:10262
	v_perm_b32 v36, v62, v64, s35
	v_perm_b32 v37, v2, v60, s35
	ds_write_b64 v180, v[36:37] offset:10296

.LBB0_947:
	v_cmp_eq_u32_e32 vcc, 1, v178
	s_and_saveexec_b64 s[68:69], vcc
	s_cbranch_execz .LBB0_949
	v_lshl_add_u32 v243, v192, 1, v2
	v_lshl_add_u32 v242, v194, 1, v2
	ds_read2st64_b32 v[36:37], v243 offset0:64 offset1:80
	ds_read2st64_b32 v[46:47], v243 offset0:96 offset1:112
	ds_read_b32 v62, v243 offset:32768
	ds_read2st64_b32 v[162:163], v242 offset0:64 offset1:80
	ds_read2st64_b32 v[164:165], v242 offset0:96 offset1:112
	v_lshl_add_u32 v50, v192, 1, v2
	s_nop 0
	s_nop 0
	s_nop 0
	v_rcp_f32_e32 v42, v54
	v_rcp_f32_e32 v43, v55
	s_waitcnt lgkmcnt(3)
	v_cvt_f32_f16_e32 v58, v47
	v_cvt_f32_f16_e32 v52, v37
	v_cvt_f32_f16_sdwa v53, v37 dst_sel:DWORD dst_unused:UNUSED_PAD src0_sel:WORD_1
	v_cvt_f32_f16_sdwa v59, v47 dst_sel:DWORD dst_unused:UNUSED_PAD src0_sel:WORD_1
	v_cvt_f32_f16_e32 v50, v36
	v_cvt_f32_f16_e32 v56, v46
	v_cvt_f32_f16_sdwa v57, v46 dst_sel:DWORD dst_unused:UNUSED_PAD src0_sel:WORD_1
	v_cvt_f32_f16_sdwa v51, v36 dst_sel:DWORD dst_unused:UNUSED_PAD src0_sel:WORD_1
	v_pk_mul_f32 v[36:37], v[60:61], v[52:53]
	v_pk_mul_f32 v[46:47], v[54:55], v[58:59]
	v_pk_mul_f32 v[52:53], v[42:43], v[56:57]
	v_pk_mul_f32 v[42:43], v[42:43], v[50:51]
	v_pk_mul_f32 v[50:51], v[40:41], v[36:37]
	v_pk_mul_f32 v[56:57], v[40:41], v[46:47]
	v_cvt_pk_f16_f32 v36, v36, v37
	v_cvt_pk_f16_f32 v37, v46, v47
	v_pk_mul_f32 v[58:59], v[38:39], v[52:53]
	v_pk_mul_f32 v[60:61], v[38:39], v[42:43]
	ds_write2st64_b32 v193, v36, v37 offset1:18
	v_cvt_pk_f16_f32 v36, v50, v51
	v_cvt_pk_f16_f32 v37, v56, v57
	v_pk_mul_f32 v[52:53], v[0:1], v[52:53]
	ds_write2st64_b32 v193, v36, v37 offset0:36 offset1:54
	v_cvt_pk_f16_f32 v36, v58, v59
	v_cvt_pk_f16_f32 v37, v60, v61
	v_lshl_add_u32 v243, v196, 1, v2
	ds_read_b32 v60, v242 offset:32768
	ds_write2st64_b32 v193, v36, v37 offset0:72 offset1:90
	v_cvt_f16_f32_e32 v36, v52
	v_pk_mul_f32 v[42:43], v[0:1], v[42:43]
	v_cvt_f16_f32_e32 v37, v53
	v_cvt_f16_f32_e32 v42, v42
	v_cvt_f16_f32_e32 v43, v43
	ds_write_b16 v180, v36 offset:8
	ds_write_b16 v180, v37 offset:48
	ds_write_b16 v180, v42 offset:5128
	ds_write_b16 v180, v43 offset:5168
	s_waitcnt lgkmcnt(10)
	ds_write_b16 v180, v62 offset:10248
	v_lshl_add_u32 v50, v194, 1, v2
	v_rcp_f32_e32 v42, v48
	v_rcp_f32_e32 v43, v49
	s_waitcnt lgkmcnt(10)
	v_cvt_f32_f16_e32 v52, v163
	v_cvt_f32_f16_sdwa v53, v163 dst_sel:DWORD dst_unused:UNUSED_PAD src0_sel:WORD_1
	s_waitcnt lgkmcnt(9)
	v_cvt_f32_f16_e32 v58, v165
	v_cvt_f32_f16_sdwa v59, v165 dst_sel:DWORD dst_unused:UNUSED_PAD src0_sel:WORD_1
	v_cvt_f32_f16_e32 v50, v162
	v_cvt_f32_f16_e32 v56, v164
	v_cvt_f32_f16_sdwa v57, v164 dst_sel:DWORD dst_unused:UNUSED_PAD src0_sel:WORD_1
	ds_read2st64_b32 v[164:165], v243 offset0:64 offset1:80
	v_cvt_f32_f16_sdwa v51, v162 dst_sel:DWORD dst_unused:UNUSED_PAD src0_sel:WORD_1
	ds_read2st64_b32 v[162:163], v243 offset0:96 offset1:112
	v_pk_mul_f32 v[36:37], v[54:55], v[52:53]
	v_pk_mul_f32 v[46:47], v[48:49], v[58:59]
	v_pk_mul_f32 v[52:53], v[42:43], v[56:57]
	v_pk_mul_f32 v[42:43], v[42:43], v[50:51]
	v_pk_mul_f32 v[50:51], v[40:41], v[36:37]
	v_pk_mul_f32 v[54:55], v[40:41], v[46:47]
	v_cvt_pk_f16_f32 v36, v36, v37
	v_cvt_pk_f16_f32 v37, v46, v47
	v_pk_mul_f32 v[56:57], v[38:39], v[52:53]
	v_pk_mul_f32 v[58:59], v[38:39], v[42:43]
	ds_write2st64_b32 v195, v36, v37 offset1:18
	v_cvt_pk_f16_f32 v36, v50, v51
	v_cvt_pk_f16_f32 v37, v54, v55
	v_pk_mul_f32 v[52:53], v[0:1], v[52:53]
	ds_write2st64_b32 v195, v36, v37 offset0:36 offset1:54
	v_cvt_pk_f16_f32 v36, v56, v57
	v_cvt_pk_f16_f32 v37, v58, v59
	v_lshl_add_u32 v242, v198, 1, v2
	ds_read_b32 v58, v243 offset:32768
	ds_write2st64_b32 v195, v36, v37 offset0:72 offset1:90
	v_cvt_f16_f32_e32 v36, v52
	v_pk_mul_f32 v[42:43], v[0:1], v[42:43]
	v_cvt_f16_f32_e32 v37, v53
	v_cvt_f16_f32_e32 v42, v42
	v_cvt_f16_f32_e32 v43, v43
	s_waitcnt lgkmcnt(14)
	ds_write_b16 v180, v36 offset:10
	s_waitcnt lgkmcnt(14)
	ds_write_b16 v180, v37 offset:50
	s_waitcnt lgkmcnt(14)
	ds_write_b16 v180, v42 offset:5130
	s_waitcnt lgkmcnt(14)
	ds_write_b16 v180, v43 offset:5170
	s_waitcnt lgkmcnt(14)
	ds_write_b16 v180, v60 offset:10250
	v_lshl_add_u32 v50, v196, 1, v2
	v_rcp_f32_e32 v42, v44
	v_rcp_f32_e32 v43, v45
	v_lshl_add_u32 v2, v198, 1, v2
	s_waitcnt lgkmcnt(10)
	v_cvt_f32_f16_e32 v52, v165
	v_cvt_f32_f16_sdwa v53, v165 dst_sel:DWORD dst_unused:UNUSED_PAD src0_sel:WORD_1
	s_waitcnt lgkmcnt(9)
	v_cvt_f32_f16_e32 v56, v163
	v_cvt_f32_f16_sdwa v57, v163 dst_sel:DWORD dst_unused:UNUSED_PAD src0_sel:WORD_1
	v_cvt_f32_f16_e32 v50, v164
	v_cvt_f32_f16_e32 v54, v162
	v_cvt_f32_f16_sdwa v55, v162 dst_sel:DWORD dst_unused:UNUSED_PAD src0_sel:WORD_1
	ds_read2st64_b32 v[162:163], v242 offset0:64 offset1:80
	v_cvt_f32_f16_sdwa v51, v164 dst_sel:DWORD dst_unused:UNUSED_PAD src0_sel:WORD_1
	ds_read2st64_b32 v[164:165], v2 offset0:96 offset1:112
	v_pk_mul_f32 v[36:37], v[48:49], v[52:53]
	v_pk_mul_f32 v[46:47], v[44:45], v[56:57]
	v_pk_mul_f32 v[48:49], v[42:43], v[54:55]
	v_pk_mul_f32 v[42:43], v[42:43], v[50:51]
	v_pk_mul_f32 v[50:51], v[40:41], v[36:37]
	v_pk_mul_f32 v[52:53], v[40:41], v[46:47]
	v_cvt_pk_f16_f32 v36, v36, v37
	v_cvt_pk_f16_f32 v37, v46, v47
	v_pk_mul_f32 v[54:55], v[38:39], v[48:49]
	v_pk_mul_f32 v[56:57], v[38:39], v[42:43]
	ds_write2st64_b32 v197, v36, v37 offset1:18
	v_cvt_pk_f16_f32 v36, v50, v51
	v_cvt_pk_f16_f32 v37, v52, v53
	v_pk_mul_f32 v[48:49], v[0:1], v[48:49]
	ds_write2st64_b32 v197, v36, v37 offset0:36 offset1:54
	v_cvt_pk_f16_f32 v36, v54, v55
	v_cvt_pk_f16_f32 v37, v56, v57
	ds_write2st64_b32 v197, v36, v37 offset0:72 offset1:90
	v_cvt_f16_f32_e32 v36, v48
	v_pk_mul_f32 v[42:43], v[0:1], v[42:43]
	v_cvt_f16_f32_e32 v37, v49
	v_cvt_f16_f32_e32 v42, v42
	v_cvt_f16_f32_e32 v43, v43
	ds_write_b16 v180, v36 offset:12
	s_waitcnt lgkmcnt(14)
	ds_write_b16 v180, v37 offset:52
	s_waitcnt lgkmcnt(14)
	ds_write_b16 v180, v42 offset:5132
	s_waitcnt lgkmcnt(14)
	ds_write_b16 v180, v43 offset:5172
	s_waitcnt lgkmcnt(14)
	ds_write_b16 v180, v58 offset:10252
	s_waitcnt lgkmcnt(14)
	ds_read_b32 v2, v2 offset:32768
	s_waitcnt lgkmcnt(10)
	v_cvt_f32_f16_e32 v48, v163
	v_cvt_f32_f16_sdwa v49, v163 dst_sel:DWORD dst_unused:UNUSED_PAD src0_sel:WORD_1
	s_waitcnt lgkmcnt(9)
	v_cvt_f32_f16_e32 v52, v165
	v_cvt_f32_f16_sdwa v53, v165 dst_sel:DWORD dst_unused:UNUSED_PAD src0_sel:WORD_1
	v_cvt_f32_f16_e32 v46, v162
	v_cvt_f32_f16_e32 v50, v164
	v_cvt_f32_f16_sdwa v51, v164 dst_sel:DWORD dst_unused:UNUSED_PAD src0_sel:WORD_1
	v_cvt_f32_f16_sdwa v47, v162 dst_sel:DWORD dst_unused:UNUSED_PAD src0_sel:WORD_1
	v_pk_mul_f32 v[36:37], v[44:45], v[48:49]
	v_pk_mul_f32 v[42:43], v[38:39], v[52:53]
	v_pk_mul_f32 v[44:45], v[40:41], v[50:51]
	v_pk_mul_f32 v[46:47], v[40:41], v[46:47]
	v_pk_mul_f32 v[48:49], v[40:41], v[36:37]
	v_pk_mul_f32 v[40:41], v[40:41], v[42:43]
	v_cvt_pk_f16_f32 v36, v36, v37
	v_cvt_pk_f16_f32 v37, v42, v43
	v_pk_mul_f32 v[50:51], v[38:39], v[44:45]
	v_pk_mul_f32 v[38:39], v[38:39], v[46:47]
	ds_write2st64_b32 v199, v36, v37 offset1:18
	v_cvt_pk_f16_f32 v36, v48, v49
	v_cvt_pk_f16_f32 v37, v40, v41
	v_pk_mul_f32 v[44:45], v[0:1], v[44:45]
	ds_write2st64_b32 v199, v36, v37 offset0:36 offset1:54
	v_cvt_pk_f16_f32 v36, v50, v51
	v_cvt_pk_f16_f32 v37, v38, v39
	ds_write2st64_b32 v199, v36, v37 offset0:72 offset1:90
	v_cvt_f16_f32_e32 v36, v44
	v_pk_mul_f32 v[46:47], v[0:1], v[46:47]
	v_cvt_f16_f32_e32 v37, v45
	v_cvt_f16_f32_e32 v38, v46
	v_cvt_f16_f32_e32 v39, v47
	ds_write_b16 v180, v36 offset:14
	ds_write_b16 v180, v37 offset:54
	ds_write_b16 v180, v38 offset:5134
	s_waitcnt lgkmcnt(14)
	ds_write_b16 v180, v39 offset:5174
	s_nop 0
	s_waitcnt lgkmcnt(7)
	ds_write_b16 v180, v2 offset:10254
	v_perm_b32 v36, v60, v62, s35
	v_perm_b32 v37, v2, v58, s35
	ds_write_b64 v180, v[36:37] offset:10288

.LBB0_994:
	s_or_b64 exec, exec, s[0:1]
	s_nop 5
	v_cvt_f16_f32_e32 v65, v65
	v_cvt_f16_f32_e32 v64, v64
	s_add_i32 s30, s30, 1
	v_cndmask_b32_e64 v68, 0, v65, s[24:25]
	v_cvt_f16_f32_e32 v65, v66
	v_cvt_f16_f32_e32 v66, v67
	v_cndmask_b32_e64 v64, v64, 0, s[22:23]
	v_pack_b32_f16 v64, v64, v68
	v_cndmask_b32_e64 v65, v65, 0, s[26:27]
	v_cndmask_b32_e64 v66, v66, 0, s[28:29]
	v_pack_b32_f16 v65, v65, v66
	ds_write_b64 v115, v[64:65]
	s_waitcnt lgkmcnt(0)
	s_barrier
	ds_read_b128 v[118:121], v116 offset:55360
	ds_read_b128 v[122:125], v117
	ds_read_b128 v[162:165], v117 offset:64
	ds_read_b128 v[178:181], v117 offset:2304
	ds_read_b128 v[182:185], v117 offset:2368
	ds_read_b128 v[186:189], v117 offset:4608
	ds_read_b128 v[190:193], v117 offset:4672
	ds_read_b128 v[194:197], v117 offset:6912
	ds_read_b128 v[64:67], v116 offset:55296
	ds_read_b128 v[198:201], v117 offset:6976
	s_nop 0
	s_nop 0
	s_nop 0
	v_add_u32_e32 v243, 0x1e500, v87
	s_waitcnt lgkmcnt(1)
	v_mfma_f32_16x16x32_f16 v[52:55], v[64:67], v[122:125], v[52:55]
	ds_read_b128 v[202:205], v243
	s_nop 0
	v_add_u32_e32 v68, 0x1e500, v87
	s_nop 0
	v_mfma_f32_16x16x32_f16 v[52:55], v[118:121], v[162:165], v[52:55]
	s_nop 0
	ds_read_b128 v[162:165], v248 offset:46080
	s_nop 0
	v_mfma_f32_16x16x32_f16 v[56:59], v[64:67], v[178:181], v[56:59]
	s_nop 0
	s_nop 3
	ds_read_b128 v[178:181], v248 offset:46144
	v_cvt_pk_f16_f32 v55, v54, v55
	v_cvt_pk_f16_f32 v54, v52, v53
	s_nop 0
	ds_read_b128 v[206:209], v68 offset:64
	v_mfma_f32_16x16x32_f16 v[56:59], v[118:121], v[182:185], v[56:59]
	v_mfma_f32_16x16x32_f16 v[60:63], v[64:67], v[186:189], v[60:63]
	ds_read_b128 v[182:185], v249 offset:48384
	s_nop 0
	s_nop 0
	v_mfma_f32_16x16x32_f16 v[60:63], v[118:121], v[190:193], v[60:63]
	ds_read_b128 v[186:189], v249 offset:48448
	v_mfma_f32_16x16x32_f16 v[48:51], v[64:67], v[194:197], v[48:51]
	ds_read_b128 v[190:193], v68 offset:128
	s_nop 0
	s_nop 0
	s_waitcnt lgkmcnt(7)
	v_mfma_f32_16x16x32_f16 v[48:51], v[118:121], v[198:201], v[48:51]
	s_nop 0
	ds_read_b128 v[194:197], v248 offset:50688
	s_nop 0
	s_waitcnt lgkmcnt(7)
	v_pk_mul_f32 v[8:9], v[8:9], v[202:203]
	v_pk_mul_f32 v[10:11], v[10:11], v[204:205]
	ds_read_b128 v[198:201], v248 offset:50752
	s_nop 0
	s_nop 2
	v_cvt_pk_f16_f32 v51, v50, v51
	ds_read_b128 v[202:205], v68 offset:192
	s_waitcnt lgkmcnt(8)
	v_mfma_f32_16x16x32_f16 v[8:11], v[162:165], v[64:67], v[8:11]
	s_nop 0
	v_cvt_pk_f16_f32 v50, v48, v49
	s_nop 0
	s_waitcnt lgkmcnt(7)
	v_mfma_f32_16x16x32_f16 v[8:11], v[178:181], v[118:121], v[8:11]
	s_waitcnt lgkmcnt(6)
	v_pk_mul_f32 v[4:5], v[4:5], v[206:207]
	v_pk_mul_f32 v[6:7], v[6:7], v[208:209]
	s_nop 0
	s_nop 0
	s_waitcnt lgkmcnt(5)
	v_mfma_f32_16x16x32_f16 v[4:7], v[182:185], v[64:67], v[4:7]
	s_nop 0
	s_nop 0
	s_waitcnt lgkmcnt(4)
	v_mfma_f32_16x16x32_f16 v[4:7], v[186:189], v[118:121], v[4:7]
	s_waitcnt lgkmcnt(3)
	v_pk_mul_f32 v[16:17], v[16:17], v[190:191]
	v_pk_mul_f32 v[18:19], v[18:19], v[192:193]
	s_nop 0
	s_nop 0
	s_waitcnt lgkmcnt(2)
	v_mfma_f32_16x16x32_f16 v[16:19], v[194:197], v[64:67], v[16:19]
	s_nop 0
	s_nop 0
	s_waitcnt lgkmcnt(1)
	v_mfma_f32_16x16x32_f16 v[16:19], v[198:201], v[118:121], v[16:19]
	s_waitcnt lgkmcnt(0)
	v_pk_mul_f32 v[12:13], v[12:13], v[202:203]
	v_pk_mul_f32 v[14:15], v[14:15], v[204:205]
	ds_read_b128 v[122:125], v249 offset:52992
	s_nop 0
	s_waitcnt lgkmcnt(0)
	v_mfma_f32_16x16x32_f16 v[12:15], v[122:125], v[64:67], v[12:15]
	ds_read_b128 v[64:67], v249 offset:53056
	s_nop 0
	s_waitcnt lgkmcnt(0)
	v_mfma_f32_16x16x32_f16 v[12:15], v[64:67], v[118:121], v[12:15]
	v_add_u32_e32 v65, s96, v104
	v_add_u32_e32 v64, s80, v80
	v_add_u32_e32 v66, 0x7ff, v65
	v_cndmask_b32_e64 v66, v66, v64, s[2:3]
	v_add_u32_e32 v52, v66, v81
	v_mad_i64_i32 v[52:53], s[0:1], v52, s88, v[76:77]
	global_store_dwordx2 v[52:53], v[54:55], off
	v_add_u32_e32 v52, 16, v64
	v_add_u32_e32 v53, 0x7ef, v65
	v_cndmask_b32_e64 v54, v53, v52, s[2:3]
	v_add_u32_e32 v54, v54, v81
	v_cvt_pk_f16_f32 v53, v58, v59
	v_cvt_pk_f16_f32 v52, v56, v57
	v_mad_i64_i32 v[54:55], s[0:1], v54, s88, v[76:77]
	global_store_dwordx2 v[54:55], v[52:53], off
	v_add_u32_e32 v52, 32, v64
	v_add_u32_e32 v53, 0x7df, v65
	v_cndmask_b32_e64 v54, v53, v52, s[2:3]
	v_add_u32_e32 v54, v54, v81
	v_cvt_pk_f16_f32 v53, v62, v63
	v_cvt_pk_f16_f32 v52, v60, v61
	v_mad_i64_i32 v[54:55], s[0:1], v54, s88, v[76:77]
	global_store_dwordx2 v[54:55], v[52:53], off
	v_add_u32_e32 v52, 48, v64
	v_add_u32_e32 v53, 0x7cf, v65
	v_cndmask_b32_e64 v52, v53, v52, s[2:3]
	v_add_u32_e32 v48, v52, v81
	s_sub_i32 s96, s96, 64
	s_add_i32 s80, s80, 64
	v_mad_i64_i32 v[48:49], s[0:1], v48, s88, v[76:77]
	s_cmpk_lg_i32 s96, 0xf800
	global_store_dwordx2 v[48:49], v[50:51], off
	s_cbranch_scc0 .LBB0_1011

.LBB0_1003:
	v_add_u32_e32 v243, v84, v98
	ds_read_b128 v[48:51], v243
	v_add_u32_e32 v52, v84, v98
	s_nop 0
	ds_read_b128 v[52:55], v243 offset:64
	s_nop 0
	s_waitcnt lgkmcnt(1)
	v_mfma_f32_16x16x32_f16 v[48:51], v[48:51], v[40:43], 0
	s_nop 0
	s_waitcnt lgkmcnt(0)
	v_mfma_f32_16x16x32_f16 v[48:51], v[52:55], v[44:47], v[48:51]
	s_nop 7
	ds_write_b128 v99, v[48:51]
	s_and_saveexec_b64 s[0:1], s[68:69]
	s_cbranch_execz .LBB0_1005
	v_mul_f32_e32 v48, 0x3fb8aa3b, v48
	v_mul_f32_e32 v49, 0x3fb8aa3b, v49
	v_mul_f32_e32 v50, 0x3fb8aa3b, v50
	v_mul_f32_e32 v51, 0x3fb8aa3b, v51
	v_exp_f32_e32 v48, v48
	v_exp_f32_e32 v49, v49
	v_exp_f32_e32 v50, v50
	v_exp_f32_e32 v51, v51
	ds_write_b128 v102, v[48:51]
.LBB0_1005:
	s_or_b64 exec, exec, s[0:1]
	v_add_u32_e32 v243, v84, v100
	ds_read_b128 v[48:51], v243
	v_add_u32_e32 v52, v84, v100
	s_nop 0
	ds_read_b128 v[52:55], v243 offset:64
	s_nop 0
	s_waitcnt lgkmcnt(1)
	v_mfma_f32_16x16x32_f16 v[48:51], v[48:51], v[40:43], 0
	s_nop 0
	s_waitcnt lgkmcnt(0)
	v_mfma_f32_16x16x32_f16 v[48:51], v[52:55], v[44:47], v[48:51]
	s_nop 7
	ds_write_b128 v101, v[48:51]
	s_and_saveexec_b64 s[0:1], s[68:69]
	s_cbranch_execz .LBB0_1007
	v_mul_f32_e32 v48, 0x3fb8aa3b, v48
	v_mul_f32_e32 v49, 0x3fb8aa3b, v49
	v_mul_f32_e32 v50, 0x3fb8aa3b, v50
	v_mul_f32_e32 v51, 0x3fb8aa3b, v51
	v_exp_f32_e32 v48, v48
	v_exp_f32_e32 v49, v49
	v_exp_f32_e32 v50, v50
	v_exp_f32_e32 v51, v51
	ds_write_b128 v103, v[48:51]
.LBB0_1007:
	s_or_b64 exec, exec, s[0:1]
	v_add_u32_e32 v57, s80, v82
	v_add_u32_e32 v56, 0x7ff, v56
	v_cndmask_b32_e64 v56, v56, v57, s[2:3]
	s_waitcnt lgkmcnt(0)
	s_barrier
	ds_read_b128 v[58:61], v83
	ds_read_b128 v[62:65], v88
	ds_read_b128 v[48:51], v83 offset:9216
	s_nop 0
	ds_read_b128 v[66:69], v85
	ds_read_b128 v[52:55], v88 offset:9216
	v_lshrrev_b32_e32 v57, 6, v56
	v_and_b32_e32 v56, 63, v56
	v_cndmask_b32_e64 v56, v56, v57, s[6:7]
	v_lshl_or_b32 v57, v56, 6, v112
	s_nop 0
	v_add_u32_e32 v243, s81, v57
	ds_read_b128 v[122:125], v243
	ds_read_b128 v[118:121], v250 offset:16
	v_add_u32_e32 v75, s81, v57
	s_add_i32 s0, 0, 0x1f600
	v_add_u32_e32 v242, s0, v57
	ds_read_b128 v[126:129], v242
	v_add_u32_e32 v79, s0, v57
	s_waitcnt lgkmcnt(6)
	v_cvt_f32_f16_sdwa v137, v62 dst_sel:DWORD dst_unused:UNUSED_PAD src0_sel:WORD_1
	v_cvt_f32_f16_e32 v136, v62
	v_or_b32_e32 v57, 16, v57
	v_cvt_f32_f16_sdwa v135, v58 dst_sel:DWORD dst_unused:UNUSED_PAD src0_sel:WORD_1
	v_cvt_f32_f16_e32 v134, v58
	s_nop 0
	s_waitcnt lgkmcnt(4)
	v_mul_f32_e32 v56, 0x3fb8aa3b, v66
	v_add_u32_e32 v140, s81, v57
	ds_read_b128 v[130:133], v93
	v_add_u32_e32 v141, s0, v57
	v_mul_f32_e32 v57, 0x3fb8aa3b, v67
	v_exp_f32_e32 v56, v56
	v_exp_f32_e32 v57, v57
	v_pk_mul_f32 v[136:137], v[136:137], s[72:73] op_sel_hi:[1,0]
	v_pk_mul_f32 v[134:135], v[134:135], s[72:73] op_sel_hi:[1,0]
	s_nop 0
	s_waitcnt lgkmcnt(1)
	v_pk_mul_f32 v[136:137], v[136:137], v[126:127]
	v_rcp_f32_e32 v66, v56
	v_cndmask_b32_e64 v137, v137, -v137, s[8:9]
	v_cndmask_b32_e64 v136, v136, -v136, s[8:9]
	v_pk_fma_f32 v[134:135], v[134:135], v[122:123], v[136:137]
	v_cvt_f32_f16_sdwa v137, v48 dst_sel:DWORD dst_unused:UNUSED_PAD src0_sel:WORD_1
	v_pk_mul_f32 v[138:139], v[134:135], v[56:57]
	v_cvt_f32_f16_sdwa v135, v52 dst_sel:DWORD dst_unused:UNUSED_PAD src0_sel:WORD_1
	v_cvt_f32_f16_e32 v134, v52
	v_cvt_f32_f16_e32 v136, v48
	s_nop 0
	v_rcp_f32_e32 v67, v57
	v_pk_mul_f32 v[126:127], v[126:127], v[134:135]
	v_add3_u32 v52, v72, v89, v247
	v_cndmask_b32_e64 v127, v127, -v127, s[8:9]
	v_cndmask_b32_e64 v126, v126, -v126, s[8:9]
	v_pk_fma_f32 v[122:123], v[122:123], v[136:137], v[126:127]
	ds_read_b128 v[134:137], v94
	v_pk_mul_f32 v[126:127], v[122:123], v[66:67]
	v_cvt_f32_f16_e32 v58, v63
	s_nop 0
	s_waitcnt lgkmcnt(1)
	v_fma_mixlo_f16 v48, v130, v126, 0
	ds_write_b16 v52, v48 offset:46080
	v_fma_mixlo_f16 v48, v131, v127, 0
	ds_write_b16 v113, v48 offset:46080
	v_mul_f32_e32 v48, 0x3fb8aa3b, v68
	v_exp_f32_e32 v66, v48
	v_mul_f32_e32 v48, 0x3fb8aa3b, v69
	v_cvt_f32_f16_sdwa v69, v59 dst_sel:DWORD dst_unused:UNUSED_PAD src0_sel:WORD_1
	v_cvt_f32_f16_e32 v68, v59
	v_cvt_f32_f16_sdwa v59, v63 dst_sel:DWORD dst_unused:UNUSED_PAD src0_sel:WORD_1
	v_exp_f32_e32 v67, v48
	v_cvt_f32_f16_e32 v52, v49
	v_pk_mul_f32 v[68:69], v[68:69], s[72:73] op_sel_hi:[1,0]
	v_pk_mul_f32 v[58:59], v[58:59], s[72:73] op_sel_hi:[1,0]
	v_rcp_f32_e32 v62, v66
	v_pk_mul_f32 v[58:59], v[58:59], v[128:129]
	v_rcp_f32_e32 v63, v67
	v_cndmask_b32_e64 v59, v59, -v59, s[8:9]
	v_cndmask_b32_e64 v58, v58, -v58, s[8:9]
	v_pk_fma_f32 v[58:59], v[68:69], v[124:125], v[58:59]
	v_cvt_pk_f16_f32 v56, v138, v139
	v_pk_mul_f32 v[130:131], v[58:59], v[66:67]
	v_cvt_f32_f16_sdwa v59, v53 dst_sel:DWORD dst_unused:UNUSED_PAD src0_sel:WORD_1
	v_cvt_f32_f16_e32 v58, v53
	v_cvt_f32_f16_sdwa v53, v49 dst_sel:DWORD dst_unused:UNUSED_PAD src0_sel:WORD_1
	v_cvt_pk_f16_f32 v57, v130, v131
	v_pk_mul_f32 v[48:49], v[128:129], v[58:59]
	s_nop 0
	v_cndmask_b32_e64 v49, v49, -v49, s[8:9]
	v_cndmask_b32_e64 v48, v48, -v48, s[8:9]
	v_pk_fma_f32 v[48:49], v[124:125], v[52:53], v[48:49]
	v_cvt_f32_f16_sdwa v59, v60 dst_sel:DWORD dst_unused:UNUSED_PAD src0_sel:WORD_1
	v_pk_mul_f32 v[48:49], v[48:49], v[62:63]
	v_cvt_f32_f16_sdwa v63, v64 dst_sel:DWORD dst_unused:UNUSED_PAD src0_sel:WORD_1
	v_fma_mixlo_f16 v52, v132, v48, 0
	ds_write_b16 v113, v52 offset:46224
	v_fma_mixlo_f16 v52, v133, v49, 0
	ds_write_b16 v113, v52 offset:46368
	ds_read_b128 v[122:125], v141
	ds_read_b128 v[66:69], v140
	v_cvt_f32_f16_e32 v62, v64
	v_cvt_f32_f16_e32 v58, v60
	v_mul_f32_e32 v52, 0x3fb8aa3b, v118
	v_mul_f32_e32 v53, 0x3fb8aa3b, v119
	v_pk_mul_f32 v[62:63], v[62:63], s[72:73] op_sel_hi:[1,0]
	v_exp_f32_e32 v52, v52
	s_nop 0
	s_waitcnt lgkmcnt(1)
	v_pk_mul_f32 v[62:63], v[62:63], v[122:123]
	v_exp_f32_e32 v53, v53
	v_pk_mul_f32 v[58:59], v[58:59], s[72:73] op_sel_hi:[1,0]
	v_cndmask_b32_e64 v63, v63, -v63, s[8:9]
	v_cndmask_b32_e64 v62, v62, -v62, s[8:9]
	s_waitcnt lgkmcnt(0)
	v_pk_fma_f32 v[58:59], v[58:59], v[66:67], v[62:63]
	v_cvt_f32_f16_sdwa v63, v54 dst_sel:DWORD dst_unused:UNUSED_PAD src0_sel:WORD_1
	v_cvt_f32_f16_e32 v62, v54
	v_cvt_f32_f16_sdwa v129, v50 dst_sel:DWORD dst_unused:UNUSED_PAD src0_sel:WORD_1
	v_cvt_f32_f16_e32 v128, v50
	v_rcp_f32_e32 v118, v52
	v_rcp_f32_e32 v119, v53
	v_pk_mul_f32 v[62:63], v[122:123], v[62:63]
	v_cvt_f32_f16_e32 v60, v65
	v_cndmask_b32_e64 v63, v63, -v63, s[8:9]
	v_cndmask_b32_e64 v62, v62, -v62, s[8:9]
	v_pk_fma_f32 v[62:63], v[66:67], v[128:129], v[62:63]
	v_pk_mul_f32 v[52:53], v[58:59], v[52:53]
	v_pk_mul_f32 v[66:67], v[62:63], v[118:119]
	v_cvt_f32_f16_sdwa v119, v61 dst_sel:DWORD dst_unused:UNUSED_PAD src0_sel:WORD_1
	v_fma_mixlo_f16 v50, v134, v66, 0
	v_cvt_f32_f16_e32 v118, v61
	v_cvt_f32_f16_sdwa v61, v65 dst_sel:DWORD dst_unused:UNUSED_PAD src0_sel:WORD_1
	ds_write_b16 v113, v50 offset:46512
	v_fma_mixlo_f16 v50, v135, v67, 0
	ds_write_b16 v113, v50 offset:46656
	v_mul_f32_e32 v50, 0x3fb8aa3b, v120
	v_exp_f32_e32 v62, v50
	v_mul_f32_e32 v50, 0x3fb8aa3b, v121
	v_exp_f32_e32 v63, v50
	v_pk_mul_f32 v[60:61], v[60:61], s[72:73] op_sel_hi:[1,0]
	v_pk_mul_f32 v[118:119], v[118:119], s[72:73] op_sel_hi:[1,0]
	v_pk_mul_f32 v[60:61], v[60:61], v[124:125]
	v_rcp_f32_e32 v64, v62
	v_cndmask_b32_e64 v61, v61, -v61, s[8:9]
	v_cndmask_b32_e64 v60, v60, -v60, s[8:9]
	v_pk_fma_f32 v[60:61], v[118:119], v[68:69], v[60:61]
	v_rcp_f32_e32 v65, v63
	v_pk_mul_f32 v[60:61], v[60:61], v[62:63]
	v_bfe_u32 v62, v131, 16, 1
	v_bfe_u32 v63, v130, 16, 1
	v_bfe_u32 v75, v53, 16, 1
	v_bfe_u32 v79, v52, 16, 1
	v_cvt_pk_f16_f32 v58, v52, v53
	v_bfe_u32 v50, v61, 16, 1
	v_add3_u32 v120, v130, v63, s34
	v_add3_u32 v62, v131, v62, s34
	v_add3_u32 v52, v52, v79, s34
	v_add3_u32 v53, v53, v75, s34
	v_cvt_pk_f16_f32 v59, v60, v61
	v_bfe_u32 v54, v60, 16, 1
	v_add3_u32 v50, v61, v50, s34
	v_perm_b32 v61, v62, v120, s35
	v_perm_b32 v62, v53, v52, s35
	v_cvt_f32_f16_sdwa v53, v55 dst_sel:DWORD dst_unused:UNUSED_PAD src0_sel:WORD_1
	v_cvt_f32_f16_e32 v52, v55
	v_add3_u32 v54, v60, v54, s34
	v_perm_b32 v63, v50, v54, s35
	v_cvt_f32_f16_sdwa v55, v51 dst_sel:DWORD dst_unused:UNUSED_PAD src0_sel:WORD_1
	v_cvt_f32_f16_e32 v54, v51
	v_pk_mul_f32 v[50:51], v[124:125], v[52:53]
	v_bfe_u32 v118, v139, 16, 1
	v_cndmask_b32_e64 v51, v51, -v51, s[8:9]
	v_cndmask_b32_e64 v50, v50, -v50, s[8:9]
	v_pk_fma_f32 v[50:51], v[68:69], v[54:55], v[50:51]
	v_bfe_u32 v119, v138, 16, 1
	v_pk_mul_f32 v[52:53], v[50:51], v[64:65]
	v_bfe_u32 v51, v48, 16, 1
	v_fma_mixlo_f16 v50, v136, v52, 0
	v_bfe_u32 v54, v53, 16, 1
	v_bfe_u32 v55, v52, 16, 1
	ds_write_b16 v113, v50 offset:46800
	v_bfe_u32 v50, v49, 16, 1
	v_bfe_u32 v64, v67, 16, 1
	v_bfe_u32 v65, v66, 16, 1
	v_bfe_u32 v68, v127, 16, 1
	v_bfe_u32 v69, v126, 16, 1
	v_add3_u32 v52, v52, v55, s34
	v_add3_u32 v54, v53, v54, s34
	v_add3_u32 v60, v138, v119, s34
	v_add3_u32 v118, v139, v118, s34
	v_add3_u32 v48, v48, v51, s34
	v_add3_u32 v49, v49, v50, s34
	v_add3_u32 v55, v126, v69, s34
	v_add3_u32 v68, v127, v68, s34
	v_add3_u32 v50, v66, v65, s34
	v_add3_u32 v64, v67, v64, s34
	v_perm_b32 v51, v54, v52, s35
	v_fma_mixlo_f16 v52, v137, v53, 0
	v_perm_b32 v60, v118, v60, s35
	v_perm_b32 v49, v49, v48, s35
	v_perm_b32 v50, v64, v50, s35
	v_perm_b32 v48, v68, v55, s35
	ds_write_b16 v113, v52 offset:46944
	ds_write_b128 v83, v[60:63] offset:18432
	ds_write_b128 v83, v[48:51] offset:27648
	ds_write_b128 v83, v[56:59] offset:36864
	v_add_u32_e32 v56, v73, v0
	s_nop 0
	s_barrier
	v_add_u32_e32 v243, v86, v95
	ds_read_b128 v[52:55], v243 offset:36864
	ds_read_b128 v[64:67], v56 offset:64
	ds_read_b128 v[162:165], v243 offset:36928
	ds_read_b128 v[60:63], v243 offset:39168
	ds_read_b128 v[118:121], v243 offset:39232
	ds_read_b128 v[122:125], v243 offset:41472
	ds_read_b128 v[126:129], v243 offset:41536
	ds_read_b128 v[130:133], v243 offset:43776
	ds_read_b128 v[134:137], v243 offset:43840
	ds_read_b128 v[48:51], v56
	v_add_u32_e32 v68, v86, v95
	s_waitcnt lgkmcnt(0)
	v_mfma_f32_16x16x32_f16 v[52:55], v[48:51], v[52:55], 0
	v_add_u32_e32 v75, v92, v0
	v_mov_b32_e32 v68, 0
	v_mov_b32_e32 v69, 0
	s_nop 0
	v_mfma_f32_16x16x32_f16 v[60:63], v[48:51], v[60:63], 0
	s_nop 0
	v_mfma_f32_16x16x32_f16 v[122:125], v[48:51], v[122:125], 0
	s_nop 0
	v_mfma_f32_16x16x32_f16 v[48:51], v[48:51], v[130:133], 0
	v_mfma_f32_16x16x32_f16 v[52:55], v[64:67], v[162:165], v[52:55]
	v_mfma_f32_16x16x32_f16 v[56:59], v[64:67], v[118:121], v[60:63]
	v_mfma_f32_16x16x32_f16 v[60:63], v[64:67], v[126:129], v[122:125]
	s_nop 0
	v_mfma_f32_16x16x32_f16 v[48:51], v[64:67], v[134:137], v[48:51]
	v_mov_b32_e32 v64, 0
	v_mov_b32_e32 v66, 0
	v_mov_b32_e32 v67, 0
	s_and_saveexec_b64 s[0:1], s[10:11]
	s_cbranch_execz .LBB0_1009
	v_add_u32_e32 v243, v86, v98
	ds_read_b128 v[66:69], v75 offset:18432
	ds_read_b128 v[118:121], v243 offset:27648
	v_add_u32_e32 v65, v86, v98
	s_nop 0
	s_nop 0
	s_nop 0
	s_waitcnt lgkmcnt(0)
	v_mfma_f32_16x16x32_bf16 v[66:69], v[118:121], v[66:69], 0
	ds_read_b128 v[122:125], v65 offset:27712
	ds_read_b128 v[118:121], v75 offset:18496
	s_nop 0
	s_nop 0
	s_waitcnt lgkmcnt(0)
	v_mfma_f32_16x16x32_bf16 v[66:69], v[122:125], v[118:121], v[66:69]
.LBB0_1009:
	s_or_b64 exec, exec, s[0:1]
	s_nop 6
	v_cvt_f16_f32_e32 v65, v66
	v_cvt_f16_f32_e32 v66, v67
	v_cvt_f16_f32_e32 v67, v68
	v_cvt_f16_f32_e32 v68, v69
	v_cndmask_b32_e64 v65, v65, 0, s[14:15]
	v_cndmask_b32_e64 v66, 0, v66, s[16:17]
	v_cndmask_b32_e64 v67, v67, 0, s[18:19]
	v_cndmask_b32_e64 v68, v68, 0, s[20:21]
	v_pack_b32_f16 v67, v67, v68
	v_pack_b32_f16 v66, v65, v66
	ds_write_b64 v114, v[66:67]
	v_mov_b32_e32 v65, 0
	v_mov_b32_e32 v66, 0
	v_mov_b32_e32 v67, 0
	s_and_saveexec_b64 s[0:1], s[12:13]
	s_cbranch_execz .LBB0_994
	v_add_u32_e32 v243, v86, v100
	ds_read_b128 v[64:67], v75 offset:18432
	ds_read_b128 v[118:121], v243 offset:27648
	v_add_u32_e32 v68, v86, v100
	s_nop 0
	s_nop 0
	s_nop 0
	s_waitcnt lgkmcnt(0)
	v_mfma_f32_16x16x32_bf16 v[64:67], v[118:121], v[64:67], 0
	ds_read_b128 v[122:125], v68 offset:27712
	ds_read_b128 v[118:121], v75 offset:18496
	s_nop 0
	s_nop 0
	s_waitcnt lgkmcnt(0)
	v_mfma_f32_16x16x32_bf16 v[64:67], v[122:125], v[118:121], v[64:67]
	s_branch .LBB0_994

.LBB0_1028:
	s_andn2_b64 vcc, exec, s[24:25]
	s_mov_b64 s[26:27], -1
	s_cbranch_vccnz .LBB0_1036
	s_and_b32 s26, s76, 1
	v_lshl_add_u32 v0, s26, 13, v229
	ds_read2_b64 v[36:39], v0 offset1:32
	v_mad_u32_u24 v2, s26, v167, v230
	s_waitcnt lgkmcnt(0)
	v_pk_mul_f32 v[66:67], v[36:37], v[38:39]
	v_xor_b32_e32 v90, 16, v0
	ds_read2_b64 v[38:41], v90 offset0:64 offset1:96
	s_waitcnt lgkmcnt(0)
	v_pk_mul_f32 v[64:65], v[66:67], v[38:39]
	s_nop 0
	v_pk_mul_f32 v[60:61], v[64:65], v[40:41]
	v_xor_b32_e32 v91, 32, v0
	ds_read2_b64 v[38:41], v91 offset0:128 offset1:160
	s_waitcnt lgkmcnt(0)
	v_pk_mul_f32 v[54:55], v[60:61], v[38:39]
	s_nop 0
	v_pk_mul_f32 v[48:49], v[54:55], v[40:41]
	v_xor_b32_e32 v92, 48, v0
	ds_read2_b64 v[38:41], v92 offset0:192 offset1:224
	v_add_u32_e32 v0, 0x800, v0
	v_xor_b32_e32 v91, 32, v0
	ds_read2_b64 v[68:71], v91 offset0:128 offset1:160
	s_waitcnt lgkmcnt(1)
	v_pk_mul_f32 v[44:45], v[48:49], v[38:39]
	s_nop 0
	v_pk_mul_f32 v[38:39], v[44:45], v[40:41]
	ds_read2_b64 v[40:43], v0 offset1:32
	s_waitcnt lgkmcnt(0)
	v_pk_mul_f32 v[58:59], v[38:39], v[40:41]
	s_nop 0
	v_pk_mul_f32 v[50:51], v[58:59], v[42:43]
	v_xor_b32_e32 v90, 16, v0
	ds_read2_b64 v[40:43], v90 offset0:64 offset1:96
	s_waitcnt lgkmcnt(0)
	v_pk_mul_f32 v[46:47], v[50:51], v[40:41]
	s_nop 0
	v_pk_mul_f32 v[42:43], v[46:47], v[42:43]
	v_rcp_f32_e32 v40, v38
	v_pk_mul_f32 v[62:63], v[42:43], v[68:69]
	v_rcp_f32_e32 v41, v39
	v_pk_mul_f32 v[56:57], v[62:63], v[70:71]
	v_xor_b32_e32 v92, 48, v0
	ds_read2_b64 v[68:71], v92 offset0:192 offset1:224
	s_waitcnt lgkmcnt(0)
	v_pk_mul_f32 v[52:53], v[56:57], v[68:69]
	s_nop 0
	v_pk_mul_f32 v[0:1], v[52:53], v[70:71]
	s_and_saveexec_b64 s[26:27], s[4:5]
	s_cbranch_execz .LBB0_1031
	v_lshl_add_u32 v243, v175, 1, v2
	v_lshl_add_u32 v242, v182, 1, v2
	ds_read2st64_b32 v[72:73], v243 offset0:96 offset1:112
	ds_read2st64_b32 v[68:69], v243 offset0:64 offset1:80
	ds_read_b32 v84, v243 offset:32768
	ds_read2st64_b32 v[162:163], v242 offset0:64 offset1:80
	ds_read2st64_b32 v[164:165], v242 offset0:96 offset1:112
	v_lshl_add_u32 v74, v175, 1, v2
	s_nop 0
	s_nop 0
	v_rcp_f32_e32 v70, v36
	v_rcp_f32_e32 v71, v37
	s_waitcnt lgkmcnt(4)
	v_cvt_f32_f16_e32 v78, v73
	v_cvt_f32_f16_sdwa v79, v73 dst_sel:DWORD dst_unused:UNUSED_PAD src0_sel:WORD_1
	s_waitcnt lgkmcnt(3)
	v_cvt_f32_f16_e32 v74, v68
	v_cvt_f32_f16_sdwa v75, v68 dst_sel:DWORD dst_unused:UNUSED_PAD src0_sel:WORD_1
	v_cvt_f32_f16_e32 v76, v72
	v_cvt_f32_f16_sdwa v77, v72 dst_sel:DWORD dst_unused:UNUSED_PAD src0_sel:WORD_1
	v_cvt_f32_f16_e32 v72, v69
	v_cvt_f32_f16_sdwa v73, v69 dst_sel:DWORD dst_unused:UNUSED_PAD src0_sel:WORD_1
	v_pk_mul_f32 v[78:79], v[36:37], v[78:79]
	v_pk_mul_f32 v[76:77], v[70:71], v[76:77]
	v_pk_mul_f32 v[70:71], v[70:71], v[74:75]
	v_pk_mul_f32 v[72:73], v[40:41], v[72:73]
	v_pk_mul_f32 v[74:75], v[40:41], v[78:79]
	v_cvt_pk_f16_f32 v68, v78, v79
	v_pk_mul_f32 v[80:81], v[38:39], v[76:77]
	v_pk_mul_f32 v[82:83], v[38:39], v[70:71]
	ds_write2st64_b32 v181, v69, v68 offset1:18
	v_cvt_pk_f16_f32 v68, v72, v73
	v_cvt_pk_f16_f32 v69, v74, v75
	v_pk_mul_f32 v[76:77], v[0:1], v[76:77]
	ds_write2st64_b32 v181, v68, v69 offset0:36 offset1:54
	v_cvt_pk_f16_f32 v68, v80, v81
	v_cvt_pk_f16_f32 v69, v82, v83
	v_lshl_add_u32 v243, v184, 1, v2
	ds_read_b32 v82, v242 offset:32768
	ds_read2st64_b32 v[234:235], v243 offset0:64 offset1:80
	ds_read2st64_b32 v[236:237], v243 offset0:96 offset1:112
	ds_write2st64_b32 v181, v68, v69 offset0:72 offset1:90
	v_cvt_f16_f32_e32 v68, v76
	v_pk_mul_f32 v[70:71], v[0:1], v[70:71]
	v_cvt_f16_f32_e32 v69, v77
	v_cvt_f16_f32_e32 v70, v70
	v_cvt_f16_f32_e32 v71, v71
	ds_write_b16 v176, v68
	ds_write_b16 v176, v69 offset:40
	ds_write_b16 v176, v70 offset:5120
	ds_write_b16 v176, v71 offset:5160
	s_waitcnt lgkmcnt(12)
	ds_write_b16 v176, v84 offset:10240
	v_lshl_add_u32 v74, v182, 1, v2
	v_rcp_f32_e32 v70, v66
	v_rcp_f32_e32 v71, v67
	s_waitcnt lgkmcnt(12)
	v_cvt_f32_f16_e32 v76, v163
	v_cvt_f32_f16_sdwa v77, v163 dst_sel:DWORD dst_unused:UNUSED_PAD src0_sel:WORD_1
	s_waitcnt lgkmcnt(11)
	v_cvt_f32_f16_e32 v80, v165
	v_cvt_f32_f16_sdwa v81, v165 dst_sel:DWORD dst_unused:UNUSED_PAD src0_sel:WORD_1
	v_cvt_f32_f16_e32 v74, v162
	v_cvt_f32_f16_e32 v78, v164
	v_cvt_f32_f16_sdwa v79, v164 dst_sel:DWORD dst_unused:UNUSED_PAD src0_sel:WORD_1
	v_cvt_f32_f16_sdwa v75, v162 dst_sel:DWORD dst_unused:UNUSED_PAD src0_sel:WORD_1
	v_pk_mul_f32 v[36:37], v[36:37], v[76:77]
	v_pk_mul_f32 v[68:69], v[66:67], v[80:81]
	v_pk_mul_f32 v[72:73], v[70:71], v[78:79]
	v_pk_mul_f32 v[70:71], v[70:71], v[74:75]
	v_pk_mul_f32 v[74:75], v[40:41], v[36:37]
	v_pk_mul_f32 v[76:77], v[40:41], v[68:69]
	v_cvt_pk_f16_f32 v36, v36, v37
	v_cvt_pk_f16_f32 v37, v68, v69
	v_pk_mul_f32 v[78:79], v[38:39], v[72:73]
	v_pk_mul_f32 v[80:81], v[38:39], v[70:71]
	ds_write2st64_b32 v183, v36, v37 offset1:18
	v_cvt_pk_f16_f32 v36, v74, v75
	v_cvt_pk_f16_f32 v37, v76, v77
	v_pk_mul_f32 v[72:73], v[0:1], v[72:73]
	ds_write2st64_b32 v183, v36, v37 offset0:36 offset1:54
	v_cvt_pk_f16_f32 v36, v78, v79
	v_cvt_pk_f16_f32 v37, v80, v81
	v_lshl_add_u32 v242, v186, 1, v2
	ds_read_b32 v80, v243 offset:32768
	ds_read2st64_b32 v[240:241], v242 offset0:64 offset1:80
	s_waitcnt lgkmcnt(14)
	ds_read2st64_b32 v[164:165], v242 offset0:96 offset1:112
	s_waitcnt lgkmcnt(14)
	ds_write2st64_b32 v183, v36, v37 offset0:72 offset1:90
	v_cvt_f16_f32_e32 v36, v72
	v_pk_mul_f32 v[70:71], v[0:1], v[70:71]
	v_cvt_f16_f32_e32 v37, v73
	v_cvt_f16_f32_e32 v68, v70
	v_cvt_f16_f32_e32 v69, v71
	s_waitcnt lgkmcnt(14)
	ds_write_b16 v176, v36 offset:2
	s_waitcnt lgkmcnt(14)
	ds_write_b16 v176, v37 offset:42
	s_waitcnt lgkmcnt(14)
	ds_write_b16 v176, v68 offset:5122
	s_waitcnt lgkmcnt(14)
	ds_write_b16 v176, v69 offset:5162
	s_waitcnt lgkmcnt(14)
	ds_write_b16 v176, v82 offset:10242
	v_lshl_add_u32 v72, v184, 1, v2
	v_rcp_f32_e32 v68, v64
	v_rcp_f32_e32 v69, v65
	v_cvt_f32_f16_e32 v74, v235
	v_cvt_f32_f16_sdwa v75, v235 dst_sel:DWORD dst_unused:UNUSED_PAD src0_sel:WORD_1
	v_cvt_f32_f16_e32 v78, v237
	v_cvt_f32_f16_sdwa v79, v237 dst_sel:DWORD dst_unused:UNUSED_PAD src0_sel:WORD_1
	v_cvt_f32_f16_e32 v72, v234
	v_cvt_f32_f16_e32 v76, v236
	v_cvt_f32_f16_sdwa v77, v236 dst_sel:DWORD dst_unused:UNUSED_PAD src0_sel:WORD_1
	v_cvt_f32_f16_sdwa v73, v234 dst_sel:DWORD dst_unused:UNUSED_PAD src0_sel:WORD_1
	v_pk_mul_f32 v[36:37], v[66:67], v[74:75]
	v_pk_mul_f32 v[66:67], v[64:65], v[78:79]
	v_pk_mul_f32 v[70:71], v[68:69], v[76:77]
	v_pk_mul_f32 v[68:69], v[68:69], v[72:73]
	v_pk_mul_f32 v[72:73], v[40:41], v[36:37]
	v_pk_mul_f32 v[74:75], v[40:41], v[66:67]
	v_cvt_pk_f16_f32 v36, v36, v37
	v_cvt_pk_f16_f32 v37, v66, v67
	v_pk_mul_f32 v[76:77], v[38:39], v[70:71]
	v_pk_mul_f32 v[78:79], v[38:39], v[68:69]
	s_waitcnt lgkmcnt(14)
	ds_write2st64_b32 v185, v36, v37 offset1:18
	v_cvt_pk_f16_f32 v36, v72, v73
	v_cvt_pk_f16_f32 v37, v74, v75
	v_pk_mul_f32 v[70:71], v[0:1], v[70:71]
	s_waitcnt lgkmcnt(14)
	ds_write2st64_b32 v185, v36, v37 offset0:36 offset1:54
	v_cvt_pk_f16_f32 v36, v76, v77
	v_cvt_pk_f16_f32 v37, v78, v79
	s_waitcnt lgkmcnt(14)
	ds_read_b32 v78, v242 offset:32768
	s_waitcnt lgkmcnt(14)
	ds_write2st64_b32 v185, v36, v37 offset0:72 offset1:90
	v_cvt_f16_f32_e32 v36, v70
	v_pk_mul_f32 v[68:69], v[0:1], v[68:69]
	v_cvt_f16_f32_e32 v37, v71
	v_cvt_f16_f32_e32 v66, v68
	v_cvt_f16_f32_e32 v67, v69
	s_waitcnt lgkmcnt(14)
	ds_write_b16 v176, v36 offset:4
	s_waitcnt lgkmcnt(14)
	ds_write_b16 v176, v37 offset:44
	s_waitcnt lgkmcnt(14)
	ds_write_b16 v176, v66 offset:5124
	s_waitcnt lgkmcnt(14)
	ds_write_b16 v176, v67 offset:5164
	s_waitcnt lgkmcnt(14)
	ds_write_b16 v176, v80 offset:10244
	v_lshl_add_u32 v70, v186, 1, v2
	v_rcp_f32_e32 v66, v60
	v_rcp_f32_e32 v67, v61
	v_cvt_f32_f16_e32 v72, v241
	v_cvt_f32_f16_sdwa v73, v241 dst_sel:DWORD dst_unused:UNUSED_PAD src0_sel:WORD_1
	v_cvt_f32_f16_e32 v76, v165
	v_cvt_f32_f16_sdwa v77, v165 dst_sel:DWORD dst_unused:UNUSED_PAD src0_sel:WORD_1
	v_cvt_f32_f16_e32 v70, v240
	v_cvt_f32_f16_e32 v74, v164
	v_cvt_f32_f16_sdwa v75, v164 dst_sel:DWORD dst_unused:UNUSED_PAD src0_sel:WORD_1
	v_cvt_f32_f16_sdwa v71, v240 dst_sel:DWORD dst_unused:UNUSED_PAD src0_sel:WORD_1
	v_pk_mul_f32 v[36:37], v[64:65], v[72:73]
	v_pk_mul_f32 v[64:65], v[60:61], v[76:77]
	v_pk_mul_f32 v[68:69], v[66:67], v[74:75]
	v_pk_mul_f32 v[66:67], v[66:67], v[70:71]
	v_pk_mul_f32 v[70:71], v[40:41], v[36:37]
	v_pk_mul_f32 v[72:73], v[40:41], v[64:65]
	v_cvt_pk_f16_f32 v36, v36, v37
	v_cvt_pk_f16_f32 v37, v64, v65
	v_pk_mul_f32 v[74:75], v[38:39], v[68:69]
	v_pk_mul_f32 v[76:77], v[38:39], v[66:67]
	s_waitcnt lgkmcnt(14)
	ds_write2st64_b32 v187, v36, v37 offset1:18
	v_cvt_pk_f16_f32 v36, v70, v71
	v_cvt_pk_f16_f32 v37, v72, v73
	v_pk_mul_f32 v[68:69], v[0:1], v[68:69]
	s_waitcnt lgkmcnt(14)
	ds_write2st64_b32 v187, v36, v37 offset0:36 offset1:54
	v_cvt_pk_f16_f32 v36, v74, v75
	v_cvt_pk_f16_f32 v37, v76, v77
	s_waitcnt lgkmcnt(14)
	ds_write2st64_b32 v187, v36, v37 offset0:72 offset1:90
	v_cvt_f16_f32_e32 v36, v68
	v_pk_mul_f32 v[66:67], v[0:1], v[66:67]
	v_cvt_f16_f32_e32 v37, v69
	v_cvt_f16_f32_e32 v64, v66
	v_cvt_f16_f32_e32 v65, v67
	s_waitcnt lgkmcnt(14)
	ds_write_b16 v176, v36 offset:6
	s_waitcnt lgkmcnt(14)
	ds_write_b16 v176, v37 offset:46
	s_waitcnt lgkmcnt(14)
	ds_write_b16 v176, v64 offset:5126
	s_waitcnt lgkmcnt(14)
	ds_write_b16 v176, v65 offset:5166
	s_nop 0
	s_waitcnt lgkmcnt(13)
	ds_write_b16 v176, v78 offset:10246
	v_perm_b32 v36, v82, v84, s35
	v_perm_b32 v37, v78, v80, s35
	ds_write_b64 v176, v[36:37] offset:10280

.LBB0_1041:
	v_cmp_lt_i32_e32 vcc, 2, v174
	s_and_saveexec_b64 s[28:29], vcc
	s_xor_b64 s[28:29], exec, s[28:29]
	s_cbranch_execz .LBB0_1043
	v_lshl_add_u32 v243, v204, 1, v2
	v_lshl_add_u32 v242, v206, 1, v2
	ds_read2st64_b32 v[36:37], v243 offset0:64 offset1:80
	ds_read2st64_b32 v[46:47], v243 offset0:96 offset1:112
	ds_read_b32 v60, v243 offset:32768
	ds_read2st64_b32 v[162:163], v242 offset0:64 offset1:80
	ds_read2st64_b32 v[164:165], v242 offset0:96 offset1:112
	ds_read_b32 v61, v242 offset:32768
	v_lshl_add_u32 v48, v204, 1, v2
	s_nop 0
	s_nop 0
	v_rcp_f32_e32 v44, v62
	v_rcp_f32_e32 v45, v63
	v_lshl_add_u32 v243, v208, 1, v2
	ds_read2st64_b32 v[234:235], v243 offset0:64 offset1:80
	s_waitcnt lgkmcnt(5)
	v_cvt_f32_f16_e32 v58, v47
	v_cvt_f32_f16_e32 v50, v37
	v_cvt_f32_f16_sdwa v51, v37 dst_sel:DWORD dst_unused:UNUSED_PAD src0_sel:WORD_1
	ds_read2st64_b32 v[236:237], v243 offset0:96 offset1:112
	v_cvt_f32_f16_sdwa v59, v47 dst_sel:DWORD dst_unused:UNUSED_PAD src0_sel:WORD_1
	v_cvt_f32_f16_e32 v48, v36
	v_cvt_f32_f16_e32 v54, v46
	v_cvt_f32_f16_sdwa v55, v46 dst_sel:DWORD dst_unused:UNUSED_PAD src0_sel:WORD_1
	v_cvt_f32_f16_sdwa v49, v36 dst_sel:DWORD dst_unused:UNUSED_PAD src0_sel:WORD_1
	v_pk_mul_f32 v[36:37], v[42:43], v[50:51]
	v_pk_mul_f32 v[42:43], v[62:63], v[58:59]
	v_pk_mul_f32 v[46:47], v[44:45], v[54:55]
	v_pk_mul_f32 v[44:45], v[44:45], v[48:49]
	v_pk_mul_f32 v[48:49], v[40:41], v[36:37]
	v_pk_mul_f32 v[50:51], v[40:41], v[42:43]
	v_cvt_pk_f16_f32 v36, v36, v37
	v_cvt_pk_f16_f32 v37, v42, v43
	v_pk_mul_f32 v[54:55], v[38:39], v[46:47]
	v_pk_mul_f32 v[58:59], v[38:39], v[44:45]
	ds_write2st64_b32 v205, v36, v37 offset1:18
	v_cvt_pk_f16_f32 v36, v48, v49
	v_cvt_pk_f16_f32 v37, v50, v51
	v_pk_mul_f32 v[46:47], v[0:1], v[46:47]
	ds_write2st64_b32 v205, v36, v37 offset0:36 offset1:54
	v_cvt_pk_f16_f32 v36, v54, v55
	v_cvt_pk_f16_f32 v37, v58, v59
	ds_write2st64_b32 v205, v36, v37 offset0:72 offset1:90
	v_cvt_f16_f32_e32 v36, v46
	v_pk_mul_f32 v[44:45], v[0:1], v[44:45]
	v_cvt_f16_f32_e32 v37, v47
	v_cvt_f16_f32_e32 v42, v44
	v_cvt_f16_f32_e32 v43, v45
	ds_write_b16 v176, v36 offset:24
	ds_write_b16 v176, v37 offset:64
	ds_write_b16 v176, v42 offset:5144
	ds_write_b16 v176, v43 offset:5184
	s_waitcnt lgkmcnt(12)
	ds_write_b16 v176, v60 offset:10264
	v_lshl_add_u32 v46, v206, 1, v2
	v_rcp_f32_e32 v42, v56
	v_rcp_f32_e32 v43, v57
	s_waitcnt lgkmcnt(12)
	v_cvt_f32_f16_e32 v48, v163
	v_cvt_f32_f16_sdwa v49, v163 dst_sel:DWORD dst_unused:UNUSED_PAD src0_sel:WORD_1
	s_waitcnt lgkmcnt(11)
	v_cvt_f32_f16_e32 v54, v165
	v_cvt_f32_f16_sdwa v55, v165 dst_sel:DWORD dst_unused:UNUSED_PAD src0_sel:WORD_1
	v_cvt_f32_f16_e32 v46, v162
	v_cvt_f32_f16_e32 v50, v164
	v_cvt_f32_f16_sdwa v51, v164 dst_sel:DWORD dst_unused:UNUSED_PAD src0_sel:WORD_1
	v_cvt_f32_f16_sdwa v47, v162 dst_sel:DWORD dst_unused:UNUSED_PAD src0_sel:WORD_1
	v_pk_mul_f32 v[36:37], v[62:63], v[48:49]
	v_pk_mul_f32 v[44:45], v[56:57], v[54:55]
	v_pk_mul_f32 v[48:49], v[42:43], v[50:51]
	v_pk_mul_f32 v[42:43], v[42:43], v[46:47]
	v_pk_mul_f32 v[46:47], v[40:41], v[36:37]
	v_pk_mul_f32 v[50:51], v[40:41], v[44:45]
	v_cvt_pk_f16_f32 v36, v36, v37
	v_cvt_pk_f16_f32 v37, v44, v45
	v_pk_mul_f32 v[54:55], v[38:39], v[48:49]
	v_pk_mul_f32 v[58:59], v[38:39], v[42:43]
	ds_write2st64_b32 v207, v36, v37 offset1:18
	v_cvt_pk_f16_f32 v36, v46, v47
	v_cvt_pk_f16_f32 v37, v50, v51
	v_pk_mul_f32 v[48:49], v[0:1], v[48:49]
	ds_write2st64_b32 v207, v36, v37 offset0:36 offset1:54
	v_cvt_pk_f16_f32 v36, v54, v55
	v_cvt_pk_f16_f32 v37, v58, v59
	v_lshl_add_u32 v242, v210, 1, v2
	ds_read_b32 v58, v243 offset:32768
	ds_read2st64_b32 v[240:241], v242 offset0:64 offset1:80
	s_waitcnt lgkmcnt(14)
	ds_read2st64_b32 v[164:165], v242 offset0:96 offset1:112
	s_waitcnt lgkmcnt(14)
	ds_write2st64_b32 v207, v36, v37 offset0:72 offset1:90
	v_cvt_f16_f32_e32 v36, v48
	v_pk_mul_f32 v[42:43], v[0:1], v[42:43]
	v_cvt_f16_f32_e32 v37, v49
	v_cvt_f16_f32_e32 v42, v42
	v_cvt_f16_f32_e32 v43, v43
	s_waitcnt lgkmcnt(14)
	ds_write_b16 v176, v36 offset:26
	s_waitcnt lgkmcnt(14)
	ds_write_b16 v176, v37 offset:66
	s_waitcnt lgkmcnt(14)
	ds_write_b16 v176, v42 offset:5146
	s_waitcnt lgkmcnt(14)
	ds_write_b16 v176, v43 offset:5186
	s_waitcnt lgkmcnt(14)
	ds_write_b16 v176, v61 offset:10266
	v_lshl_add_u32 v46, v208, 1, v2
	v_rcp_f32_e32 v42, v52
	v_rcp_f32_e32 v43, v53
	v_lshl_add_u32 v2, v210, 1, v2
	v_cvt_f32_f16_e32 v48, v235
	v_cvt_f32_f16_sdwa v49, v235 dst_sel:DWORD dst_unused:UNUSED_PAD src0_sel:WORD_1
	v_cvt_f32_f16_e32 v54, v237
	v_cvt_f32_f16_sdwa v55, v237 dst_sel:DWORD dst_unused:UNUSED_PAD src0_sel:WORD_1
	v_cvt_f32_f16_e32 v46, v234
	v_cvt_f32_f16_e32 v50, v236
	v_cvt_f32_f16_sdwa v51, v236 dst_sel:DWORD dst_unused:UNUSED_PAD src0_sel:WORD_1
	v_cvt_f32_f16_sdwa v47, v234 dst_sel:DWORD dst_unused:UNUSED_PAD src0_sel:WORD_1
	v_pk_mul_f32 v[36:37], v[56:57], v[48:49]
	v_pk_mul_f32 v[44:45], v[52:53], v[54:55]
	v_pk_mul_f32 v[48:49], v[42:43], v[50:51]
	v_pk_mul_f32 v[42:43], v[42:43], v[46:47]
	v_pk_mul_f32 v[46:47], v[40:41], v[36:37]
	v_pk_mul_f32 v[50:51], v[40:41], v[44:45]
	v_cvt_pk_f16_f32 v36, v36, v37
	v_cvt_pk_f16_f32 v37, v44, v45
	v_pk_mul_f32 v[54:55], v[38:39], v[48:49]
	v_pk_mul_f32 v[56:57], v[38:39], v[42:43]
	s_waitcnt lgkmcnt(14)
	ds_write2st64_b32 v209, v36, v37 offset1:18
	v_cvt_pk_f16_f32 v36, v46, v47
	v_cvt_pk_f16_f32 v37, v50, v51
	v_pk_mul_f32 v[48:49], v[0:1], v[48:49]
	s_waitcnt lgkmcnt(14)
	ds_write2st64_b32 v209, v36, v37 offset0:36 offset1:54
	v_cvt_pk_f16_f32 v36, v54, v55
	v_cvt_pk_f16_f32 v37, v56, v57
	s_waitcnt lgkmcnt(14)
	ds_write2st64_b32 v209, v36, v37 offset0:72 offset1:90
	v_cvt_f16_f32_e32 v36, v48
	v_pk_mul_f32 v[42:43], v[0:1], v[42:43]
	v_cvt_f16_f32_e32 v37, v49
	v_cvt_f16_f32_e32 v42, v42
	v_cvt_f16_f32_e32 v43, v43
	s_waitcnt lgkmcnt(14)
	ds_write_b16 v176, v36 offset:28
	s_waitcnt lgkmcnt(14)
	ds_write_b16 v176, v37 offset:68
	s_waitcnt lgkmcnt(14)
	ds_write_b16 v176, v42 offset:5148
	s_waitcnt lgkmcnt(14)
	ds_write_b16 v176, v43 offset:5188
	s_waitcnt lgkmcnt(14)
	ds_write_b16 v176, v58 offset:10268
	s_waitcnt lgkmcnt(14)
	ds_read_b32 v2, v242 offset:32768
	v_rcp_f32_e32 v42, v0
	v_rcp_f32_e32 v43, v1
	v_cvt_f32_f16_e32 v48, v241
	v_cvt_f32_f16_sdwa v49, v241 dst_sel:DWORD dst_unused:UNUSED_PAD src0_sel:WORD_1
	v_cvt_f32_f16_e32 v54, v165
	v_cvt_f32_f16_sdwa v55, v165 dst_sel:DWORD dst_unused:UNUSED_PAD src0_sel:WORD_1
	v_cvt_f32_f16_e32 v46, v240
	v_cvt_f32_f16_e32 v50, v164
	v_cvt_f32_f16_sdwa v51, v164 dst_sel:DWORD dst_unused:UNUSED_PAD src0_sel:WORD_1
	v_cvt_f32_f16_sdwa v47, v240 dst_sel:DWORD dst_unused:UNUSED_PAD src0_sel:WORD_1
	v_pk_mul_f32 v[36:37], v[52:53], v[48:49]
	v_pk_mul_f32 v[44:45], v[0:1], v[54:55]
	v_pk_mul_f32 v[48:49], v[42:43], v[50:51]
	v_pk_mul_f32 v[42:43], v[42:43], v[46:47]
	v_pk_mul_f32 v[46:47], v[40:41], v[36:37]
	v_pk_mul_f32 v[40:41], v[40:41], v[44:45]
	v_cvt_pk_f16_f32 v36, v36, v37
	v_cvt_pk_f16_f32 v37, v44, v45
	v_pk_mul_f32 v[50:51], v[38:39], v[48:49]
	v_pk_mul_f32 v[38:39], v[38:39], v[42:43]
	s_waitcnt lgkmcnt(14)
	ds_write2st64_b32 v211, v36, v37 offset1:18
	v_cvt_pk_f16_f32 v36, v46, v47
	v_cvt_pk_f16_f32 v37, v40, v41
	v_pk_mul_f32 v[48:49], v[0:1], v[48:49]
	s_waitcnt lgkmcnt(14)
	ds_write2st64_b32 v211, v36, v37 offset0:36 offset1:54
	v_cvt_pk_f16_f32 v36, v50, v51
	v_cvt_pk_f16_f32 v37, v38, v39
	s_waitcnt lgkmcnt(14)
	ds_write2st64_b32 v211, v36, v37 offset0:72 offset1:90
	v_cvt_f16_f32_e32 v36, v48
	v_pk_mul_f32 v[42:43], v[0:1], v[42:43]
	v_cvt_f16_f32_e32 v37, v49
	v_cvt_f16_f32_e32 v38, v42
	v_cvt_f16_f32_e32 v39, v43
	s_waitcnt lgkmcnt(14)
	ds_write_b16 v176, v36 offset:30
	s_waitcnt lgkmcnt(14)
	ds_write_b16 v176, v37 offset:70
	s_waitcnt lgkmcnt(14)
	ds_write_b16 v176, v38 offset:5150
	s_waitcnt lgkmcnt(14)
	ds_write_b16 v176, v39 offset:5190
	s_nop 0
	s_waitcnt lgkmcnt(7)
	ds_write_b16 v176, v2 offset:10270
	v_perm_b32 v36, v61, v60, s35
	v_perm_b32 v37, v2, v58, s35
	ds_write_b64 v176, v[36:37] offset:10304
.LBB0_1043:
	s_andn2_saveexec_b64 s[28:29], s[28:29]
	s_cbranch_execz .LBB0_1045
	v_lshl_add_u32 v243, v196, 1, v2
	v_lshl_add_u32 v242, v198, 1, v2
	ds_read2st64_b32 v[36:37], v243 offset0:64 offset1:80
	ds_read2st64_b32 v[48:49], v243 offset0:96 offset1:112
	ds_read_b32 v64, v243 offset:32768
	ds_read2st64_b32 v[162:163], v242 offset0:64 offset1:80
	ds_read2st64_b32 v[164:165], v242 offset0:96 offset1:112
	v_lshl_add_u32 v52, v196, 1, v2
	s_nop 0
	s_nop 0
	s_nop 0
	v_rcp_f32_e32 v44, v58
	v_rcp_f32_e32 v45, v59
	s_waitcnt lgkmcnt(3)
	v_cvt_f32_f16_e32 v60, v49
	v_cvt_f32_f16_e32 v54, v37
	v_cvt_f32_f16_sdwa v55, v37 dst_sel:DWORD dst_unused:UNUSED_PAD src0_sel:WORD_1
	v_cvt_f32_f16_sdwa v61, v49 dst_sel:DWORD dst_unused:UNUSED_PAD src0_sel:WORD_1
	v_cvt_f32_f16_e32 v52, v36
	v_cvt_f32_f16_e32 v56, v48
	v_cvt_f32_f16_sdwa v57, v48 dst_sel:DWORD dst_unused:UNUSED_PAD src0_sel:WORD_1
	v_cvt_f32_f16_sdwa v53, v36 dst_sel:DWORD dst_unused:UNUSED_PAD src0_sel:WORD_1
	v_pk_mul_f32 v[36:37], v[38:39], v[54:55]
	v_pk_mul_f32 v[48:49], v[58:59], v[60:61]
	v_pk_mul_f32 v[54:55], v[44:45], v[56:57]
	v_pk_mul_f32 v[44:45], v[44:45], v[52:53]
	v_pk_mul_f32 v[52:53], v[40:41], v[36:37]
	v_pk_mul_f32 v[56:57], v[40:41], v[48:49]
	v_cvt_pk_f16_f32 v36, v36, v37
	v_cvt_pk_f16_f32 v37, v48, v49
	v_pk_mul_f32 v[60:61], v[38:39], v[54:55]
	v_pk_mul_f32 v[62:63], v[38:39], v[44:45]
	ds_write2st64_b32 v197, v36, v37 offset1:18
	v_cvt_pk_f16_f32 v36, v52, v53
	v_cvt_pk_f16_f32 v37, v56, v57
	v_pk_mul_f32 v[54:55], v[0:1], v[54:55]
	ds_write2st64_b32 v197, v36, v37 offset0:36 offset1:54
	v_cvt_pk_f16_f32 v36, v60, v61
	v_cvt_pk_f16_f32 v37, v62, v63
	v_lshl_add_u32 v243, v200, 1, v2
	ds_read_b32 v62, v242 offset:32768
	ds_read2st64_b32 v[234:235], v243 offset0:64 offset1:80
	ds_read2st64_b32 v[236:237], v243 offset0:96 offset1:112
	ds_write2st64_b32 v197, v36, v37 offset0:72 offset1:90
	v_cvt_f16_f32_e32 v36, v54
	v_pk_mul_f32 v[44:45], v[0:1], v[44:45]
	v_cvt_f16_f32_e32 v37, v55
	v_cvt_f16_f32_e32 v44, v44
	v_cvt_f16_f32_e32 v45, v45
	ds_write_b16 v176, v36 offset:16
	ds_write_b16 v176, v37 offset:56
	ds_write_b16 v176, v44 offset:5136
	ds_write_b16 v176, v45 offset:5176
	s_waitcnt lgkmcnt(12)
	ds_write_b16 v176, v64 offset:10256
	v_lshl_add_u32 v52, v198, 1, v2
	v_rcp_f32_e32 v44, v50
	v_rcp_f32_e32 v45, v51
	s_waitcnt lgkmcnt(12)
	v_cvt_f32_f16_e32 v54, v163
	v_cvt_f32_f16_sdwa v55, v163 dst_sel:DWORD dst_unused:UNUSED_PAD src0_sel:WORD_1
	s_waitcnt lgkmcnt(11)
	v_cvt_f32_f16_e32 v60, v165
	v_cvt_f32_f16_sdwa v61, v165 dst_sel:DWORD dst_unused:UNUSED_PAD src0_sel:WORD_1
	v_cvt_f32_f16_e32 v52, v162
	v_cvt_f32_f16_e32 v56, v164
	v_cvt_f32_f16_sdwa v57, v164 dst_sel:DWORD dst_unused:UNUSED_PAD src0_sel:WORD_1
	v_cvt_f32_f16_sdwa v53, v162 dst_sel:DWORD dst_unused:UNUSED_PAD src0_sel:WORD_1
	v_pk_mul_f32 v[36:37], v[58:59], v[54:55]
	v_pk_mul_f32 v[48:49], v[50:51], v[60:61]
	v_pk_mul_f32 v[54:55], v[44:45], v[56:57]
	v_pk_mul_f32 v[44:45], v[44:45], v[52:53]
	v_pk_mul_f32 v[52:53], v[40:41], v[36:37]
	v_pk_mul_f32 v[56:57], v[40:41], v[48:49]
	v_cvt_pk_f16_f32 v36, v36, v37
	v_cvt_pk_f16_f32 v37, v48, v49
	v_pk_mul_f32 v[58:59], v[38:39], v[54:55]
	v_pk_mul_f32 v[60:61], v[38:39], v[44:45]
	ds_write2st64_b32 v199, v36, v37 offset1:18
	v_cvt_pk_f16_f32 v36, v52, v53
	v_cvt_pk_f16_f32 v37, v56, v57
	v_pk_mul_f32 v[54:55], v[0:1], v[54:55]
	ds_write2st64_b32 v199, v36, v37 offset0:36 offset1:54
	v_cvt_pk_f16_f32 v36, v58, v59
	v_cvt_pk_f16_f32 v37, v60, v61
	v_lshl_add_u32 v242, v202, 1, v2
	ds_read_b32 v60, v243 offset:32768
	ds_read2st64_b32 v[240:241], v242 offset0:64 offset1:80
	s_waitcnt lgkmcnt(14)
	ds_read2st64_b32 v[164:165], v242 offset0:96 offset1:112
	s_waitcnt lgkmcnt(14)
	ds_write2st64_b32 v199, v36, v37 offset0:72 offset1:90
	v_cvt_f16_f32_e32 v36, v54
	v_pk_mul_f32 v[44:45], v[0:1], v[44:45]
	v_cvt_f16_f32_e32 v37, v55
	v_cvt_f16_f32_e32 v44, v44
	v_cvt_f16_f32_e32 v45, v45
	s_waitcnt lgkmcnt(14)
	ds_write_b16 v176, v36 offset:18
	s_waitcnt lgkmcnt(14)
	ds_write_b16 v176, v37 offset:58
	s_waitcnt lgkmcnt(14)
	ds_write_b16 v176, v44 offset:5138
	s_waitcnt lgkmcnt(14)
	ds_write_b16 v176, v45 offset:5178
	s_waitcnt lgkmcnt(14)
	ds_write_b16 v176, v62 offset:10258
	v_lshl_add_u32 v52, v200, 1, v2
	v_rcp_f32_e32 v44, v46
	v_rcp_f32_e32 v45, v47
	v_lshl_add_u32 v2, v202, 1, v2
	v_cvt_f32_f16_e32 v54, v235
	v_cvt_f32_f16_sdwa v55, v235 dst_sel:DWORD dst_unused:UNUSED_PAD src0_sel:WORD_1
	v_cvt_f32_f16_e32 v58, v237
	v_cvt_f32_f16_sdwa v59, v237 dst_sel:DWORD dst_unused:UNUSED_PAD src0_sel:WORD_1
	v_cvt_f32_f16_e32 v52, v234
	v_cvt_f32_f16_e32 v56, v236
	v_cvt_f32_f16_sdwa v57, v236 dst_sel:DWORD dst_unused:UNUSED_PAD src0_sel:WORD_1
	v_cvt_f32_f16_sdwa v53, v234 dst_sel:DWORD dst_unused:UNUSED_PAD src0_sel:WORD_1
	v_pk_mul_f32 v[36:37], v[50:51], v[54:55]
	v_pk_mul_f32 v[48:49], v[46:47], v[58:59]
	v_pk_mul_f32 v[50:51], v[44:45], v[56:57]
	v_pk_mul_f32 v[44:45], v[44:45], v[52:53]
	v_pk_mul_f32 v[52:53], v[40:41], v[36:37]
	v_pk_mul_f32 v[54:55], v[40:41], v[48:49]
	v_cvt_pk_f16_f32 v36, v36, v37
	v_cvt_pk_f16_f32 v37, v48, v49
	v_pk_mul_f32 v[56:57], v[38:39], v[50:51]
	v_pk_mul_f32 v[58:59], v[38:39], v[44:45]
	s_waitcnt lgkmcnt(14)
	ds_write2st64_b32 v201, v36, v37 offset1:18
	v_cvt_pk_f16_f32 v36, v52, v53
	v_cvt_pk_f16_f32 v37, v54, v55
	v_pk_mul_f32 v[50:51], v[0:1], v[50:51]
	s_waitcnt lgkmcnt(14)
	ds_write2st64_b32 v201, v36, v37 offset0:36 offset1:54
	v_cvt_pk_f16_f32 v36, v56, v57
	v_cvt_pk_f16_f32 v37, v58, v59
	s_waitcnt lgkmcnt(14)
	ds_write2st64_b32 v201, v36, v37 offset0:72 offset1:90
	v_cvt_f16_f32_e32 v36, v50
	v_pk_mul_f32 v[44:45], v[0:1], v[44:45]
	v_cvt_f16_f32_e32 v37, v51
	v_cvt_f16_f32_e32 v44, v44
	v_cvt_f16_f32_e32 v45, v45
	s_waitcnt lgkmcnt(14)
	ds_write_b16 v176, v36 offset:20
	s_waitcnt lgkmcnt(14)
	ds_write_b16 v176, v37 offset:60
	s_waitcnt lgkmcnt(14)
	ds_write_b16 v176, v44 offset:5140
	s_waitcnt lgkmcnt(14)
	ds_write_b16 v176, v45 offset:5180
	s_waitcnt lgkmcnt(14)
	ds_write_b16 v176, v60 offset:10260
	s_waitcnt lgkmcnt(14)
	ds_read_b32 v2, v242 offset:32768
	v_rcp_f32_e32 v44, v42
	v_rcp_f32_e32 v45, v43
	v_cvt_f32_f16_e32 v52, v241
	v_cvt_f32_f16_sdwa v53, v241 dst_sel:DWORD dst_unused:UNUSED_PAD src0_sel:WORD_1
	v_cvt_f32_f16_e32 v56, v165
	v_cvt_f32_f16_sdwa v57, v165 dst_sel:DWORD dst_unused:UNUSED_PAD src0_sel:WORD_1
	v_cvt_f32_f16_e32 v50, v240
	v_cvt_f32_f16_e32 v54, v164
	v_cvt_f32_f16_sdwa v55, v164 dst_sel:DWORD dst_unused:UNUSED_PAD src0_sel:WORD_1
	v_cvt_f32_f16_sdwa v51, v240 dst_sel:DWORD dst_unused:UNUSED_PAD src0_sel:WORD_1
	v_pk_mul_f32 v[36:37], v[46:47], v[52:53]
	v_pk_mul_f32 v[42:43], v[42:43], v[56:57]
	v_pk_mul_f32 v[46:47], v[44:45], v[54:55]
	v_pk_mul_f32 v[44:45], v[44:45], v[50:51]
	v_pk_mul_f32 v[48:49], v[40:41], v[36:37]
	v_pk_mul_f32 v[40:41], v[40:41], v[42:43]
	v_cvt_pk_f16_f32 v36, v36, v37
	v_cvt_pk_f16_f32 v37, v42, v43
	v_pk_mul_f32 v[50:51], v[38:39], v[46:47]
	v_pk_mul_f32 v[38:39], v[38:39], v[44:45]
	s_waitcnt lgkmcnt(14)
	ds_write2st64_b32 v203, v36, v37 offset1:18
	v_cvt_pk_f16_f32 v36, v48, v49
	v_cvt_pk_f16_f32 v37, v40, v41
	v_pk_mul_f32 v[46:47], v[0:1], v[46:47]
	s_waitcnt lgkmcnt(14)
	ds_write2st64_b32 v203, v36, v37 offset0:36 offset1:54
	v_cvt_pk_f16_f32 v36, v50, v51
	v_cvt_pk_f16_f32 v37, v38, v39
	s_waitcnt lgkmcnt(14)
	ds_write2st64_b32 v203, v36, v37 offset0:72 offset1:90
	v_cvt_f16_f32_e32 v36, v46
	v_pk_mul_f32 v[44:45], v[0:1], v[44:45]
	v_cvt_f16_f32_e32 v37, v47
	v_cvt_f16_f32_e32 v38, v44
	v_cvt_f16_f32_e32 v39, v45
	s_waitcnt lgkmcnt(14)
	ds_write_b16 v176, v36 offset:22
	s_waitcnt lgkmcnt(14)
	ds_write_b16 v176, v37 offset:62
	s_waitcnt lgkmcnt(14)
	ds_write_b16 v176, v38 offset:5142
	s_waitcnt lgkmcnt(14)
	ds_write_b16 v176, v39 offset:5182
	s_nop 0
	s_waitcnt lgkmcnt(7)
	ds_write_b16 v176, v2 offset:10262
	v_perm_b32 v36, v62, v64, s35
	v_perm_b32 v37, v2, v60, s35
	ds_write_b64 v176, v[36:37] offset:10296

.LBB0_1046:
	v_cmp_eq_u32_e32 vcc, 1, v174
	s_and_saveexec_b64 s[28:29], vcc
	s_cbranch_execz .LBB0_1048
	v_lshl_add_u32 v243, v188, 1, v2
	v_lshl_add_u32 v242, v190, 1, v2
	ds_read2st64_b32 v[36:37], v243 offset0:64 offset1:80
	ds_read2st64_b32 v[46:47], v243 offset0:96 offset1:112
	ds_read_b32 v62, v243 offset:32768
	ds_read2st64_b32 v[162:163], v242 offset0:64 offset1:80
	ds_read2st64_b32 v[164:165], v242 offset0:96 offset1:112
	v_lshl_add_u32 v50, v188, 1, v2
	s_nop 0
	s_nop 0
	s_nop 0
	v_rcp_f32_e32 v42, v54
	v_rcp_f32_e32 v43, v55
	s_waitcnt lgkmcnt(3)
	v_cvt_f32_f16_e32 v58, v47
	v_cvt_f32_f16_e32 v52, v37
	v_cvt_f32_f16_sdwa v53, v37 dst_sel:DWORD dst_unused:UNUSED_PAD src0_sel:WORD_1
	v_cvt_f32_f16_sdwa v59, v47 dst_sel:DWORD dst_unused:UNUSED_PAD src0_sel:WORD_1
	v_cvt_f32_f16_e32 v50, v36
	v_cvt_f32_f16_e32 v56, v46
	v_cvt_f32_f16_sdwa v57, v46 dst_sel:DWORD dst_unused:UNUSED_PAD src0_sel:WORD_1
	v_cvt_f32_f16_sdwa v51, v36 dst_sel:DWORD dst_unused:UNUSED_PAD src0_sel:WORD_1
	v_pk_mul_f32 v[36:37], v[60:61], v[52:53]
	v_pk_mul_f32 v[46:47], v[54:55], v[58:59]
	v_pk_mul_f32 v[52:53], v[42:43], v[56:57]
	v_pk_mul_f32 v[42:43], v[42:43], v[50:51]
	v_pk_mul_f32 v[50:51], v[40:41], v[36:37]
	v_pk_mul_f32 v[56:57], v[40:41], v[46:47]
	v_cvt_pk_f16_f32 v36, v36, v37
	v_cvt_pk_f16_f32 v37, v46, v47
	v_pk_mul_f32 v[58:59], v[38:39], v[52:53]
	v_pk_mul_f32 v[60:61], v[38:39], v[42:43]
	ds_write2st64_b32 v189, v36, v37 offset1:18
	v_cvt_pk_f16_f32 v36, v50, v51
	v_cvt_pk_f16_f32 v37, v56, v57
	v_pk_mul_f32 v[52:53], v[0:1], v[52:53]
	ds_write2st64_b32 v189, v36, v37 offset0:36 offset1:54
	v_cvt_pk_f16_f32 v36, v58, v59
	v_cvt_pk_f16_f32 v37, v60, v61
	v_lshl_add_u32 v243, v192, 1, v2
	ds_read_b32 v60, v242 offset:32768
	ds_read2st64_b32 v[234:235], v243 offset0:64 offset1:80
	ds_read2st64_b32 v[236:237], v243 offset0:96 offset1:112
	ds_write2st64_b32 v189, v36, v37 offset0:72 offset1:90
	v_cvt_f16_f32_e32 v36, v52
	v_pk_mul_f32 v[42:43], v[0:1], v[42:43]
	v_cvt_f16_f32_e32 v37, v53
	v_cvt_f16_f32_e32 v42, v42
	v_cvt_f16_f32_e32 v43, v43
	ds_write_b16 v176, v36 offset:8
	ds_write_b16 v176, v37 offset:48
	ds_write_b16 v176, v42 offset:5128
	ds_write_b16 v176, v43 offset:5168
	s_waitcnt lgkmcnt(12)
	ds_write_b16 v176, v62 offset:10248
	v_lshl_add_u32 v50, v190, 1, v2
	v_rcp_f32_e32 v42, v48
	v_rcp_f32_e32 v43, v49
	s_waitcnt lgkmcnt(12)
	v_cvt_f32_f16_e32 v52, v163
	v_cvt_f32_f16_sdwa v53, v163 dst_sel:DWORD dst_unused:UNUSED_PAD src0_sel:WORD_1
	s_waitcnt lgkmcnt(11)
	v_cvt_f32_f16_e32 v58, v165
	v_cvt_f32_f16_sdwa v59, v165 dst_sel:DWORD dst_unused:UNUSED_PAD src0_sel:WORD_1
	v_cvt_f32_f16_e32 v50, v162
	v_cvt_f32_f16_e32 v56, v164
	v_cvt_f32_f16_sdwa v57, v164 dst_sel:DWORD dst_unused:UNUSED_PAD src0_sel:WORD_1
	v_cvt_f32_f16_sdwa v51, v162 dst_sel:DWORD dst_unused:UNUSED_PAD src0_sel:WORD_1
	v_pk_mul_f32 v[36:37], v[54:55], v[52:53]
	v_pk_mul_f32 v[46:47], v[48:49], v[58:59]
	v_pk_mul_f32 v[52:53], v[42:43], v[56:57]
	v_pk_mul_f32 v[42:43], v[42:43], v[50:51]
	v_pk_mul_f32 v[50:51], v[40:41], v[36:37]
	v_pk_mul_f32 v[54:55], v[40:41], v[46:47]
	v_cvt_pk_f16_f32 v36, v36, v37
	v_cvt_pk_f16_f32 v37, v46, v47
	v_pk_mul_f32 v[56:57], v[38:39], v[52:53]
	v_pk_mul_f32 v[58:59], v[38:39], v[42:43]
	ds_write2st64_b32 v191, v36, v37 offset1:18
	v_cvt_pk_f16_f32 v36, v50, v51
	v_cvt_pk_f16_f32 v37, v54, v55
	v_pk_mul_f32 v[52:53], v[0:1], v[52:53]
	ds_write2st64_b32 v191, v36, v37 offset0:36 offset1:54
	v_cvt_pk_f16_f32 v36, v56, v57
	v_cvt_pk_f16_f32 v37, v58, v59
	v_lshl_add_u32 v242, v194, 1, v2
	ds_read_b32 v58, v243 offset:32768
	ds_read2st64_b32 v[240:241], v242 offset0:64 offset1:80
	s_waitcnt lgkmcnt(14)
	ds_read2st64_b32 v[164:165], v242 offset0:96 offset1:112
	s_waitcnt lgkmcnt(14)
	ds_write2st64_b32 v191, v36, v37 offset0:72 offset1:90
	v_cvt_f16_f32_e32 v36, v52
	v_pk_mul_f32 v[42:43], v[0:1], v[42:43]
	v_cvt_f16_f32_e32 v37, v53
	v_cvt_f16_f32_e32 v42, v42
	v_cvt_f16_f32_e32 v43, v43
	s_waitcnt lgkmcnt(14)
	ds_write_b16 v176, v36 offset:10
	s_waitcnt lgkmcnt(14)
	ds_write_b16 v176, v37 offset:50
	s_waitcnt lgkmcnt(14)
	ds_write_b16 v176, v42 offset:5130
	s_waitcnt lgkmcnt(14)
	ds_write_b16 v176, v43 offset:5170
	s_waitcnt lgkmcnt(14)
	ds_write_b16 v176, v60 offset:10250
	v_lshl_add_u32 v50, v192, 1, v2
	v_rcp_f32_e32 v42, v44
	v_rcp_f32_e32 v43, v45
	v_lshl_add_u32 v2, v194, 1, v2
	v_cvt_f32_f16_e32 v52, v235
	v_cvt_f32_f16_sdwa v53, v235 dst_sel:DWORD dst_unused:UNUSED_PAD src0_sel:WORD_1
	v_cvt_f32_f16_e32 v56, v237
	v_cvt_f32_f16_sdwa v57, v237 dst_sel:DWORD dst_unused:UNUSED_PAD src0_sel:WORD_1
	v_cvt_f32_f16_e32 v50, v234
	v_cvt_f32_f16_e32 v54, v236
	v_cvt_f32_f16_sdwa v55, v236 dst_sel:DWORD dst_unused:UNUSED_PAD src0_sel:WORD_1
	v_cvt_f32_f16_sdwa v51, v234 dst_sel:DWORD dst_unused:UNUSED_PAD src0_sel:WORD_1
	v_pk_mul_f32 v[36:37], v[48:49], v[52:53]
	v_pk_mul_f32 v[46:47], v[44:45], v[56:57]
	v_pk_mul_f32 v[48:49], v[42:43], v[54:55]
	v_pk_mul_f32 v[42:43], v[42:43], v[50:51]
	v_pk_mul_f32 v[50:51], v[40:41], v[36:37]
	v_pk_mul_f32 v[52:53], v[40:41], v[46:47]
	v_cvt_pk_f16_f32 v36, v36, v37
	v_cvt_pk_f16_f32 v37, v46, v47
	v_pk_mul_f32 v[54:55], v[38:39], v[48:49]
	v_pk_mul_f32 v[56:57], v[38:39], v[42:43]
	s_waitcnt lgkmcnt(14)
	ds_write2st64_b32 v193, v36, v37 offset1:18
	v_cvt_pk_f16_f32 v36, v50, v51
	v_cvt_pk_f16_f32 v37, v52, v53
	v_pk_mul_f32 v[48:49], v[0:1], v[48:49]
	s_waitcnt lgkmcnt(14)
	ds_write2st64_b32 v193, v36, v37 offset0:36 offset1:54
	v_cvt_pk_f16_f32 v36, v54, v55
	v_cvt_pk_f16_f32 v37, v56, v57
	s_waitcnt lgkmcnt(14)
	ds_write2st64_b32 v193, v36, v37 offset0:72 offset1:90
	v_cvt_f16_f32_e32 v36, v48
	v_pk_mul_f32 v[42:43], v[0:1], v[42:43]
	v_cvt_f16_f32_e32 v37, v49
	v_cvt_f16_f32_e32 v42, v42
	v_cvt_f16_f32_e32 v43, v43
	s_waitcnt lgkmcnt(14)
	ds_write_b16 v176, v36 offset:12
	s_waitcnt lgkmcnt(14)
	ds_write_b16 v176, v37 offset:52
	s_waitcnt lgkmcnt(14)
	ds_write_b16 v176, v42 offset:5132
	s_waitcnt lgkmcnt(14)
	ds_write_b16 v176, v43 offset:5172
	s_waitcnt lgkmcnt(14)
	ds_write_b16 v176, v58 offset:10252
	s_waitcnt lgkmcnt(14)
	ds_read_b32 v2, v242 offset:32768
	v_cvt_f32_f16_e32 v48, v241
	v_cvt_f32_f16_sdwa v49, v241 dst_sel:DWORD dst_unused:UNUSED_PAD src0_sel:WORD_1
	v_cvt_f32_f16_e32 v52, v165
	v_cvt_f32_f16_sdwa v53, v165 dst_sel:DWORD dst_unused:UNUSED_PAD src0_sel:WORD_1
	v_cvt_f32_f16_e32 v46, v240
	v_cvt_f32_f16_e32 v50, v164
	v_cvt_f32_f16_sdwa v51, v164 dst_sel:DWORD dst_unused:UNUSED_PAD src0_sel:WORD_1
	v_cvt_f32_f16_sdwa v47, v240 dst_sel:DWORD dst_unused:UNUSED_PAD src0_sel:WORD_1
	v_pk_mul_f32 v[36:37], v[44:45], v[48:49]
	v_pk_mul_f32 v[42:43], v[38:39], v[52:53]
	v_pk_mul_f32 v[44:45], v[40:41], v[50:51]
	v_pk_mul_f32 v[46:47], v[40:41], v[46:47]
	v_pk_mul_f32 v[48:49], v[40:41], v[36:37]
	v_pk_mul_f32 v[40:41], v[40:41], v[42:43]
	v_cvt_pk_f16_f32 v36, v36, v37
	v_cvt_pk_f16_f32 v37, v42, v43
	v_pk_mul_f32 v[50:51], v[38:39], v[44:45]
	v_pk_mul_f32 v[38:39], v[38:39], v[46:47]
	s_waitcnt lgkmcnt(14)
	ds_write2st64_b32 v195, v36, v37 offset1:18
	v_cvt_pk_f16_f32 v36, v48, v49
	v_cvt_pk_f16_f32 v37, v40, v41
	v_pk_mul_f32 v[44:45], v[0:1], v[44:45]
	s_waitcnt lgkmcnt(14)
	ds_write2st64_b32 v195, v36, v37 offset0:36 offset1:54
	v_cvt_pk_f16_f32 v36, v50, v51
	v_cvt_pk_f16_f32 v37, v38, v39
	s_waitcnt lgkmcnt(14)
	ds_write2st64_b32 v195, v36, v37 offset0:72 offset1:90
	v_cvt_f16_f32_e32 v36, v44
	v_pk_mul_f32 v[46:47], v[0:1], v[46:47]
	v_cvt_f16_f32_e32 v37, v45
	v_cvt_f16_f32_e32 v38, v46
	v_cvt_f16_f32_e32 v39, v47
	s_waitcnt lgkmcnt(14)
	ds_write_b16 v176, v36 offset:14
	s_waitcnt lgkmcnt(14)
	ds_write_b16 v176, v37 offset:54
	s_waitcnt lgkmcnt(14)
	ds_write_b16 v176, v38 offset:5134
	s_waitcnt lgkmcnt(14)
	ds_write_b16 v176, v39 offset:5174
	s_nop 0
	s_waitcnt lgkmcnt(7)
	ds_write_b16 v176, v2 offset:10254
	v_perm_b32 v36, v60, v62, s35
	v_perm_b32 v37, v2, v58, s35
	ds_write_b64 v176, v[36:37] offset:10288
